# GVT workspace rows stored with their 256-byte block index XORed by (row&15) (gla_in store and gla_scan load agree): rows of one chunk spread over address bits 8..11
# baseline (speedup 1.0000x reference)
; DI u32x2 pk4(float a, float b, float c, float d) { u32x2 r; r.x = pk2(a, b); r.y = pk2(c, d); return r; }
;     ...
;         if (vtile) {
; #pragma unroll
;             for (int mi = 0; mi < MI; ++mi)
; #pragma unroll
;                 for (int ch = 0; ch < 2; ++ch) {
;                     const int tok = mt * 256 + wr * C::WROWS + mi * 32 + ch * 16 + 4 * q, bb = tok >> 12, sq = tok & 4095;
; #pragma unroll
;                     for (int ni = 0; ni < 2; ++ni)
; #pragma unroll
;                         for (int rh = 0; rh < 2; ++rh) {
;                             const int n = (nt * C::BN + wc * 64 - 1024) + ni * 32 + rh * 16 + r16;
;                             const f32x4 v = acc[mi][ni][rh][ch];
;                             *(u32x2*)(GVT + ((size_t)(bb * 1024 + n)) * 4096 + sq) = pk4(v.x, v.y, v.z, v.w);
;                         }
;                 }
;             continue;
.LBB0_330:
	s_and_b64 vcc, exec, s[0:1]
	s_cbranch_vccz .LBB0_194
	v_and_b32_e32 v129, 0xf80, v128
	v_ashrrev_i32_e32 v128, 2, v128
	s_addk_i32 s52, 0xfc00
	v_lshlrev_b32_e32 v130, 6, v149
	v_and_b32_e32 v128, 0xfffffc00, v128
	v_or_b32_e32 v131, s52, v148
	v_add3_u32 v128, v131, v130, v128
	v_lshlrev_b32_e32 v129, 1, v129
	v_readlane_b32 s0, v253, 11
	v_cvt_pk_bf16_f32 v120, v120, v121
	v_cvt_pk_bf16_f32 v121, v122, v123
	v_or_b32_e32 v122, 16, v128
	v_lshl_or_b32 v176, v141, 3, v129
	v_lshlrev_b32_e32 v129, 8, v148
	v_xor_b32_e32 v176, v176, v129
	v_readlane_b32 s1, v253, 12
	v_ashrrev_i32_e32 v123, 31, v122
	v_lshlrev_b64 v[122:123], 13, v[122:123]
	v_lshl_add_u64 v[130:131], s[0:1], 0, v[176:177]
	v_lshl_add_u64 v[122:123], v[130:131], 0, v[122:123]
	v_cvt_pk_bf16_f32 v104, v104, v105
	v_cvt_pk_bf16_f32 v105, v106, v107
	v_or_b32_e32 v106, 48, v128
	global_store_dwordx2 v[122:123], v[120:121], off
	v_or_b32_e32 v120, 32, v128
	v_ashrrev_i32_e32 v107, 31, v106
	v_ashrrev_i32_e32 v129, 31, v128
	v_ashrrev_i32_e32 v121, 31, v120
	v_lshlrev_b64 v[106:107], 13, v[106:107]
	v_cvt_pk_bf16_f32 v124, v124, v125
	v_cvt_pk_bf16_f32 v125, v126, v127
	v_lshlrev_b64 v[126:127], 13, v[128:129]
	v_cvt_pk_bf16_f32 v112, v112, v113
	v_cvt_pk_bf16_f32 v113, v114, v115
	v_lshlrev_b64 v[114:115], 13, v[120:121]
	v_lshl_add_u64 v[106:107], v[130:131], 0, v[106:107]
	v_cvt_pk_bf16_f32 v72, v72, v73
	v_cvt_pk_bf16_f32 v73, v74, v75
	v_cvt_pk_bf16_f32 v36, v36, v37
	v_cvt_pk_bf16_f32 v37, v38, v39
	v_cvt_pk_bf16_f32 v4, v4, v5
	v_cvt_pk_bf16_f32 v5, v6, v7
	v_lshl_add_u64 v[126:127], v[130:131], 0, v[126:127]
	v_lshl_add_u64 v[114:115], v[130:131], 0, v[114:115]
	global_store_dwordx2 v[106:107], v[104:105], off
	v_cvt_pk_bf16_f32 v104, v116, v117
	v_cvt_pk_bf16_f32 v105, v118, v119
	global_store_dwordx2 v[106:107], v[72:73], off offset:64
	v_cvt_pk_bf16_f32 v72, v84, v85
	v_cvt_pk_bf16_f32 v73, v86, v87
	global_store_dwordx2 v[106:107], v[36:37], off offset:128
	v_cvt_pk_bf16_f32 v36, v48, v49
	v_cvt_pk_bf16_f32 v37, v50, v51
	global_store_dwordx2 v[106:107], v[4:5], off offset:192
	v_cvt_pk_bf16_f32 v4, v16, v17
	v_cvt_pk_bf16_f32 v5, v18, v19
	v_cvt_pk_bf16_f32 v0, v0, v1
	v_cvt_pk_bf16_f32 v1, v2, v3
	global_store_dwordx2 v[126:127], v[104:105], off offset:32
	v_cvt_pk_bf16_f32 v104, v108, v109
	v_cvt_pk_bf16_f32 v105, v110, v111
	v_cvt_pk_bf16_f32 v100, v100, v101
	v_cvt_pk_bf16_f32 v101, v102, v103
	v_cvt_pk_bf16_f32 v96, v96, v97
	v_cvt_pk_bf16_f32 v97, v98, v99
	v_cvt_pk_bf16_f32 v92, v92, v93
	v_cvt_pk_bf16_f32 v93, v94, v95
	v_cvt_pk_bf16_f32 v88, v88, v89
	v_cvt_pk_bf16_f32 v89, v90, v91
	v_cvt_pk_bf16_f32 v80, v80, v81
	v_cvt_pk_bf16_f32 v81, v82, v83
	global_store_dwordx2 v[126:127], v[72:73], off offset:96
	v_cvt_pk_bf16_f32 v72, v76, v77
	v_cvt_pk_bf16_f32 v73, v78, v79
	v_cvt_pk_bf16_f32 v68, v68, v69
	v_cvt_pk_bf16_f32 v69, v70, v71
	v_cvt_pk_bf16_f32 v64, v64, v65
	v_cvt_pk_bf16_f32 v65, v66, v67
	v_cvt_pk_bf16_f32 v56, v56, v57
	v_cvt_pk_bf16_f32 v57, v58, v59
	v_cvt_pk_bf16_f32 v52, v52, v53
	v_cvt_pk_bf16_f32 v53, v54, v55
	v_cvt_pk_bf16_f32 v44, v44, v45
	v_cvt_pk_bf16_f32 v45, v46, v47
	global_store_dwordx2 v[126:127], v[36:37], off offset:160
	v_cvt_pk_bf16_f32 v36, v40, v41
	v_cvt_pk_bf16_f32 v37, v42, v43
	v_cvt_pk_bf16_f32 v32, v32, v33
	v_cvt_pk_bf16_f32 v33, v34, v35
	v_cvt_pk_bf16_f32 v28, v28, v29
	v_cvt_pk_bf16_f32 v29, v30, v31
	v_cvt_pk_bf16_f32 v24, v24, v25
	v_cvt_pk_bf16_f32 v25, v26, v27
	v_cvt_pk_bf16_f32 v20, v20, v21
	v_cvt_pk_bf16_f32 v21, v22, v23
	v_cvt_pk_bf16_f32 v12, v12, v13
	v_cvt_pk_bf16_f32 v13, v14, v15
	global_store_dwordx2 v[126:127], v[4:5], off offset:224
	v_cvt_pk_bf16_f32 v4, v8, v9
	v_cvt_pk_bf16_f32 v5, v10, v11
	global_store_dwordx2 v[114:115], v[0:1], off offset:224
	v_cvt_pk_bf16_f32 v0, v60, v61
	v_cvt_pk_bf16_f32 v1, v62, v63
	global_store_dwordx2 v[126:127], v[124:125], off
	global_store_dwordx2 v[114:115], v[112:113], off
	global_store_dwordx2 v[122:123], v[104:105], off offset:32
	global_store_dwordx2 v[114:115], v[100:101], off offset:32
	global_store_dwordx2 v[106:107], v[96:97], off offset:32
	global_store_dwordx2 v[126:127], v[92:93], off offset:64
	global_store_dwordx2 v[122:123], v[88:89], off offset:64
	global_store_dwordx2 v[114:115], v[80:81], off offset:64
	global_store_dwordx2 v[122:123], v[72:73], off offset:96
	global_store_dwordx2 v[114:115], v[68:69], off offset:96
	global_store_dwordx2 v[106:107], v[64:65], off offset:96
	global_store_dwordx2 v[126:127], v[56:57], off offset:128
	global_store_dwordx2 v[122:123], v[52:53], off offset:128
	global_store_dwordx2 v[114:115], v[44:45], off offset:128
	global_store_dwordx2 v[122:123], v[36:37], off offset:160
	global_store_dwordx2 v[114:115], v[32:33], off offset:160
	global_store_dwordx2 v[106:107], v[28:29], off offset:160
	global_store_dwordx2 v[126:127], v[24:25], off offset:192
	global_store_dwordx2 v[122:123], v[20:21], off offset:192
	global_store_dwordx2 v[114:115], v[12:13], off offset:192
	global_store_dwordx2 v[122:123], v[4:5], off offset:224
	global_store_dwordx2 v[106:107], v[0:1], off offset:224
	s_branch .LBB0_194

;     ...
;     for (int u = vb; u < 256; u += nb) {
;         const int b = u >> 5, hh = (u >> 3) & 3, ksl = u & 7;
;         const int kc0 = hh * 128 + ksl * 16 + 2 * w;
;         float wa[2][16], bb[2];
; #pragma unroll
;         for (int e = 0; e < 2; ++e) { bb[e] = ba[kc0 + e];
; #pragma unroll
;             for (int jj = 0; jj < 16; ++jj) wa[e][jj] = w2[jj * 512 + kc0 + e]; }
;         f32x4 acc[2];
; #pragma unroll
;         for (int e = 0; e < 2; ++e) acc[e] = (f32x4){0.f, 0.f, 0.f, 0.f};
;         __syncthreads();
;         f32x4 a4n[4]; unsigned krawn; bf16x8 vfrn[2][2];
;         auto ldchunk = [&](int n) {
;             const int tok = b * 4096 + n * 64 + l;
; #pragma unroll
;             for (int q = 0; q < 4; ++q) a4n[q] = *(const f32x4*)(GA + (size_t)tok * 16 + 4 * q);
;             krawn = *(const unsigned*)(GK + (size_t)tok * 512 + kc0);
; #pragma unroll
;             for (int e = 0; e < 2; ++e)
; #pragma unroll
;                 for (int ks = 0; ks < 2; ++ks)
;                     vfrn[e][ks] = *(const bf16x8*)(GVT + ((size_t)(b * 1024 + hh * 256 + (2 * w + e) * 16 + (l & 15))) * 4096 + n * 64 + ks * 32 + (l >> 4) * 8);
;         };
;         ldchunk(0);
.LBB0_418:
	s_bfe_u32 s57, s56, 0x20003
	s_lshl_b32 s21, s56, 4
	s_and_b32 s21, s21, 0x70
	s_lshl_b32 s20, s57, 7
	s_or_b32 s20, s20, s21
	s_ashr_i32 s28, s56, 5
	v_mov_b32_e32 v220, 0xbfb8aa3b
	v_mov_b32_e32 v222, 1.0
	v_mov_b32_e32 v223, 1.0
	v_mov_b32_e32 v224, 0x3f317217
	v_mov_b32_e32 v225, 0x3f317217
	v_mov_b32_e32 v226, 0x3377d1cf
	v_mov_b32_e32 v227, 0x3377d1cf
	v_mov_b32_e32 v228, 0x3fb8aa3b
	v_mov_b32_e32 v229, 0x3fb8aa3b
	v_mov_b32_e32 v214, 0x3d800000
	v_mov_b32_e32 v215, 0x3d800000
	v_lshrrev_b32_e32 v27, 6, v249
	v_lshrrev_b32_e32 v61, 3, v160
	v_lshl_add_u32 v60, v27, 3, v61
	v_and_b32_e32 v62, 7, v160
	v_lshlrev_b32_e32 v230, 3, v160
	v_lshl_add_u32 v230, v27, 9, v230
	v_lshlrev_b32_e32 v231, 2, v62
	v_lshl_add_u32 v231, v60, 10, v231
	v_mul_u32_u24_e32 v28, 0x50, v60
	v_lshl_add_u32 v28, v62, 3, v28
	v_add_u32_e32 v28, 0x2010, v28
	v_mul_u32_u24_e32 v29, 0x50, v160
	v_add_u32_e32 v29, 0x2010, v29
	v_mul_u32_u24_e32 v30, 0x104, v62
	v_lshl_add_u32 v30, v60, 2, v30
	v_add_u32_e32 v30, 0x5010, v30
	v_mul_u32_u24_e32 v31, 0x104, v27
	v_lshl_add_u32 v31, v160, 2, v31
	v_add_u32_e32 v31, 0x5010, v31
	v_lshrrev_b32_e32 v64, 4, v160
	v_lshlrev_b32_e32 v232, 13, v72
	v_lshl_add_u32 v232, v64, 4, v232
	v_add_u32_e32 v233, 0x20000, v232
	v_lshlrev_b32_e32 v234, 8, v72
	v_lshl_add_u32 v234, v64, 3, v234
	v_add_u32_e32 v235, 0x1000, v234
	v_add_u32_e32 v65, s20, v161
	v_lshlrev_b32_e32 v65, 2, v65
	s_mov_b64 s[50:51], s[8:9]
	global_load_dwordx2 v[86:87], v65, s[50:51]
	global_load_dwordx2 v[88:89], v65, s[50:51] offset:2048
	s_add_u32 s50, s50, 0x1000
	s_addc_u32 s51, s51, 0
	global_load_dwordx2 v[90:91], v65, s[50:51]
	global_load_dwordx2 v[92:93], v65, s[50:51] offset:2048
	s_add_u32 s50, s50, 0x1000
	s_addc_u32 s51, s51, 0
	global_load_dwordx2 v[94:95], v65, s[50:51]
	global_load_dwordx2 v[96:97], v65, s[50:51] offset:2048
	s_add_u32 s50, s50, 0x1000
	s_addc_u32 s51, s51, 0
	global_load_dwordx2 v[98:99], v65, s[50:51]
	global_load_dwordx2 v[100:101], v65, s[50:51] offset:2048
	s_add_u32 s50, s50, 0x1000
	s_addc_u32 s51, s51, 0
	global_load_dwordx2 v[102:103], v65, s[50:51]
	global_load_dwordx2 v[104:105], v65, s[50:51] offset:2048
	s_add_u32 s50, s50, 0x1000
	s_addc_u32 s51, s51, 0
	global_load_dwordx2 v[106:107], v65, s[50:51]
	global_load_dwordx2 v[108:109], v65, s[50:51] offset:2048
	s_add_u32 s50, s50, 0x1000
	s_addc_u32 s51, s51, 0
	global_load_dwordx2 v[110:111], v65, s[50:51]
	global_load_dwordx2 v[112:113], v65, s[50:51] offset:2048
	s_add_u32 s50, s50, 0x1000
	s_addc_u32 s51, s51, 0
	global_load_dwordx2 v[114:115], v65, s[50:51]
	global_load_dwordx2 v[116:117], v65, s[50:51] offset:2048
	s_add_u32 s50, s50, 0x1000
	s_addc_u32 s51, s51, 0
	global_load_dwordx2 v[118:119], v65, s[18:19]
	v_readlane_b32 s26, v253, 13
	v_readlane_b32 s27, v253, 14
	v_readlane_b32 s58, v254, 26
	v_readlane_b32 s59, v254, 27
	v_readlane_b32 s34, v253, 11
	v_readlane_b32 s35, v253, 12
	v_readlane_b32 s100, v254, 28
	v_readlane_b32 s101, v254, 29
	s_lshl_b32 s52, s28, 18
	s_add_u32 s26, s26, s52
	s_addc_u32 s27, s27, 0
	s_lshl_b32 s52, s28, 22
	s_lshl_b32 s53, s20, 1
	s_add_u32 s52, s52, s53
	s_add_u32 s58, s58, s52
	s_addc_u32 s59, s59, 0
	s_lshl_b32 s52, s28, 23
	s_lshl_b32 s53, s57, 21
	s_add_u32 s52, s52, s53
	s_add_u32 s34, s34, s52
	s_addc_u32 s35, s35, 0
	s_lshl_b32 s52, s28, 8
	s_or_b32 s52, s52, s57
	s_lshl_b32 s52, s52, 16
	s_lshl_b32 s53, s21, 1
	s_add_u32 s52, s52, s53
	s_add_u32 s100, s100, s52
	s_addc_u32 s101, s101, 0
	v_mov_b32_e32 v0, 0
	v_mov_b32_e32 v1, 0
	v_mov_b32_e32 v2, 0
	v_mov_b32_e32 v3, 0
	v_mov_b32_e32 v4, 0
	v_mov_b32_e32 v5, 0
	v_mov_b32_e32 v6, 0
	v_mov_b32_e32 v7, 0
	s_barrier
	v_lshlrev_b32_e32 v25, 8, v162
	s_mov_b32 s57, 0
	global_load_dwordx2 v[48:49], v230, s[26:27]
	global_load_dword v50, v231, s[58:59]
	s_add_u32 s26, s26, 0x1000
	s_addc_u32 s27, s27, 0
	s_add_u32 s58, s58, 0x10000
	s_addc_u32 s59, s59, 0
	global_load_dwordx2 v[52:53], v230, s[26:27]
	global_load_dword v54, v231, s[58:59]
	s_add_u32 s26, s26, 0x1000
	s_addc_u32 s27, s27, 0
	s_add_u32 s58, s58, 0x10000
	s_addc_u32 s59, s59, 0
	global_load_dwordx2 v[56:57], v230, s[26:27]
	global_load_dword v58, v231, s[58:59]
	s_add_u32 s26, s26, 0x1000
	s_addc_u32 s27, s27, 0
	s_add_u32 s58, s58, 0x10000
	s_addc_u32 s59, s59, 0
	v_xor_b32_e32 v26, s57, v25
	v_add_u32_e32 v59, v26, v232
	v_add_u32_e32 v63, 0x20000, v59
	global_load_dwordx4 v[32:35], v59, s[34:35]
	global_load_dwordx4 v[36:39], v59, s[34:35] offset:64
	global_load_dwordx4 v[40:43], v63, s[34:35]
	global_load_dwordx4 v[44:47], v63, s[34:35] offset:64
	s_add_u32 s57, s57, 0x80
	s_waitcnt vmcnt(0)
	ds_write_b64 v28, v[48:49] offset:0
	ds_write_b32 v30, v50 offset:0
	s_waitcnt lgkmcnt(0)
	s_barrier
; DI bf16_t f2bf(float x) { return (bf16_t)(pk2(x, 0.f) & 0xffffu); }
; DI float bf2f(unsigned x) { return __uint_as_float(x << 16); }
;     ...
;         for (int n = 0; n < 64; ++n) {
;             const int buf = n & 1;
;             f32x4 a4[4]; bf16x8 vfr[2][2];
; #pragma unroll
;             for (int q = 0; q < 4; ++q) a4[q] = a4n[q];
;             const unsigned kraw = krawn;
; #pragma unroll
;             for (int e = 0; e < 2; ++e)
; #pragma unroll
;                 for (int ks = 0; ks < 2; ++ks) vfr[e][ks] = vfrn[e][ks];
;             if (n + 1 < 64) ldchunk(n + 1);
;             float cum[2];
; #pragma unroll
;             for (int e = 0; e < 2; ++e) {
;                 float z = bb[e];
; #pragma unroll
;                 for (int q = 0; q < 4; ++q) { z += a4[q].x * wa[e][4 * q] + a4[q].y * wa[e][4 * q + 1] + a4[q].z * wa[e][4 * q + 2] + a4[q].w * wa[e][4 * q + 3]; }
;                 cum[e] = (fminf(z, 0.f) - __logf(1.f + __expf(-fabsf(z)))) * (1.f / 16.f);
;             }
; #pragma unroll
;             for (int o = 1; o < 64; o <<= 1) {
;                 const float t0 = __shfl_up(cum[0], o), t1 = __shfl_up(cum[1], o);
;                 if (l >= o) { cum[0] += t0; cum[1] += t1; }
;             }
;             const float tot0 = __shfl(cum[0], 63), tot1 = __shfl(cum[1], 63);
;             kdl[(buf * 16 + 2 * w) * 64 + l] = f2bf(bf2f(kraw & 0xffffu) * __expf(tot0 - cum[0]));
;             kdl[(buf * 16 + 2 * w + 1) * 64 + l] = f2bf(bf2f(kraw >> 16) * __expf(tot1 - cum[1]));
;             if (l == 0) { decl[buf * 16 + 2 * w] = __expf(tot0); decl[buf * 16 + 2 * w + 1] = __expf(tot1); }
	ds_read_b128 v[8:11], v29 offset:0
	ds_read_b128 v[12:15], v29 offset:16
	ds_read_b128 v[16:19], v29 offset:32
	ds_read_b128 v[20:23], v29 offset:48
	ds_read_b32 v24, v31 offset:0
	global_load_dwordx2 v[48:49], v230, s[26:27]
	global_load_dword v50, v231, s[58:59]
	s_add_u32 s26, s26, 0x1000
	s_addc_u32 s27, s27, 0
	s_add_u32 s58, s58, 0x10000
	s_addc_u32 s59, s59, 0
	v_xor_b32_e32 v26, s57, v25
	v_add_u32_e32 v59, v26, v232
	v_add_u32_e32 v63, 0x20000, v59
	global_load_dwordx4 v[178:181], v59, s[34:35]
	global_load_dwordx4 v[182:185], v59, s[34:35] offset:64
	global_load_dwordx4 v[186:189], v63, s[34:35]
	global_load_dwordx4 v[190:193], v63, s[34:35] offset:64
	s_add_u32 s57, s57, 0x80
	s_waitcnt lgkmcnt(0)
	v_pk_fma_f32 v[64:65], v[8:9], v[86:87], v[118:119] op_sel:[0,0,0] op_sel_hi:[0,1,1]
	v_pk_mul_f32 v[66:67], v[16:17], v[102:103] op_sel:[0,0] op_sel_hi:[0,1]
	v_pk_fma_f32 v[64:65], v[8:9], v[88:89], v[64:65] op_sel:[1,0,0] op_sel_hi:[1,1,1]
	v_pk_fma_f32 v[66:67], v[16:17], v[104:105], v[66:67] op_sel:[1,0,0] op_sel_hi:[1,1,1]
	v_pk_fma_f32 v[64:65], v[10:11], v[90:91], v[64:65] op_sel:[0,0,0] op_sel_hi:[0,1,1]
	v_pk_fma_f32 v[66:67], v[18:19], v[106:107], v[66:67] op_sel:[0,0,0] op_sel_hi:[0,1,1]
	v_pk_fma_f32 v[64:65], v[10:11], v[92:93], v[64:65] op_sel:[1,0,0] op_sel_hi:[1,1,1]
	v_pk_fma_f32 v[66:67], v[18:19], v[108:109], v[66:67] op_sel:[1,0,0] op_sel_hi:[1,1,1]
	v_pk_fma_f32 v[64:65], v[12:13], v[94:95], v[64:65] op_sel:[0,0,0] op_sel_hi:[0,1,1]
	v_pk_fma_f32 v[66:67], v[20:21], v[110:111], v[66:67] op_sel:[0,0,0] op_sel_hi:[0,1,1]
	v_pk_fma_f32 v[64:65], v[12:13], v[96:97], v[64:65] op_sel:[1,0,0] op_sel_hi:[1,1,1]
	v_pk_fma_f32 v[66:67], v[20:21], v[112:113], v[66:67] op_sel:[1,0,0] op_sel_hi:[1,1,1]
	v_pk_fma_f32 v[64:65], v[14:15], v[98:99], v[64:65] op_sel:[0,0,0] op_sel_hi:[0,1,1]
	v_pk_fma_f32 v[66:67], v[22:23], v[114:115], v[66:67] op_sel:[0,0,0] op_sel_hi:[0,1,1]
	v_pk_fma_f32 v[64:65], v[14:15], v[100:101], v[64:65] op_sel:[1,0,0] op_sel_hi:[1,1,1]
	v_pk_fma_f32 v[66:67], v[22:23], v[116:117], v[66:67] op_sel:[1,0,0] op_sel_hi:[1,1,1]
	v_lshlrev_b32_e32 v148, 16, v24
	v_pk_add_f32 v[64:65], v[64:65], v[66:67]
	v_and_b32_e32 v149, 0xffff0000, v24
	v_mul_f32_e64 v68, |v64|, v220
	v_mul_f32_e64 v69, |v65|, v220
	v_exp_f32_e32 v68, v68
	v_exp_f32_e32 v69, v69
	v_min_f32_e32 v70, 0, v64
	v_min_f32_e32 v71, 0, v65
	v_pk_add_f32 v[68:69], v[68:69], v[222:223]
	s_nop 0
	v_log_f32_e32 v138, v68
	v_log_f32_e32 v139, v69
	s_nop 0
	v_pk_mul_f32 v[140:141], v[138:139], v[224:225]
	s_nop 0
	v_pk_fma_f32 v[142:143], v[138:139], v[224:225], v[140:141] neg_lo:[0,0,1] neg_hi:[0,0,1]
	s_nop 0
	v_pk_fma_f32 v[142:143], v[138:139], v[226:227], v[142:143]
	s_nop 0
	v_pk_fma_f32 v[142:143], v[138:139], v[224:225], v[142:143]
	s_nop 0
	v_pk_add_f32 v[144:145], v[70:71], v[142:143] neg_lo:[0,1] neg_hi:[0,1]
	s_nop 0
	v_pk_mul_f32 v[144:145], v[144:145], v[214:215]
	s_nop 1
	v_add_f32_dpp v144, v144, v144 row_shr:1 row_mask:0xf bank_mask:0xf
	v_add_f32_dpp v145, v145, v145 row_shr:1 row_mask:0xf bank_mask:0xf
	s_nop 0
	v_add_f32_dpp v144, v144, v144 row_shr:2 row_mask:0xf bank_mask:0xf
	v_add_f32_dpp v145, v145, v145 row_shr:2 row_mask:0xf bank_mask:0xf
	s_nop 0
	v_add_f32_dpp v144, v144, v144 row_shr:4 row_mask:0xf bank_mask:0xf
	v_add_f32_dpp v145, v145, v145 row_shr:4 row_mask:0xf bank_mask:0xf
	s_nop 0
	v_add_f32_dpp v144, v144, v144 row_shr:8 row_mask:0xf bank_mask:0xf
	v_add_f32_dpp v145, v145, v145 row_shr:8 row_mask:0xf bank_mask:0xf
	s_nop 0
	v_add_f32_dpp v144, v144, v144 row_bcast:15 row_mask:0xa bank_mask:0xf
	v_add_f32_dpp v145, v145, v145 row_bcast:15 row_mask:0xa bank_mask:0xf
	s_nop 0
	v_add_f32_dpp v144, v144, v144 row_bcast:31 row_mask:0xc bank_mask:0xf
	v_add_f32_dpp v145, v145, v145 row_bcast:31 row_mask:0xc bank_mask:0xf
	s_nop 0
	v_readlane_b32 s98, v144, 63
	v_readlane_b32 s99, v145, 63
	s_nop 1
	v_pk_add_f32 v[146:147], s[98:99], v[144:145] neg_lo:[0,1] neg_hi:[0,1]
	v_mul_f32_e64 v152, s98, v228
	v_mul_f32_e64 v153, s99, v228
	v_pk_mul_f32 v[146:147], v[146:147], v[228:229]
	v_exp_f32_e32 v152, v152
	v_exp_f32_e32 v153, v153
	v_exp_f32_e32 v146, v146
	v_exp_f32_e32 v147, v147
	s_nop 0
	v_pk_mul_f32 v[146:147], v[146:147], v[148:149]
	s_nop 0
	v_cvt_pk_bf16_f32 v150, v146, v147
	s_nop 0
	ds_write_b16 v172, v150 offset:0
	ds_write_b16_d16_hi v172, v150 offset:128
	s_and_saveexec_b64 s[20:21], vcc
	ds_write_b64 v163, v[152:153] offset:4096
	s_mov_b64 exec, s[20:21]
	s_waitcnt vmcnt(22)
	ds_write_b64 v28, v[52:53] offset:5120
	ds_write_b32 v30, v54 offset:2080
	s_waitcnt lgkmcnt(0)
	s_barrier
; #define MFMA16(a, b, c) __builtin_amdgcn_mfma_f32_16x16x32_bf16((a), (b), (c), 0, 0, 0)
;     ...
;         for (int n = 0; n < 64; ++n) {
;             const int buf = n & 1;
;             f32x4 a4[4]; bf16x8 vfr[2][2];
; #pragma unroll
;             for (int q = 0; q < 4; ++q) a4[q] = a4n[q];
;             const unsigned kraw = krawn;
; #pragma unroll
;             for (int e = 0; e < 2; ++e)
; #pragma unroll
;                 for (int ks = 0; ks < 2; ++ks) vfr[e][ks] = vfrn[e][ks];
;             if (n + 1 < 64) ldchunk(n + 1);
;             float cum[2];
; #pragma unroll
;             for (int e = 0; e < 2; ++e) {
;                 float z = bb[e];
; #pragma unroll
;                 for (int q = 0; q < 4; ++q) { z += a4[q].x * wa[e][4 * q] + a4[q].y * wa[e][4 * q + 1] + a4[q].z * wa[e][4 * q + 2] + a4[q].w * wa[e][4 * q + 3]; }
;                 cum[e] = (fminf(z, 0.f) - __logf(1.f + __expf(-fabsf(z)))) * (1.f / 16.f);
;             }
; #pragma unroll
;             for (int o = 1; o < 64; o <<= 1) {
;                 const float t0 = __shfl_up(cum[0], o), t1 = __shfl_up(cum[1], o);
;                 if (l >= o) { cum[0] += t0; cum[1] += t1; }
;             }
;             const float tot0 = __shfl(cum[0], 63), tot1 = __shfl(cum[1], 63);
;             kdl[(buf * 16 + 2 * w) * 64 + l] = f2bf(bf2f(kraw & 0xffffu) * __expf(tot0 - cum[0]));
;             kdl[(buf * 16 + 2 * w + 1) * 64 + l] = f2bf(bf2f(kraw >> 16) * __expf(tot1 - cum[1]));
;             if (l == 0) { decl[buf * 16 + 2 * w] = __expf(tot0); decl[buf * 16 + 2 * w + 1] = __expf(tot1); }
;             __syncthreads();
;             const f32x4 d4 = *(const f32x4*)(decl + buf * 16 + (l >> 4) * 4);
; #pragma unroll
;             for (int e = 0; e < 2; ++e) acc[e] = acc[e] * d4;
; #pragma unroll
;             for (int ks = 0; ks < 2; ++ks) {
;                 const bf16x8 af = *(const bf16x8*)(kdl + (buf * 16 + (l & 15)) * 64 + ks * 32 + (l >> 4) * 8);
; #pragma unroll
;                 for (int e = 0; e < 2; ++e) acc[e] = MFMA16(af, vfr[e][ks], acc[e]);
;             }
;             const int cidx = b * 64 + n;
; #pragma unroll
;             for (int e = 0; e < 2; ++e) {
;                 const int vv = (2 * w + e) * 16 + (l & 15);
;                 *(u32x2*)(ST + (((size_t)(cidx * 4 + hh)) * 256 + vv) * 128 + ksl * 16 + (l >> 4) * 4) = pk4(acc[e].x, acc[e].y, acc[e].z, acc[e].w);
;             }
	ds_read_b128 v[8:11], v29 offset:5120
	ds_read_b128 v[12:15], v29 offset:5136
	ds_read_b128 v[16:19], v29 offset:5152
	ds_read_b128 v[20:23], v29 offset:5168
	ds_read_b32 v24, v31 offset:2080
	global_load_dwordx2 v[52:53], v230, s[26:27]
	global_load_dword v54, v231, s[58:59]
	s_add_u32 s26, s26, 0x1000
	s_addc_u32 s27, s27, 0
	s_add_u32 s58, s58, 0x10000
	s_addc_u32 s59, s59, 0
	v_xor_b32_e32 v26, s57, v25
	v_add_u32_e32 v59, v26, v232
	v_add_u32_e32 v63, 0x20000, v59
	global_load_dwordx4 v[194:197], v59, s[34:35]
	global_load_dwordx4 v[198:201], v59, s[34:35] offset:64
	global_load_dwordx4 v[202:205], v63, s[34:35]
	global_load_dwordx4 v[206:209], v63, s[34:35] offset:64
	s_add_u32 s57, s57, 0x80
	ds_read_b128 v[154:157], v75 offset:0
	ds_read_b128 v[240:243], v164 offset:4096
	ds_read_b128 v[236:239], v75 offset:64
	s_waitcnt lgkmcnt(3)
	v_pk_fma_f32 v[64:65], v[8:9], v[86:87], v[118:119] op_sel:[0,0,0] op_sel_hi:[0,1,1]
	v_pk_mul_f32 v[66:67], v[16:17], v[102:103] op_sel:[0,0] op_sel_hi:[0,1]
	v_pk_fma_f32 v[64:65], v[8:9], v[88:89], v[64:65] op_sel:[1,0,0] op_sel_hi:[1,1,1]
	v_pk_fma_f32 v[66:67], v[16:17], v[104:105], v[66:67] op_sel:[1,0,0] op_sel_hi:[1,1,1]
	v_pk_fma_f32 v[64:65], v[10:11], v[90:91], v[64:65] op_sel:[0,0,0] op_sel_hi:[0,1,1]
	v_pk_fma_f32 v[66:67], v[18:19], v[106:107], v[66:67] op_sel:[0,0,0] op_sel_hi:[0,1,1]
	v_pk_fma_f32 v[64:65], v[10:11], v[92:93], v[64:65] op_sel:[1,0,0] op_sel_hi:[1,1,1]
	v_pk_fma_f32 v[66:67], v[18:19], v[108:109], v[66:67] op_sel:[1,0,0] op_sel_hi:[1,1,1]
	v_pk_fma_f32 v[64:65], v[12:13], v[94:95], v[64:65] op_sel:[0,0,0] op_sel_hi:[0,1,1]
	v_pk_fma_f32 v[66:67], v[20:21], v[110:111], v[66:67] op_sel:[0,0,0] op_sel_hi:[0,1,1]
	v_pk_fma_f32 v[64:65], v[12:13], v[96:97], v[64:65] op_sel:[1,0,0] op_sel_hi:[1,1,1]
	v_pk_fma_f32 v[66:67], v[20:21], v[112:113], v[66:67] op_sel:[1,0,0] op_sel_hi:[1,1,1]
	v_pk_fma_f32 v[64:65], v[14:15], v[98:99], v[64:65] op_sel:[0,0,0] op_sel_hi:[0,1,1]
	v_pk_fma_f32 v[66:67], v[22:23], v[114:115], v[66:67] op_sel:[0,0,0] op_sel_hi:[0,1,1]
	v_pk_fma_f32 v[64:65], v[14:15], v[100:101], v[64:65] op_sel:[1,0,0] op_sel_hi:[1,1,1]
	v_pk_fma_f32 v[66:67], v[22:23], v[116:117], v[66:67] op_sel:[1,0,0] op_sel_hi:[1,1,1]
	v_lshlrev_b32_e32 v148, 16, v24
	v_pk_add_f32 v[64:65], v[64:65], v[66:67]
	v_and_b32_e32 v149, 0xffff0000, v24
	s_waitcnt lgkmcnt(0)
	v_pk_mul_f32 v[0:1], v[0:1], v[240:241]
	v_pk_mul_f32 v[2:3], v[2:3], v[242:243]
	v_pk_mul_f32 v[4:5], v[4:5], v[240:241]
	v_pk_mul_f32 v[6:7], v[6:7], v[242:243]
	s_waitcnt vmcnt(16)
	s_nop 0
	v_mfma_f32_16x16x32_bf16 v[0:3], v[154:157], v[32:35], v[0:3]
	v_mfma_f32_16x16x32_bf16 v[4:7], v[154:157], v[40:43], v[4:7]
	v_mfma_f32_16x16x32_bf16 v[0:3], v[236:239], v[36:39], v[0:3]
	v_mfma_f32_16x16x32_bf16 v[4:7], v[236:239], v[44:47], v[4:7]
	v_mul_f32_e64 v68, |v64|, v220
	v_mul_f32_e64 v69, |v65|, v220
	v_exp_f32_e32 v68, v68
	v_exp_f32_e32 v69, v69
	v_min_f32_e32 v70, 0, v64
	v_min_f32_e32 v71, 0, v65
	v_pk_add_f32 v[68:69], v[68:69], v[222:223]
	s_nop 0
	v_log_f32_e32 v138, v68
	v_log_f32_e32 v139, v69
	s_nop 0
	v_pk_mul_f32 v[140:141], v[138:139], v[224:225]
	s_nop 0
	v_pk_fma_f32 v[142:143], v[138:139], v[224:225], v[140:141] neg_lo:[0,0,1] neg_hi:[0,0,1]
	s_nop 0
	v_pk_fma_f32 v[142:143], v[138:139], v[226:227], v[142:143]
	s_nop 0
	v_pk_fma_f32 v[142:143], v[138:139], v[224:225], v[142:143]
	s_nop 0
	v_pk_add_f32 v[144:145], v[70:71], v[142:143] neg_lo:[0,1] neg_hi:[0,1]
	s_nop 0
	v_pk_mul_f32 v[144:145], v[144:145], v[214:215]
	v_cvt_pk_bf16_f32 v244, v0, v1
	v_cvt_pk_bf16_f32 v245, v2, v3
	v_cvt_pk_bf16_f32 v246, v4, v5
	v_cvt_pk_bf16_f32 v247, v6, v7
	global_store_dwordx2 v234, v[244:245], s[100:101]
	global_store_dwordx2 v235, v[246:247], s[100:101]
	s_add_u32 s100, s100, 0x40000
	s_addc_u32 s101, s101, 0
	v_add_f32_dpp v144, v144, v144 row_shr:1 row_mask:0xf bank_mask:0xf
	v_add_f32_dpp v145, v145, v145 row_shr:1 row_mask:0xf bank_mask:0xf
	s_nop 0
	v_add_f32_dpp v144, v144, v144 row_shr:2 row_mask:0xf bank_mask:0xf
	v_add_f32_dpp v145, v145, v145 row_shr:2 row_mask:0xf bank_mask:0xf
	s_nop 0
	v_add_f32_dpp v144, v144, v144 row_shr:4 row_mask:0xf bank_mask:0xf
	v_add_f32_dpp v145, v145, v145 row_shr:4 row_mask:0xf bank_mask:0xf
	s_nop 0
	v_add_f32_dpp v144, v144, v144 row_shr:8 row_mask:0xf bank_mask:0xf
	v_add_f32_dpp v145, v145, v145 row_shr:8 row_mask:0xf bank_mask:0xf
	s_nop 0
	v_add_f32_dpp v144, v144, v144 row_bcast:15 row_mask:0xa bank_mask:0xf
	v_add_f32_dpp v145, v145, v145 row_bcast:15 row_mask:0xa bank_mask:0xf
	s_nop 0
	v_add_f32_dpp v144, v144, v144 row_bcast:31 row_mask:0xc bank_mask:0xf
	v_add_f32_dpp v145, v145, v145 row_bcast:31 row_mask:0xc bank_mask:0xf
	s_nop 0
	v_readlane_b32 s98, v144, 63
	v_readlane_b32 s99, v145, 63
	s_nop 1
	v_pk_add_f32 v[146:147], s[98:99], v[144:145] neg_lo:[0,1] neg_hi:[0,1]
	v_mul_f32_e64 v152, s98, v228
	v_mul_f32_e64 v153, s99, v228
	v_pk_mul_f32 v[146:147], v[146:147], v[228:229]
	v_exp_f32_e32 v152, v152
	v_exp_f32_e32 v153, v153
	v_exp_f32_e32 v146, v146
	v_exp_f32_e32 v147, v147
	s_nop 0
	v_pk_mul_f32 v[146:147], v[146:147], v[148:149]
	s_nop 0
	v_cvt_pk_bf16_f32 v150, v146, v147
	s_nop 0
	ds_write_b16 v172, v150 offset:2048
	ds_write_b16_d16_hi v172, v150 offset:2176
	s_and_saveexec_b64 s[20:21], vcc
	ds_write_b64 v163, v[152:153] offset:4160
	s_mov_b64 exec, s[20:21]
	s_waitcnt vmcnt(22)
	ds_write_b64 v28, v[56:57] offset:0
	ds_write_b32 v30, v58 offset:0
	s_waitcnt lgkmcnt(0)
	s_barrier
; #define MFMA16(a, b, c) __builtin_amdgcn_mfma_f32_16x16x32_bf16((a), (b), (c), 0, 0, 0)
;     ...
;         for (int n = 0; n < 64; ++n) {
;             const int buf = n & 1;
;             f32x4 a4[4]; bf16x8 vfr[2][2];
; #pragma unroll
;             for (int q = 0; q < 4; ++q) a4[q] = a4n[q];
;             const unsigned kraw = krawn;
; #pragma unroll
;             for (int e = 0; e < 2; ++e)
; #pragma unroll
;                 for (int ks = 0; ks < 2; ++ks) vfr[e][ks] = vfrn[e][ks];
;             if (n + 1 < 64) ldchunk(n + 1);
;             float cum[2];
; #pragma unroll
;             for (int e = 0; e < 2; ++e) {
;                 float z = bb[e];
; #pragma unroll
;                 for (int q = 0; q < 4; ++q) { z += a4[q].x * wa[e][4 * q] + a4[q].y * wa[e][4 * q + 1] + a4[q].z * wa[e][4 * q + 2] + a4[q].w * wa[e][4 * q + 3]; }
;                 cum[e] = (fminf(z, 0.f) - __logf(1.f + __expf(-fabsf(z)))) * (1.f / 16.f);
;             }
; #pragma unroll
;             for (int o = 1; o < 64; o <<= 1) {
;                 const float t0 = __shfl_up(cum[0], o), t1 = __shfl_up(cum[1], o);
;                 if (l >= o) { cum[0] += t0; cum[1] += t1; }
;             }
;             const float tot0 = __shfl(cum[0], 63), tot1 = __shfl(cum[1], 63);
;             kdl[(buf * 16 + 2 * w) * 64 + l] = f2bf(bf2f(kraw & 0xffffu) * __expf(tot0 - cum[0]));
;             kdl[(buf * 16 + 2 * w + 1) * 64 + l] = f2bf(bf2f(kraw >> 16) * __expf(tot1 - cum[1]));
;             if (l == 0) { decl[buf * 16 + 2 * w] = __expf(tot0); decl[buf * 16 + 2 * w + 1] = __expf(tot1); }
;             __syncthreads();
;             const f32x4 d4 = *(const f32x4*)(decl + buf * 16 + (l >> 4) * 4);
; #pragma unroll
;             for (int e = 0; e < 2; ++e) acc[e] = acc[e] * d4;
; #pragma unroll
;             for (int ks = 0; ks < 2; ++ks) {
;                 const bf16x8 af = *(const bf16x8*)(kdl + (buf * 16 + (l & 15)) * 64 + ks * 32 + (l >> 4) * 8);
; #pragma unroll
;                 for (int e = 0; e < 2; ++e) acc[e] = MFMA16(af, vfr[e][ks], acc[e]);
;             }
;             const int cidx = b * 64 + n;
; #pragma unroll
;             for (int e = 0; e < 2; ++e) {
;                 const int vv = (2 * w + e) * 16 + (l & 15);
;                 *(u32x2*)(ST + (((size_t)(cidx * 4 + hh)) * 256 + vv) * 128 + ksl * 16 + (l >> 4) * 4) = pk4(acc[e].x, acc[e].y, acc[e].z, acc[e].w);
;             }
	ds_read_b128 v[8:11], v29 offset:0
	ds_read_b128 v[12:15], v29 offset:16
	ds_read_b128 v[16:19], v29 offset:32
	ds_read_b128 v[20:23], v29 offset:48
	ds_read_b32 v24, v31 offset:0
	global_load_dwordx2 v[56:57], v230, s[26:27]
	global_load_dword v58, v231, s[58:59]
	s_add_u32 s26, s26, 0x1000
	s_addc_u32 s27, s27, 0
	s_add_u32 s58, s58, 0x10000
	s_addc_u32 s59, s59, 0
	v_xor_b32_e32 v26, s57, v25
	v_add_u32_e32 v59, v26, v232
	v_add_u32_e32 v63, 0x20000, v59
	global_load_dwordx4 v[32:35], v59, s[34:35]
	global_load_dwordx4 v[36:39], v59, s[34:35] offset:64
	global_load_dwordx4 v[40:43], v63, s[34:35]
	global_load_dwordx4 v[44:47], v63, s[34:35] offset:64
	s_add_u32 s57, s57, 0x80
	ds_read_b128 v[154:157], v75 offset:2048
	ds_read_b128 v[240:243], v164 offset:4160
	ds_read_b128 v[236:239], v75 offset:2112
	s_waitcnt lgkmcnt(3)
	v_pk_fma_f32 v[64:65], v[8:9], v[86:87], v[118:119] op_sel:[0,0,0] op_sel_hi:[0,1,1]
	v_pk_mul_f32 v[66:67], v[16:17], v[102:103] op_sel:[0,0] op_sel_hi:[0,1]
	v_pk_fma_f32 v[64:65], v[8:9], v[88:89], v[64:65] op_sel:[1,0,0] op_sel_hi:[1,1,1]
	v_pk_fma_f32 v[66:67], v[16:17], v[104:105], v[66:67] op_sel:[1,0,0] op_sel_hi:[1,1,1]
	v_pk_fma_f32 v[64:65], v[10:11], v[90:91], v[64:65] op_sel:[0,0,0] op_sel_hi:[0,1,1]
	v_pk_fma_f32 v[66:67], v[18:19], v[106:107], v[66:67] op_sel:[0,0,0] op_sel_hi:[0,1,1]
	v_pk_fma_f32 v[64:65], v[10:11], v[92:93], v[64:65] op_sel:[1,0,0] op_sel_hi:[1,1,1]
	v_pk_fma_f32 v[66:67], v[18:19], v[108:109], v[66:67] op_sel:[1,0,0] op_sel_hi:[1,1,1]
	v_pk_fma_f32 v[64:65], v[12:13], v[94:95], v[64:65] op_sel:[0,0,0] op_sel_hi:[0,1,1]
	v_pk_fma_f32 v[66:67], v[20:21], v[110:111], v[66:67] op_sel:[0,0,0] op_sel_hi:[0,1,1]
	v_pk_fma_f32 v[64:65], v[12:13], v[96:97], v[64:65] op_sel:[1,0,0] op_sel_hi:[1,1,1]
	v_pk_fma_f32 v[66:67], v[20:21], v[112:113], v[66:67] op_sel:[1,0,0] op_sel_hi:[1,1,1]
	v_pk_fma_f32 v[64:65], v[14:15], v[98:99], v[64:65] op_sel:[0,0,0] op_sel_hi:[0,1,1]
	v_pk_fma_f32 v[66:67], v[22:23], v[114:115], v[66:67] op_sel:[0,0,0] op_sel_hi:[0,1,1]
	v_pk_fma_f32 v[64:65], v[14:15], v[100:101], v[64:65] op_sel:[1,0,0] op_sel_hi:[1,1,1]
	v_pk_fma_f32 v[66:67], v[22:23], v[116:117], v[66:67] op_sel:[1,0,0] op_sel_hi:[1,1,1]
	v_lshlrev_b32_e32 v148, 16, v24
	v_pk_add_f32 v[64:65], v[64:65], v[66:67]
	v_and_b32_e32 v149, 0xffff0000, v24
	s_waitcnt lgkmcnt(0)
	v_pk_mul_f32 v[0:1], v[0:1], v[240:241]
	v_pk_mul_f32 v[2:3], v[2:3], v[242:243]
	v_pk_mul_f32 v[4:5], v[4:5], v[240:241]
	v_pk_mul_f32 v[6:7], v[6:7], v[242:243]
	s_waitcnt vmcnt(14)
	s_nop 0
	v_mfma_f32_16x16x32_bf16 v[0:3], v[154:157], v[178:181], v[0:3]
	v_mfma_f32_16x16x32_bf16 v[4:7], v[154:157], v[186:189], v[4:7]
	v_mfma_f32_16x16x32_bf16 v[0:3], v[236:239], v[182:185], v[0:3]
	v_mfma_f32_16x16x32_bf16 v[4:7], v[236:239], v[190:193], v[4:7]
	v_mul_f32_e64 v68, |v64|, v220
	v_mul_f32_e64 v69, |v65|, v220
	v_exp_f32_e32 v68, v68
	v_exp_f32_e32 v69, v69
	v_min_f32_e32 v70, 0, v64
	v_min_f32_e32 v71, 0, v65
	v_pk_add_f32 v[68:69], v[68:69], v[222:223]
	s_nop 0
	v_log_f32_e32 v138, v68
	v_log_f32_e32 v139, v69
	s_nop 0
	v_pk_mul_f32 v[140:141], v[138:139], v[224:225]
	s_nop 0
	v_pk_fma_f32 v[142:143], v[138:139], v[224:225], v[140:141] neg_lo:[0,0,1] neg_hi:[0,0,1]
	s_nop 0
	v_pk_fma_f32 v[142:143], v[138:139], v[226:227], v[142:143]
	s_nop 0
	v_pk_fma_f32 v[142:143], v[138:139], v[224:225], v[142:143]
	s_nop 0
	v_pk_add_f32 v[144:145], v[70:71], v[142:143] neg_lo:[0,1] neg_hi:[0,1]
	s_nop 0
	v_pk_mul_f32 v[144:145], v[144:145], v[214:215]
	v_cvt_pk_bf16_f32 v244, v0, v1
	v_cvt_pk_bf16_f32 v245, v2, v3
	v_cvt_pk_bf16_f32 v246, v4, v5
	v_cvt_pk_bf16_f32 v247, v6, v7
	global_store_dwordx2 v234, v[244:245], s[100:101]
	global_store_dwordx2 v235, v[246:247], s[100:101]
	s_add_u32 s100, s100, 0x40000
	s_addc_u32 s101, s101, 0
	v_add_f32_dpp v144, v144, v144 row_shr:1 row_mask:0xf bank_mask:0xf
	v_add_f32_dpp v145, v145, v145 row_shr:1 row_mask:0xf bank_mask:0xf
	s_nop 0
	v_add_f32_dpp v144, v144, v144 row_shr:2 row_mask:0xf bank_mask:0xf
	v_add_f32_dpp v145, v145, v145 row_shr:2 row_mask:0xf bank_mask:0xf
	s_nop 0
	v_add_f32_dpp v144, v144, v144 row_shr:4 row_mask:0xf bank_mask:0xf
	v_add_f32_dpp v145, v145, v145 row_shr:4 row_mask:0xf bank_mask:0xf
	s_nop 0
	v_add_f32_dpp v144, v144, v144 row_shr:8 row_mask:0xf bank_mask:0xf
	v_add_f32_dpp v145, v145, v145 row_shr:8 row_mask:0xf bank_mask:0xf
	s_nop 0
	v_add_f32_dpp v144, v144, v144 row_bcast:15 row_mask:0xa bank_mask:0xf
	v_add_f32_dpp v145, v145, v145 row_bcast:15 row_mask:0xa bank_mask:0xf
	s_nop 0
	v_add_f32_dpp v144, v144, v144 row_bcast:31 row_mask:0xc bank_mask:0xf
	v_add_f32_dpp v145, v145, v145 row_bcast:31 row_mask:0xc bank_mask:0xf
	s_nop 0
	v_readlane_b32 s98, v144, 63
	v_readlane_b32 s99, v145, 63
	s_nop 1
	v_pk_add_f32 v[146:147], s[98:99], v[144:145] neg_lo:[0,1] neg_hi:[0,1]
	v_mul_f32_e64 v152, s98, v228
	v_mul_f32_e64 v153, s99, v228
	v_pk_mul_f32 v[146:147], v[146:147], v[228:229]
	v_exp_f32_e32 v152, v152
	v_exp_f32_e32 v153, v153
	v_exp_f32_e32 v146, v146
	v_exp_f32_e32 v147, v147
	s_nop 0
	v_pk_mul_f32 v[146:147], v[146:147], v[148:149]
	s_nop 0
	v_cvt_pk_bf16_f32 v150, v146, v147
	s_nop 0
	ds_write_b16 v172, v150 offset:0
	ds_write_b16_d16_hi v172, v150 offset:128
	s_and_saveexec_b64 s[20:21], vcc
	ds_write_b64 v163, v[152:153] offset:4096
	s_mov_b64 exec, s[20:21]
	s_waitcnt vmcnt(20)
	ds_write_b64 v28, v[48:49] offset:5120
	ds_write_b32 v30, v50 offset:2080
	s_waitcnt lgkmcnt(0)
	s_barrier
; #define MFMA16(a, b, c) __builtin_amdgcn_mfma_f32_16x16x32_bf16((a), (b), (c), 0, 0, 0)
;     ...
;         for (int n = 0; n < 64; ++n) {
;             const int buf = n & 1;
;             f32x4 a4[4]; bf16x8 vfr[2][2];
; #pragma unroll
;             for (int q = 0; q < 4; ++q) a4[q] = a4n[q];
;             const unsigned kraw = krawn;
; #pragma unroll
;             for (int e = 0; e < 2; ++e)
; #pragma unroll
;                 for (int ks = 0; ks < 2; ++ks) vfr[e][ks] = vfrn[e][ks];
;             if (n + 1 < 64) ldchunk(n + 1);
;             float cum[2];
; #pragma unroll
;             for (int e = 0; e < 2; ++e) {
;                 float z = bb[e];
; #pragma unroll
;                 for (int q = 0; q < 4; ++q) { z += a4[q].x * wa[e][4 * q] + a4[q].y * wa[e][4 * q + 1] + a4[q].z * wa[e][4 * q + 2] + a4[q].w * wa[e][4 * q + 3]; }
;                 cum[e] = (fminf(z, 0.f) - __logf(1.f + __expf(-fabsf(z)))) * (1.f / 16.f);
;             }
; #pragma unroll
;             for (int o = 1; o < 64; o <<= 1) {
;                 const float t0 = __shfl_up(cum[0], o), t1 = __shfl_up(cum[1], o);
;                 if (l >= o) { cum[0] += t0; cum[1] += t1; }
;             }
;             const float tot0 = __shfl(cum[0], 63), tot1 = __shfl(cum[1], 63);
;             kdl[(buf * 16 + 2 * w) * 64 + l] = f2bf(bf2f(kraw & 0xffffu) * __expf(tot0 - cum[0]));
;             kdl[(buf * 16 + 2 * w + 1) * 64 + l] = f2bf(bf2f(kraw >> 16) * __expf(tot1 - cum[1]));
;             if (l == 0) { decl[buf * 16 + 2 * w] = __expf(tot0); decl[buf * 16 + 2 * w + 1] = __expf(tot1); }
;             __syncthreads();
;             const f32x4 d4 = *(const f32x4*)(decl + buf * 16 + (l >> 4) * 4);
; #pragma unroll
;             for (int e = 0; e < 2; ++e) acc[e] = acc[e] * d4;
; #pragma unroll
;             for (int ks = 0; ks < 2; ++ks) {
;                 const bf16x8 af = *(const bf16x8*)(kdl + (buf * 16 + (l & 15)) * 64 + ks * 32 + (l >> 4) * 8);
; #pragma unroll
;                 for (int e = 0; e < 2; ++e) acc[e] = MFMA16(af, vfr[e][ks], acc[e]);
;             }
;             const int cidx = b * 64 + n;
; #pragma unroll
;             for (int e = 0; e < 2; ++e) {
;                 const int vv = (2 * w + e) * 16 + (l & 15);
;                 *(u32x2*)(ST + (((size_t)(cidx * 4 + hh)) * 256 + vv) * 128 + ksl * 16 + (l >> 4) * 4) = pk4(acc[e].x, acc[e].y, acc[e].z, acc[e].w);
;             }
	ds_read_b128 v[8:11], v29 offset:5120
	ds_read_b128 v[12:15], v29 offset:5136
	ds_read_b128 v[16:19], v29 offset:5152
	ds_read_b128 v[20:23], v29 offset:5168
	ds_read_b32 v24, v31 offset:2080
	global_load_dwordx2 v[48:49], v230, s[26:27]
	global_load_dword v50, v231, s[58:59]
	s_add_u32 s26, s26, 0x1000
	s_addc_u32 s27, s27, 0
	s_add_u32 s58, s58, 0x10000
	s_addc_u32 s59, s59, 0
	v_xor_b32_e32 v26, s57, v25
	v_add_u32_e32 v59, v26, v232
	v_add_u32_e32 v63, 0x20000, v59
	global_load_dwordx4 v[178:181], v59, s[34:35]
	global_load_dwordx4 v[182:185], v59, s[34:35] offset:64
	global_load_dwordx4 v[186:189], v63, s[34:35]
	global_load_dwordx4 v[190:193], v63, s[34:35] offset:64
	s_add_u32 s57, s57, 0x80
	ds_read_b128 v[154:157], v75 offset:0
	ds_read_b128 v[240:243], v164 offset:4096
	ds_read_b128 v[236:239], v75 offset:64
	s_waitcnt lgkmcnt(3)
	v_pk_fma_f32 v[64:65], v[8:9], v[86:87], v[118:119] op_sel:[0,0,0] op_sel_hi:[0,1,1]
	v_pk_mul_f32 v[66:67], v[16:17], v[102:103] op_sel:[0,0] op_sel_hi:[0,1]
	v_pk_fma_f32 v[64:65], v[8:9], v[88:89], v[64:65] op_sel:[1,0,0] op_sel_hi:[1,1,1]
	v_pk_fma_f32 v[66:67], v[16:17], v[104:105], v[66:67] op_sel:[1,0,0] op_sel_hi:[1,1,1]
	v_pk_fma_f32 v[64:65], v[10:11], v[90:91], v[64:65] op_sel:[0,0,0] op_sel_hi:[0,1,1]
	v_pk_fma_f32 v[66:67], v[18:19], v[106:107], v[66:67] op_sel:[0,0,0] op_sel_hi:[0,1,1]
	v_pk_fma_f32 v[64:65], v[10:11], v[92:93], v[64:65] op_sel:[1,0,0] op_sel_hi:[1,1,1]
	v_pk_fma_f32 v[66:67], v[18:19], v[108:109], v[66:67] op_sel:[1,0,0] op_sel_hi:[1,1,1]
	v_pk_fma_f32 v[64:65], v[12:13], v[94:95], v[64:65] op_sel:[0,0,0] op_sel_hi:[0,1,1]
	v_pk_fma_f32 v[66:67], v[20:21], v[110:111], v[66:67] op_sel:[0,0,0] op_sel_hi:[0,1,1]
	v_pk_fma_f32 v[64:65], v[12:13], v[96:97], v[64:65] op_sel:[1,0,0] op_sel_hi:[1,1,1]
	v_pk_fma_f32 v[66:67], v[20:21], v[112:113], v[66:67] op_sel:[1,0,0] op_sel_hi:[1,1,1]
	v_pk_fma_f32 v[64:65], v[14:15], v[98:99], v[64:65] op_sel:[0,0,0] op_sel_hi:[0,1,1]
	v_pk_fma_f32 v[66:67], v[22:23], v[114:115], v[66:67] op_sel:[0,0,0] op_sel_hi:[0,1,1]
	v_pk_fma_f32 v[64:65], v[14:15], v[100:101], v[64:65] op_sel:[1,0,0] op_sel_hi:[1,1,1]
	v_pk_fma_f32 v[66:67], v[22:23], v[116:117], v[66:67] op_sel:[1,0,0] op_sel_hi:[1,1,1]
	v_lshlrev_b32_e32 v148, 16, v24
	v_pk_add_f32 v[64:65], v[64:65], v[66:67]
	v_and_b32_e32 v149, 0xffff0000, v24
	s_waitcnt lgkmcnt(0)
	v_pk_mul_f32 v[0:1], v[0:1], v[240:241]
	v_pk_mul_f32 v[2:3], v[2:3], v[242:243]
	v_pk_mul_f32 v[4:5], v[4:5], v[240:241]
	v_pk_mul_f32 v[6:7], v[6:7], v[242:243]
	s_waitcnt vmcnt(16)
	s_nop 0
	v_mfma_f32_16x16x32_bf16 v[0:3], v[154:157], v[194:197], v[0:3]
	v_mfma_f32_16x16x32_bf16 v[4:7], v[154:157], v[202:205], v[4:7]
	v_mfma_f32_16x16x32_bf16 v[0:3], v[236:239], v[198:201], v[0:3]
	v_mfma_f32_16x16x32_bf16 v[4:7], v[236:239], v[206:209], v[4:7]
	v_mul_f32_e64 v68, |v64|, v220
	v_mul_f32_e64 v69, |v65|, v220
	v_exp_f32_e32 v68, v68
	v_exp_f32_e32 v69, v69
	v_min_f32_e32 v70, 0, v64
	v_min_f32_e32 v71, 0, v65
	v_pk_add_f32 v[68:69], v[68:69], v[222:223]
	s_nop 0
	v_log_f32_e32 v138, v68
	v_log_f32_e32 v139, v69
	s_nop 0
	v_pk_mul_f32 v[140:141], v[138:139], v[224:225]
	s_nop 0
	v_pk_fma_f32 v[142:143], v[138:139], v[224:225], v[140:141] neg_lo:[0,0,1] neg_hi:[0,0,1]
	s_nop 0
	v_pk_fma_f32 v[142:143], v[138:139], v[226:227], v[142:143]
	s_nop 0
	v_pk_fma_f32 v[142:143], v[138:139], v[224:225], v[142:143]
	s_nop 0
	v_pk_add_f32 v[144:145], v[70:71], v[142:143] neg_lo:[0,1] neg_hi:[0,1]
	s_nop 0
	v_pk_mul_f32 v[144:145], v[144:145], v[214:215]
	v_cvt_pk_bf16_f32 v244, v0, v1
	v_cvt_pk_bf16_f32 v245, v2, v3
	v_cvt_pk_bf16_f32 v246, v4, v5
	v_cvt_pk_bf16_f32 v247, v6, v7
	global_store_dwordx2 v234, v[244:245], s[100:101]
	global_store_dwordx2 v235, v[246:247], s[100:101]
	s_add_u32 s100, s100, 0x40000
	s_addc_u32 s101, s101, 0
	v_add_f32_dpp v144, v144, v144 row_shr:1 row_mask:0xf bank_mask:0xf
	v_add_f32_dpp v145, v145, v145 row_shr:1 row_mask:0xf bank_mask:0xf
	s_nop 0
	v_add_f32_dpp v144, v144, v144 row_shr:2 row_mask:0xf bank_mask:0xf
	v_add_f32_dpp v145, v145, v145 row_shr:2 row_mask:0xf bank_mask:0xf
	s_nop 0
	v_add_f32_dpp v144, v144, v144 row_shr:4 row_mask:0xf bank_mask:0xf
	v_add_f32_dpp v145, v145, v145 row_shr:4 row_mask:0xf bank_mask:0xf
	s_nop 0
	v_add_f32_dpp v144, v144, v144 row_shr:8 row_mask:0xf bank_mask:0xf
	v_add_f32_dpp v145, v145, v145 row_shr:8 row_mask:0xf bank_mask:0xf
	s_nop 0
	v_add_f32_dpp v144, v144, v144 row_bcast:15 row_mask:0xa bank_mask:0xf
	v_add_f32_dpp v145, v145, v145 row_bcast:15 row_mask:0xa bank_mask:0xf
	s_nop 0
	v_add_f32_dpp v144, v144, v144 row_bcast:31 row_mask:0xc bank_mask:0xf
	v_add_f32_dpp v145, v145, v145 row_bcast:31 row_mask:0xc bank_mask:0xf
	s_nop 0
	v_readlane_b32 s98, v144, 63
	v_readlane_b32 s99, v145, 63
	s_nop 1
	v_pk_add_f32 v[146:147], s[98:99], v[144:145] neg_lo:[0,1] neg_hi:[0,1]
	v_mul_f32_e64 v152, s98, v228
	v_mul_f32_e64 v153, s99, v228
	v_pk_mul_f32 v[146:147], v[146:147], v[228:229]
	v_exp_f32_e32 v152, v152
	v_exp_f32_e32 v153, v153
	v_exp_f32_e32 v146, v146
	v_exp_f32_e32 v147, v147
	s_nop 0
	v_pk_mul_f32 v[146:147], v[146:147], v[148:149]
	s_nop 0
	v_cvt_pk_bf16_f32 v150, v146, v147
	s_nop 0
	ds_write_b16 v172, v150 offset:2048
	ds_write_b16_d16_hi v172, v150 offset:2176
	s_and_saveexec_b64 s[20:21], vcc
	ds_write_b64 v163, v[152:153] offset:4160
	s_mov_b64 exec, s[20:21]
	s_waitcnt vmcnt(22)
	ds_write_b64 v28, v[52:53] offset:0
	ds_write_b32 v30, v54 offset:0
	s_waitcnt lgkmcnt(0)
	s_barrier
; #define MFMA16(a, b, c) __builtin_amdgcn_mfma_f32_16x16x32_bf16((a), (b), (c), 0, 0, 0)
;     ...
;         for (int n = 0; n < 64; ++n) {
;             const int buf = n & 1;
;             f32x4 a4[4]; bf16x8 vfr[2][2];
; #pragma unroll
;             for (int q = 0; q < 4; ++q) a4[q] = a4n[q];
;             const unsigned kraw = krawn;
; #pragma unroll
;             for (int e = 0; e < 2; ++e)
; #pragma unroll
;                 for (int ks = 0; ks < 2; ++ks) vfr[e][ks] = vfrn[e][ks];
;             if (n + 1 < 64) ldchunk(n + 1);
;             float cum[2];
; #pragma unroll
;             for (int e = 0; e < 2; ++e) {
;                 float z = bb[e];
; #pragma unroll
;                 for (int q = 0; q < 4; ++q) { z += a4[q].x * wa[e][4 * q] + a4[q].y * wa[e][4 * q + 1] + a4[q].z * wa[e][4 * q + 2] + a4[q].w * wa[e][4 * q + 3]; }
;                 cum[e] = (fminf(z, 0.f) - __logf(1.f + __expf(-fabsf(z)))) * (1.f / 16.f);
;             }
; #pragma unroll
;             for (int o = 1; o < 64; o <<= 1) {
;                 const float t0 = __shfl_up(cum[0], o), t1 = __shfl_up(cum[1], o);
;                 if (l >= o) { cum[0] += t0; cum[1] += t1; }
;             }
;             const float tot0 = __shfl(cum[0], 63), tot1 = __shfl(cum[1], 63);
;             kdl[(buf * 16 + 2 * w) * 64 + l] = f2bf(bf2f(kraw & 0xffffu) * __expf(tot0 - cum[0]));
;             kdl[(buf * 16 + 2 * w + 1) * 64 + l] = f2bf(bf2f(kraw >> 16) * __expf(tot1 - cum[1]));
;             if (l == 0) { decl[buf * 16 + 2 * w] = __expf(tot0); decl[buf * 16 + 2 * w + 1] = __expf(tot1); }
;             __syncthreads();
;             const f32x4 d4 = *(const f32x4*)(decl + buf * 16 + (l >> 4) * 4);
; #pragma unroll
;             for (int e = 0; e < 2; ++e) acc[e] = acc[e] * d4;
; #pragma unroll
;             for (int ks = 0; ks < 2; ++ks) {
;                 const bf16x8 af = *(const bf16x8*)(kdl + (buf * 16 + (l & 15)) * 64 + ks * 32 + (l >> 4) * 8);
; #pragma unroll
;                 for (int e = 0; e < 2; ++e) acc[e] = MFMA16(af, vfr[e][ks], acc[e]);
;             }
;             const int cidx = b * 64 + n;
; #pragma unroll
;             for (int e = 0; e < 2; ++e) {
;                 const int vv = (2 * w + e) * 16 + (l & 15);
;                 *(u32x2*)(ST + (((size_t)(cidx * 4 + hh)) * 256 + vv) * 128 + ksl * 16 + (l >> 4) * 4) = pk4(acc[e].x, acc[e].y, acc[e].z, acc[e].w);
;             }
	ds_read_b128 v[8:11], v29 offset:0
	ds_read_b128 v[12:15], v29 offset:16
	ds_read_b128 v[16:19], v29 offset:32
	ds_read_b128 v[20:23], v29 offset:48
	ds_read_b32 v24, v31 offset:0
	global_load_dwordx2 v[52:53], v230, s[26:27]
	global_load_dword v54, v231, s[58:59]
	s_add_u32 s26, s26, 0x1000
	s_addc_u32 s27, s27, 0
	s_add_u32 s58, s58, 0x10000
	s_addc_u32 s59, s59, 0
	v_xor_b32_e32 v26, s57, v25
	v_add_u32_e32 v59, v26, v232
	v_add_u32_e32 v63, 0x20000, v59
	global_load_dwordx4 v[194:197], v59, s[34:35]
	global_load_dwordx4 v[198:201], v59, s[34:35] offset:64
	global_load_dwordx4 v[202:205], v63, s[34:35]
	global_load_dwordx4 v[206:209], v63, s[34:35] offset:64
	s_add_u32 s57, s57, 0x80
	ds_read_b128 v[154:157], v75 offset:2048
	ds_read_b128 v[240:243], v164 offset:4160
	ds_read_b128 v[236:239], v75 offset:2112
	s_waitcnt lgkmcnt(3)
	v_pk_fma_f32 v[64:65], v[8:9], v[86:87], v[118:119] op_sel:[0,0,0] op_sel_hi:[0,1,1]
	v_pk_mul_f32 v[66:67], v[16:17], v[102:103] op_sel:[0,0] op_sel_hi:[0,1]
	v_pk_fma_f32 v[64:65], v[8:9], v[88:89], v[64:65] op_sel:[1,0,0] op_sel_hi:[1,1,1]
	v_pk_fma_f32 v[66:67], v[16:17], v[104:105], v[66:67] op_sel:[1,0,0] op_sel_hi:[1,1,1]
	v_pk_fma_f32 v[64:65], v[10:11], v[90:91], v[64:65] op_sel:[0,0,0] op_sel_hi:[0,1,1]
	v_pk_fma_f32 v[66:67], v[18:19], v[106:107], v[66:67] op_sel:[0,0,0] op_sel_hi:[0,1,1]
	v_pk_fma_f32 v[64:65], v[10:11], v[92:93], v[64:65] op_sel:[1,0,0] op_sel_hi:[1,1,1]
	v_pk_fma_f32 v[66:67], v[18:19], v[108:109], v[66:67] op_sel:[1,0,0] op_sel_hi:[1,1,1]
	v_pk_fma_f32 v[64:65], v[12:13], v[94:95], v[64:65] op_sel:[0,0,0] op_sel_hi:[0,1,1]
	v_pk_fma_f32 v[66:67], v[20:21], v[110:111], v[66:67] op_sel:[0,0,0] op_sel_hi:[0,1,1]
	v_pk_fma_f32 v[64:65], v[12:13], v[96:97], v[64:65] op_sel:[1,0,0] op_sel_hi:[1,1,1]
	v_pk_fma_f32 v[66:67], v[20:21], v[112:113], v[66:67] op_sel:[1,0,0] op_sel_hi:[1,1,1]
	v_pk_fma_f32 v[64:65], v[14:15], v[98:99], v[64:65] op_sel:[0,0,0] op_sel_hi:[0,1,1]
	v_pk_fma_f32 v[66:67], v[22:23], v[114:115], v[66:67] op_sel:[0,0,0] op_sel_hi:[0,1,1]
	v_pk_fma_f32 v[64:65], v[14:15], v[100:101], v[64:65] op_sel:[1,0,0] op_sel_hi:[1,1,1]
	v_pk_fma_f32 v[66:67], v[22:23], v[116:117], v[66:67] op_sel:[1,0,0] op_sel_hi:[1,1,1]
	v_lshlrev_b32_e32 v148, 16, v24
	v_pk_add_f32 v[64:65], v[64:65], v[66:67]
	v_and_b32_e32 v149, 0xffff0000, v24
	s_waitcnt lgkmcnt(0)
	v_pk_mul_f32 v[0:1], v[0:1], v[240:241]
	v_pk_mul_f32 v[2:3], v[2:3], v[242:243]
	v_pk_mul_f32 v[4:5], v[4:5], v[240:241]
	v_pk_mul_f32 v[6:7], v[6:7], v[242:243]
	s_waitcnt vmcnt(16)
	s_nop 0
	v_mfma_f32_16x16x32_bf16 v[0:3], v[154:157], v[32:35], v[0:3]
	v_mfma_f32_16x16x32_bf16 v[4:7], v[154:157], v[40:43], v[4:7]
	v_mfma_f32_16x16x32_bf16 v[0:3], v[236:239], v[36:39], v[0:3]
	v_mfma_f32_16x16x32_bf16 v[4:7], v[236:239], v[44:47], v[4:7]
	v_mul_f32_e64 v68, |v64|, v220
	v_mul_f32_e64 v69, |v65|, v220
	v_exp_f32_e32 v68, v68
	v_exp_f32_e32 v69, v69
	v_min_f32_e32 v70, 0, v64
	v_min_f32_e32 v71, 0, v65
	v_pk_add_f32 v[68:69], v[68:69], v[222:223]
	s_nop 0
	v_log_f32_e32 v138, v68
	v_log_f32_e32 v139, v69
	s_nop 0
	v_pk_mul_f32 v[140:141], v[138:139], v[224:225]
	s_nop 0
	v_pk_fma_f32 v[142:143], v[138:139], v[224:225], v[140:141] neg_lo:[0,0,1] neg_hi:[0,0,1]
	s_nop 0
	v_pk_fma_f32 v[142:143], v[138:139], v[226:227], v[142:143]
	s_nop 0
	v_pk_fma_f32 v[142:143], v[138:139], v[224:225], v[142:143]
	s_nop 0
	v_pk_add_f32 v[144:145], v[70:71], v[142:143] neg_lo:[0,1] neg_hi:[0,1]
	s_nop 0
	v_pk_mul_f32 v[144:145], v[144:145], v[214:215]
	v_cvt_pk_bf16_f32 v244, v0, v1
	v_cvt_pk_bf16_f32 v245, v2, v3
	v_cvt_pk_bf16_f32 v246, v4, v5
	v_cvt_pk_bf16_f32 v247, v6, v7
	global_store_dwordx2 v234, v[244:245], s[100:101]
	global_store_dwordx2 v235, v[246:247], s[100:101]
	s_add_u32 s100, s100, 0x40000
	s_addc_u32 s101, s101, 0
	v_add_f32_dpp v144, v144, v144 row_shr:1 row_mask:0xf bank_mask:0xf
	v_add_f32_dpp v145, v145, v145 row_shr:1 row_mask:0xf bank_mask:0xf
	s_nop 0
	v_add_f32_dpp v144, v144, v144 row_shr:2 row_mask:0xf bank_mask:0xf
	v_add_f32_dpp v145, v145, v145 row_shr:2 row_mask:0xf bank_mask:0xf
	s_nop 0
	v_add_f32_dpp v144, v144, v144 row_shr:4 row_mask:0xf bank_mask:0xf
	v_add_f32_dpp v145, v145, v145 row_shr:4 row_mask:0xf bank_mask:0xf
	s_nop 0
	v_add_f32_dpp v144, v144, v144 row_shr:8 row_mask:0xf bank_mask:0xf
	v_add_f32_dpp v145, v145, v145 row_shr:8 row_mask:0xf bank_mask:0xf
	s_nop 0
	v_add_f32_dpp v144, v144, v144 row_bcast:15 row_mask:0xa bank_mask:0xf
	v_add_f32_dpp v145, v145, v145 row_bcast:15 row_mask:0xa bank_mask:0xf
	s_nop 0
	v_add_f32_dpp v144, v144, v144 row_bcast:31 row_mask:0xc bank_mask:0xf
	v_add_f32_dpp v145, v145, v145 row_bcast:31 row_mask:0xc bank_mask:0xf
	s_nop 0
	v_readlane_b32 s98, v144, 63
	v_readlane_b32 s99, v145, 63
	s_nop 1
	v_pk_add_f32 v[146:147], s[98:99], v[144:145] neg_lo:[0,1] neg_hi:[0,1]
	v_mul_f32_e64 v152, s98, v228
	v_mul_f32_e64 v153, s99, v228
	v_pk_mul_f32 v[146:147], v[146:147], v[228:229]
	v_exp_f32_e32 v152, v152
	v_exp_f32_e32 v153, v153
	v_exp_f32_e32 v146, v146
	v_exp_f32_e32 v147, v147
	s_nop 0
	v_pk_mul_f32 v[146:147], v[146:147], v[148:149]
	s_nop 0
	v_cvt_pk_bf16_f32 v150, v146, v147
	s_nop 0
	ds_write_b16 v172, v150 offset:0
	ds_write_b16_d16_hi v172, v150 offset:128
	s_and_saveexec_b64 s[20:21], vcc
	ds_write_b64 v163, v[152:153] offset:4096
	s_mov_b64 exec, s[20:21]
	s_waitcnt vmcnt(22)
	ds_write_b64 v28, v[56:57] offset:5120
	ds_write_b32 v30, v58 offset:2080
	s_waitcnt lgkmcnt(0)
	s_barrier
; #define MFMA16(a, b, c) __builtin_amdgcn_mfma_f32_16x16x32_bf16((a), (b), (c), 0, 0, 0)
;     ...
;         for (int n = 0; n < 64; ++n) {
;             const int buf = n & 1;
;             f32x4 a4[4]; bf16x8 vfr[2][2];
; #pragma unroll
;             for (int q = 0; q < 4; ++q) a4[q] = a4n[q];
;             const unsigned kraw = krawn;
; #pragma unroll
;             for (int e = 0; e < 2; ++e)
; #pragma unroll
;                 for (int ks = 0; ks < 2; ++ks) vfr[e][ks] = vfrn[e][ks];
;             if (n + 1 < 64) ldchunk(n + 1);
;             float cum[2];
; #pragma unroll
;             for (int e = 0; e < 2; ++e) {
;                 float z = bb[e];
; #pragma unroll
;                 for (int q = 0; q < 4; ++q) { z += a4[q].x * wa[e][4 * q] + a4[q].y * wa[e][4 * q + 1] + a4[q].z * wa[e][4 * q + 2] + a4[q].w * wa[e][4 * q + 3]; }
;                 cum[e] = (fminf(z, 0.f) - __logf(1.f + __expf(-fabsf(z)))) * (1.f / 16.f);
;             }
; #pragma unroll
;             for (int o = 1; o < 64; o <<= 1) {
;                 const float t0 = __shfl_up(cum[0], o), t1 = __shfl_up(cum[1], o);
;                 if (l >= o) { cum[0] += t0; cum[1] += t1; }
;             }
;             const float tot0 = __shfl(cum[0], 63), tot1 = __shfl(cum[1], 63);
;             kdl[(buf * 16 + 2 * w) * 64 + l] = f2bf(bf2f(kraw & 0xffffu) * __expf(tot0 - cum[0]));
;             kdl[(buf * 16 + 2 * w + 1) * 64 + l] = f2bf(bf2f(kraw >> 16) * __expf(tot1 - cum[1]));
;             if (l == 0) { decl[buf * 16 + 2 * w] = __expf(tot0); decl[buf * 16 + 2 * w + 1] = __expf(tot1); }
;             __syncthreads();
;             const f32x4 d4 = *(const f32x4*)(decl + buf * 16 + (l >> 4) * 4);
; #pragma unroll
;             for (int e = 0; e < 2; ++e) acc[e] = acc[e] * d4;
; #pragma unroll
;             for (int ks = 0; ks < 2; ++ks) {
;                 const bf16x8 af = *(const bf16x8*)(kdl + (buf * 16 + (l & 15)) * 64 + ks * 32 + (l >> 4) * 8);
; #pragma unroll
;                 for (int e = 0; e < 2; ++e) acc[e] = MFMA16(af, vfr[e][ks], acc[e]);
;             }
;             const int cidx = b * 64 + n;
; #pragma unroll
;             for (int e = 0; e < 2; ++e) {
;                 const int vv = (2 * w + e) * 16 + (l & 15);
;                 *(u32x2*)(ST + (((size_t)(cidx * 4 + hh)) * 256 + vv) * 128 + ksl * 16 + (l >> 4) * 4) = pk4(acc[e].x, acc[e].y, acc[e].z, acc[e].w);
;             }
	ds_read_b128 v[8:11], v29 offset:5120
	ds_read_b128 v[12:15], v29 offset:5136
	ds_read_b128 v[16:19], v29 offset:5152
	ds_read_b128 v[20:23], v29 offset:5168
	ds_read_b32 v24, v31 offset:2080
	global_load_dwordx2 v[56:57], v230, s[26:27]
	global_load_dword v58, v231, s[58:59]
	s_add_u32 s26, s26, 0x1000
	s_addc_u32 s27, s27, 0
	s_add_u32 s58, s58, 0x10000
	s_addc_u32 s59, s59, 0
	v_xor_b32_e32 v26, s57, v25
	v_add_u32_e32 v59, v26, v232
	v_add_u32_e32 v63, 0x20000, v59
	global_load_dwordx4 v[32:35], v59, s[34:35]
	global_load_dwordx4 v[36:39], v59, s[34:35] offset:64
	global_load_dwordx4 v[40:43], v63, s[34:35]
	global_load_dwordx4 v[44:47], v63, s[34:35] offset:64
	s_add_u32 s57, s57, 0x80
	ds_read_b128 v[154:157], v75 offset:0
	ds_read_b128 v[240:243], v164 offset:4096
	ds_read_b128 v[236:239], v75 offset:64
	s_waitcnt lgkmcnt(3)
	v_pk_fma_f32 v[64:65], v[8:9], v[86:87], v[118:119] op_sel:[0,0,0] op_sel_hi:[0,1,1]
	v_pk_mul_f32 v[66:67], v[16:17], v[102:103] op_sel:[0,0] op_sel_hi:[0,1]
	v_pk_fma_f32 v[64:65], v[8:9], v[88:89], v[64:65] op_sel:[1,0,0] op_sel_hi:[1,1,1]
	v_pk_fma_f32 v[66:67], v[16:17], v[104:105], v[66:67] op_sel:[1,0,0] op_sel_hi:[1,1,1]
	v_pk_fma_f32 v[64:65], v[10:11], v[90:91], v[64:65] op_sel:[0,0,0] op_sel_hi:[0,1,1]
	v_pk_fma_f32 v[66:67], v[18:19], v[106:107], v[66:67] op_sel:[0,0,0] op_sel_hi:[0,1,1]
	v_pk_fma_f32 v[64:65], v[10:11], v[92:93], v[64:65] op_sel:[1,0,0] op_sel_hi:[1,1,1]
	v_pk_fma_f32 v[66:67], v[18:19], v[108:109], v[66:67] op_sel:[1,0,0] op_sel_hi:[1,1,1]
	v_pk_fma_f32 v[64:65], v[12:13], v[94:95], v[64:65] op_sel:[0,0,0] op_sel_hi:[0,1,1]
	v_pk_fma_f32 v[66:67], v[20:21], v[110:111], v[66:67] op_sel:[0,0,0] op_sel_hi:[0,1,1]
	v_pk_fma_f32 v[64:65], v[12:13], v[96:97], v[64:65] op_sel:[1,0,0] op_sel_hi:[1,1,1]
	v_pk_fma_f32 v[66:67], v[20:21], v[112:113], v[66:67] op_sel:[1,0,0] op_sel_hi:[1,1,1]
	v_pk_fma_f32 v[64:65], v[14:15], v[98:99], v[64:65] op_sel:[0,0,0] op_sel_hi:[0,1,1]
	v_pk_fma_f32 v[66:67], v[22:23], v[114:115], v[66:67] op_sel:[0,0,0] op_sel_hi:[0,1,1]
	v_pk_fma_f32 v[64:65], v[14:15], v[100:101], v[64:65] op_sel:[1,0,0] op_sel_hi:[1,1,1]
	v_pk_fma_f32 v[66:67], v[22:23], v[116:117], v[66:67] op_sel:[1,0,0] op_sel_hi:[1,1,1]
	v_lshlrev_b32_e32 v148, 16, v24
	v_pk_add_f32 v[64:65], v[64:65], v[66:67]
	v_and_b32_e32 v149, 0xffff0000, v24
	s_waitcnt lgkmcnt(0)
	v_pk_mul_f32 v[0:1], v[0:1], v[240:241]
	v_pk_mul_f32 v[2:3], v[2:3], v[242:243]
	v_pk_mul_f32 v[4:5], v[4:5], v[240:241]
	v_pk_mul_f32 v[6:7], v[6:7], v[242:243]
	s_waitcnt vmcnt(16)
	s_nop 0
	v_mfma_f32_16x16x32_bf16 v[0:3], v[154:157], v[178:181], v[0:3]
	v_mfma_f32_16x16x32_bf16 v[4:7], v[154:157], v[186:189], v[4:7]
	v_mfma_f32_16x16x32_bf16 v[0:3], v[236:239], v[182:185], v[0:3]
	v_mfma_f32_16x16x32_bf16 v[4:7], v[236:239], v[190:193], v[4:7]
	v_mul_f32_e64 v68, |v64|, v220
	v_mul_f32_e64 v69, |v65|, v220
	v_exp_f32_e32 v68, v68
	v_exp_f32_e32 v69, v69
	v_min_f32_e32 v70, 0, v64
	v_min_f32_e32 v71, 0, v65
	v_pk_add_f32 v[68:69], v[68:69], v[222:223]
	s_nop 0
	v_log_f32_e32 v138, v68
	v_log_f32_e32 v139, v69
	s_nop 0
	v_pk_mul_f32 v[140:141], v[138:139], v[224:225]
	s_nop 0
	v_pk_fma_f32 v[142:143], v[138:139], v[224:225], v[140:141] neg_lo:[0,0,1] neg_hi:[0,0,1]
	s_nop 0
	v_pk_fma_f32 v[142:143], v[138:139], v[226:227], v[142:143]
	s_nop 0
	v_pk_fma_f32 v[142:143], v[138:139], v[224:225], v[142:143]
	s_nop 0
	v_pk_add_f32 v[144:145], v[70:71], v[142:143] neg_lo:[0,1] neg_hi:[0,1]
	s_nop 0
	v_pk_mul_f32 v[144:145], v[144:145], v[214:215]
	v_cvt_pk_bf16_f32 v244, v0, v1
	v_cvt_pk_bf16_f32 v245, v2, v3
	v_cvt_pk_bf16_f32 v246, v4, v5
	v_cvt_pk_bf16_f32 v247, v6, v7
	global_store_dwordx2 v234, v[244:245], s[100:101]
	global_store_dwordx2 v235, v[246:247], s[100:101]
	s_add_u32 s100, s100, 0x40000
	s_addc_u32 s101, s101, 0
	v_add_f32_dpp v144, v144, v144 row_shr:1 row_mask:0xf bank_mask:0xf
	v_add_f32_dpp v145, v145, v145 row_shr:1 row_mask:0xf bank_mask:0xf
	s_nop 0
	v_add_f32_dpp v144, v144, v144 row_shr:2 row_mask:0xf bank_mask:0xf
	v_add_f32_dpp v145, v145, v145 row_shr:2 row_mask:0xf bank_mask:0xf
	s_nop 0
	v_add_f32_dpp v144, v144, v144 row_shr:4 row_mask:0xf bank_mask:0xf
	v_add_f32_dpp v145, v145, v145 row_shr:4 row_mask:0xf bank_mask:0xf
	s_nop 0
	v_add_f32_dpp v144, v144, v144 row_shr:8 row_mask:0xf bank_mask:0xf
	v_add_f32_dpp v145, v145, v145 row_shr:8 row_mask:0xf bank_mask:0xf
	s_nop 0
	v_add_f32_dpp v144, v144, v144 row_bcast:15 row_mask:0xa bank_mask:0xf
	v_add_f32_dpp v145, v145, v145 row_bcast:15 row_mask:0xa bank_mask:0xf
	s_nop 0
	v_add_f32_dpp v144, v144, v144 row_bcast:31 row_mask:0xc bank_mask:0xf
	v_add_f32_dpp v145, v145, v145 row_bcast:31 row_mask:0xc bank_mask:0xf
	s_nop 0
	v_readlane_b32 s98, v144, 63
	v_readlane_b32 s99, v145, 63
	s_nop 1
	v_pk_add_f32 v[146:147], s[98:99], v[144:145] neg_lo:[0,1] neg_hi:[0,1]
	v_mul_f32_e64 v152, s98, v228
	v_mul_f32_e64 v153, s99, v228
	v_pk_mul_f32 v[146:147], v[146:147], v[228:229]
	v_exp_f32_e32 v152, v152
	v_exp_f32_e32 v153, v153
	v_exp_f32_e32 v146, v146
	v_exp_f32_e32 v147, v147
	s_nop 0
	v_pk_mul_f32 v[146:147], v[146:147], v[148:149]
	s_nop 0
	v_cvt_pk_bf16_f32 v150, v146, v147
	s_nop 0
	ds_write_b16 v172, v150 offset:2048
	ds_write_b16_d16_hi v172, v150 offset:2176
	s_and_saveexec_b64 s[20:21], vcc
	ds_write_b64 v163, v[152:153] offset:4160
	s_mov_b64 exec, s[20:21]
	s_waitcnt vmcnt(22)
	ds_write_b64 v28, v[48:49] offset:0
	ds_write_b32 v30, v50 offset:0
	s_waitcnt lgkmcnt(0)
	s_barrier
	ds_read_b128 v[8:11], v29 offset:0
	ds_read_b128 v[12:15], v29 offset:16
	ds_read_b128 v[16:19], v29 offset:32
	ds_read_b128 v[20:23], v29 offset:48
	ds_read_b32 v24, v31 offset:0
	s_mov_b32 s28, 9
; #define MFMA16(a, b, c) __builtin_amdgcn_mfma_f32_16x16x32_bf16((a), (b), (c), 0, 0, 0)
;     ...
;         for (int n = 0; n < 64; ++n) {
;             const int buf = n & 1;
;             f32x4 a4[4]; bf16x8 vfr[2][2];
; #pragma unroll
;             for (int q = 0; q < 4; ++q) a4[q] = a4n[q];
;             const unsigned kraw = krawn;
; #pragma unroll
;             for (int e = 0; e < 2; ++e)
; #pragma unroll
;                 for (int ks = 0; ks < 2; ++ks) vfr[e][ks] = vfrn[e][ks];
;             if (n + 1 < 64) ldchunk(n + 1);
;             float cum[2];
; #pragma unroll
;             for (int e = 0; e < 2; ++e) {
;                 float z = bb[e];
; #pragma unroll
;                 for (int q = 0; q < 4; ++q) { z += a4[q].x * wa[e][4 * q] + a4[q].y * wa[e][4 * q + 1] + a4[q].z * wa[e][4 * q + 2] + a4[q].w * wa[e][4 * q + 3]; }
;                 cum[e] = (fminf(z, 0.f) - __logf(1.f + __expf(-fabsf(z)))) * (1.f / 16.f);
;             }
; #pragma unroll
;             for (int o = 1; o < 64; o <<= 1) {
;                 const float t0 = __shfl_up(cum[0], o), t1 = __shfl_up(cum[1], o);
;                 if (l >= o) { cum[0] += t0; cum[1] += t1; }
;             }
;             const float tot0 = __shfl(cum[0], 63), tot1 = __shfl(cum[1], 63);
;             kdl[(buf * 16 + 2 * w) * 64 + l] = f2bf(bf2f(kraw & 0xffffu) * __expf(tot0 - cum[0]));
;             kdl[(buf * 16 + 2 * w + 1) * 64 + l] = f2bf(bf2f(kraw >> 16) * __expf(tot1 - cum[1]));
;             if (l == 0) { decl[buf * 16 + 2 * w] = __expf(tot0); decl[buf * 16 + 2 * w + 1] = __expf(tot1); }
;             __syncthreads();
;             const f32x4 d4 = *(const f32x4*)(decl + buf * 16 + (l >> 4) * 4);
; #pragma unroll
;             for (int e = 0; e < 2; ++e) acc[e] = acc[e] * d4;
; #pragma unroll
;             for (int ks = 0; ks < 2; ++ks) {
;                 const bf16x8 af = *(const bf16x8*)(kdl + (buf * 16 + (l & 15)) * 64 + ks * 32 + (l >> 4) * 8);
; #pragma unroll
;                 for (int e = 0; e < 2; ++e) acc[e] = MFMA16(af, vfr[e][ks], acc[e]);
;             }
;             const int cidx = b * 64 + n;
; #pragma unroll
;             for (int e = 0; e < 2; ++e) {
;                 const int vv = (2 * w + e) * 16 + (l & 15);
;                 *(u32x2*)(ST + (((size_t)(cidx * 4 + hh)) * 256 + vv) * 128 + ksl * 16 + (l >> 4) * 4) = pk4(acc[e].x, acc[e].y, acc[e].z, acc[e].w);
;             }
.Lgscan_loop:
	global_load_dwordx2 v[48:49], v230, s[26:27]
	global_load_dword v50, v231, s[58:59]
	s_add_u32 s26, s26, 0x1000
	s_addc_u32 s27, s27, 0
	s_add_u32 s58, s58, 0x10000
	s_addc_u32 s59, s59, 0
	v_xor_b32_e32 v26, s57, v25
	v_add_u32_e32 v59, v26, v232
	v_add_u32_e32 v63, 0x20000, v59
	global_load_dwordx4 v[178:181], v59, s[34:35]
	global_load_dwordx4 v[182:185], v59, s[34:35] offset:64
	global_load_dwordx4 v[186:189], v63, s[34:35]
	global_load_dwordx4 v[190:193], v63, s[34:35] offset:64
	s_add_u32 s57, s57, 0x80
	ds_read_b128 v[154:157], v75 offset:2048
	ds_read_b128 v[240:243], v164 offset:4160
	ds_read_b128 v[236:239], v75 offset:2112
	s_waitcnt lgkmcnt(3)
	v_pk_fma_f32 v[64:65], v[8:9], v[86:87], v[118:119] op_sel:[0,0,0] op_sel_hi:[0,1,1]
	v_pk_mul_f32 v[66:67], v[16:17], v[102:103] op_sel:[0,0] op_sel_hi:[0,1]
	v_pk_fma_f32 v[64:65], v[8:9], v[88:89], v[64:65] op_sel:[1,0,0] op_sel_hi:[1,1,1]
	v_pk_fma_f32 v[66:67], v[16:17], v[104:105], v[66:67] op_sel:[1,0,0] op_sel_hi:[1,1,1]
	v_pk_fma_f32 v[64:65], v[10:11], v[90:91], v[64:65] op_sel:[0,0,0] op_sel_hi:[0,1,1]
	v_pk_fma_f32 v[66:67], v[18:19], v[106:107], v[66:67] op_sel:[0,0,0] op_sel_hi:[0,1,1]
	v_pk_fma_f32 v[64:65], v[10:11], v[92:93], v[64:65] op_sel:[1,0,0] op_sel_hi:[1,1,1]
	v_pk_fma_f32 v[66:67], v[18:19], v[108:109], v[66:67] op_sel:[1,0,0] op_sel_hi:[1,1,1]
	v_pk_fma_f32 v[64:65], v[12:13], v[94:95], v[64:65] op_sel:[0,0,0] op_sel_hi:[0,1,1]
	v_pk_fma_f32 v[66:67], v[20:21], v[110:111], v[66:67] op_sel:[0,0,0] op_sel_hi:[0,1,1]
	v_pk_fma_f32 v[64:65], v[12:13], v[96:97], v[64:65] op_sel:[1,0,0] op_sel_hi:[1,1,1]
	v_pk_fma_f32 v[66:67], v[20:21], v[112:113], v[66:67] op_sel:[1,0,0] op_sel_hi:[1,1,1]
	v_pk_fma_f32 v[64:65], v[14:15], v[98:99], v[64:65] op_sel:[0,0,0] op_sel_hi:[0,1,1]
	v_pk_fma_f32 v[66:67], v[22:23], v[114:115], v[66:67] op_sel:[0,0,0] op_sel_hi:[0,1,1]
	v_pk_fma_f32 v[64:65], v[14:15], v[100:101], v[64:65] op_sel:[1,0,0] op_sel_hi:[1,1,1]
	v_pk_fma_f32 v[66:67], v[22:23], v[116:117], v[66:67] op_sel:[1,0,0] op_sel_hi:[1,1,1]
	v_lshlrev_b32_e32 v148, 16, v24
	v_pk_add_f32 v[64:65], v[64:65], v[66:67]
	v_and_b32_e32 v149, 0xffff0000, v24
	s_waitcnt lgkmcnt(0)
	v_pk_mul_f32 v[0:1], v[0:1], v[240:241]
	v_pk_mul_f32 v[2:3], v[2:3], v[242:243]
	v_pk_mul_f32 v[4:5], v[4:5], v[240:241]
	v_pk_mul_f32 v[6:7], v[6:7], v[242:243]
	s_waitcnt vmcnt(16)
	s_nop 0
	v_mfma_f32_16x16x32_bf16 v[0:3], v[154:157], v[194:197], v[0:3]
	v_mfma_f32_16x16x32_bf16 v[4:7], v[154:157], v[202:205], v[4:7]
	v_mfma_f32_16x16x32_bf16 v[0:3], v[236:239], v[198:201], v[0:3]
	v_mfma_f32_16x16x32_bf16 v[4:7], v[236:239], v[206:209], v[4:7]
	v_mul_f32_e64 v68, |v64|, v220
	v_mul_f32_e64 v69, |v65|, v220
	v_exp_f32_e32 v68, v68
	v_exp_f32_e32 v69, v69
	v_min_f32_e32 v70, 0, v64
	v_min_f32_e32 v71, 0, v65
	v_pk_add_f32 v[68:69], v[68:69], v[222:223]
	s_nop 0
	v_log_f32_e32 v138, v68
	v_log_f32_e32 v139, v69
	s_nop 0
	v_pk_mul_f32 v[140:141], v[138:139], v[224:225]
	s_nop 0
	v_pk_fma_f32 v[142:143], v[138:139], v[224:225], v[140:141] neg_lo:[0,0,1] neg_hi:[0,0,1]
	s_nop 0
	v_pk_fma_f32 v[142:143], v[138:139], v[226:227], v[142:143]
	s_nop 0
	v_pk_fma_f32 v[142:143], v[138:139], v[224:225], v[142:143]
	s_nop 0
	v_pk_add_f32 v[144:145], v[70:71], v[142:143] neg_lo:[0,1] neg_hi:[0,1]
	s_nop 0
	v_pk_mul_f32 v[144:145], v[144:145], v[214:215]
	v_cvt_pk_bf16_f32 v244, v0, v1
	v_cvt_pk_bf16_f32 v245, v2, v3
	v_cvt_pk_bf16_f32 v246, v4, v5
	v_cvt_pk_bf16_f32 v247, v6, v7
	global_store_dwordx2 v234, v[244:245], s[100:101]
	global_store_dwordx2 v235, v[246:247], s[100:101]
	s_add_u32 s100, s100, 0x40000
	s_addc_u32 s101, s101, 0
	v_add_f32_dpp v144, v144, v144 row_shr:1 row_mask:0xf bank_mask:0xf
	v_add_f32_dpp v145, v145, v145 row_shr:1 row_mask:0xf bank_mask:0xf
	s_nop 0
	v_add_f32_dpp v144, v144, v144 row_shr:2 row_mask:0xf bank_mask:0xf
	v_add_f32_dpp v145, v145, v145 row_shr:2 row_mask:0xf bank_mask:0xf
	s_nop 0
	v_add_f32_dpp v144, v144, v144 row_shr:4 row_mask:0xf bank_mask:0xf
	v_add_f32_dpp v145, v145, v145 row_shr:4 row_mask:0xf bank_mask:0xf
	s_nop 0
	v_add_f32_dpp v144, v144, v144 row_shr:8 row_mask:0xf bank_mask:0xf
	v_add_f32_dpp v145, v145, v145 row_shr:8 row_mask:0xf bank_mask:0xf
	s_nop 0
	v_add_f32_dpp v144, v144, v144 row_bcast:15 row_mask:0xa bank_mask:0xf
	v_add_f32_dpp v145, v145, v145 row_bcast:15 row_mask:0xa bank_mask:0xf
	s_nop 0
	v_add_f32_dpp v144, v144, v144 row_bcast:31 row_mask:0xc bank_mask:0xf
	v_add_f32_dpp v145, v145, v145 row_bcast:31 row_mask:0xc bank_mask:0xf
	s_nop 0
	v_readlane_b32 s98, v144, 63
	v_readlane_b32 s99, v145, 63
	s_nop 1
	v_pk_add_f32 v[146:147], s[98:99], v[144:145] neg_lo:[0,1] neg_hi:[0,1]
	v_mul_f32_e64 v152, s98, v228
	v_mul_f32_e64 v153, s99, v228
	v_pk_mul_f32 v[146:147], v[146:147], v[228:229]
	v_exp_f32_e32 v152, v152
	v_exp_f32_e32 v153, v153
	v_exp_f32_e32 v146, v146
	v_exp_f32_e32 v147, v147
	s_nop 0
	v_pk_mul_f32 v[146:147], v[146:147], v[148:149]
	s_nop 0
	v_cvt_pk_bf16_f32 v150, v146, v147
	s_nop 0
	ds_write_b16 v172, v150 offset:0
	ds_write_b16_d16_hi v172, v150 offset:128
	s_and_saveexec_b64 s[20:21], vcc
	ds_write_b64 v163, v[152:153] offset:4096
	s_mov_b64 exec, s[20:21]
	s_waitcnt vmcnt(22)
	ds_write_b64 v28, v[52:53] offset:5120
	ds_write_b32 v30, v54 offset:2080
	s_waitcnt lgkmcnt(0)
	s_barrier
; #define MFMA16(a, b, c) __builtin_amdgcn_mfma_f32_16x16x32_bf16((a), (b), (c), 0, 0, 0)
;     ...
;         for (int n = 0; n < 64; ++n) {
;             const int buf = n & 1;
;             f32x4 a4[4]; bf16x8 vfr[2][2];
; #pragma unroll
;             for (int q = 0; q < 4; ++q) a4[q] = a4n[q];
;             const unsigned kraw = krawn;
; #pragma unroll
;             for (int e = 0; e < 2; ++e)
; #pragma unroll
;                 for (int ks = 0; ks < 2; ++ks) vfr[e][ks] = vfrn[e][ks];
;             if (n + 1 < 64) ldchunk(n + 1);
;             float cum[2];
; #pragma unroll
;             for (int e = 0; e < 2; ++e) {
;                 float z = bb[e];
; #pragma unroll
;                 for (int q = 0; q < 4; ++q) { z += a4[q].x * wa[e][4 * q] + a4[q].y * wa[e][4 * q + 1] + a4[q].z * wa[e][4 * q + 2] + a4[q].w * wa[e][4 * q + 3]; }
;                 cum[e] = (fminf(z, 0.f) - __logf(1.f + __expf(-fabsf(z)))) * (1.f / 16.f);
;             }
; #pragma unroll
;             for (int o = 1; o < 64; o <<= 1) {
;                 const float t0 = __shfl_up(cum[0], o), t1 = __shfl_up(cum[1], o);
;                 if (l >= o) { cum[0] += t0; cum[1] += t1; }
;             }
;             const float tot0 = __shfl(cum[0], 63), tot1 = __shfl(cum[1], 63);
;             kdl[(buf * 16 + 2 * w) * 64 + l] = f2bf(bf2f(kraw & 0xffffu) * __expf(tot0 - cum[0]));
;             kdl[(buf * 16 + 2 * w + 1) * 64 + l] = f2bf(bf2f(kraw >> 16) * __expf(tot1 - cum[1]));
;             if (l == 0) { decl[buf * 16 + 2 * w] = __expf(tot0); decl[buf * 16 + 2 * w + 1] = __expf(tot1); }
;             __syncthreads();
;             const f32x4 d4 = *(const f32x4*)(decl + buf * 16 + (l >> 4) * 4);
; #pragma unroll
;             for (int e = 0; e < 2; ++e) acc[e] = acc[e] * d4;
; #pragma unroll
;             for (int ks = 0; ks < 2; ++ks) {
;                 const bf16x8 af = *(const bf16x8*)(kdl + (buf * 16 + (l & 15)) * 64 + ks * 32 + (l >> 4) * 8);
; #pragma unroll
;                 for (int e = 0; e < 2; ++e) acc[e] = MFMA16(af, vfr[e][ks], acc[e]);
;             }
;             const int cidx = b * 64 + n;
; #pragma unroll
;             for (int e = 0; e < 2; ++e) {
;                 const int vv = (2 * w + e) * 16 + (l & 15);
;                 *(u32x2*)(ST + (((size_t)(cidx * 4 + hh)) * 256 + vv) * 128 + ksl * 16 + (l >> 4) * 4) = pk4(acc[e].x, acc[e].y, acc[e].z, acc[e].w);
;             }
	ds_read_b128 v[8:11], v29 offset:5120
	ds_read_b128 v[12:15], v29 offset:5136
	ds_read_b128 v[16:19], v29 offset:5152
	ds_read_b128 v[20:23], v29 offset:5168
	ds_read_b32 v24, v31 offset:2080
	global_load_dwordx2 v[52:53], v230, s[26:27]
	global_load_dword v54, v231, s[58:59]
	s_add_u32 s26, s26, 0x1000
	s_addc_u32 s27, s27, 0
	s_add_u32 s58, s58, 0x10000
	s_addc_u32 s59, s59, 0
	v_xor_b32_e32 v26, s57, v25
	v_add_u32_e32 v59, v26, v232
	v_add_u32_e32 v63, 0x20000, v59
	global_load_dwordx4 v[194:197], v59, s[34:35]
	global_load_dwordx4 v[198:201], v59, s[34:35] offset:64
	global_load_dwordx4 v[202:205], v63, s[34:35]
	global_load_dwordx4 v[206:209], v63, s[34:35] offset:64
	s_add_u32 s57, s57, 0x80
	ds_read_b128 v[154:157], v75 offset:0
	ds_read_b128 v[240:243], v164 offset:4096
	ds_read_b128 v[236:239], v75 offset:64
	s_waitcnt lgkmcnt(3)
	v_pk_fma_f32 v[64:65], v[8:9], v[86:87], v[118:119] op_sel:[0,0,0] op_sel_hi:[0,1,1]
	v_pk_mul_f32 v[66:67], v[16:17], v[102:103] op_sel:[0,0] op_sel_hi:[0,1]
	v_pk_fma_f32 v[64:65], v[8:9], v[88:89], v[64:65] op_sel:[1,0,0] op_sel_hi:[1,1,1]
	v_pk_fma_f32 v[66:67], v[16:17], v[104:105], v[66:67] op_sel:[1,0,0] op_sel_hi:[1,1,1]
	v_pk_fma_f32 v[64:65], v[10:11], v[90:91], v[64:65] op_sel:[0,0,0] op_sel_hi:[0,1,1]
	v_pk_fma_f32 v[66:67], v[18:19], v[106:107], v[66:67] op_sel:[0,0,0] op_sel_hi:[0,1,1]
	v_pk_fma_f32 v[64:65], v[10:11], v[92:93], v[64:65] op_sel:[1,0,0] op_sel_hi:[1,1,1]
	v_pk_fma_f32 v[66:67], v[18:19], v[108:109], v[66:67] op_sel:[1,0,0] op_sel_hi:[1,1,1]
	v_pk_fma_f32 v[64:65], v[12:13], v[94:95], v[64:65] op_sel:[0,0,0] op_sel_hi:[0,1,1]
	v_pk_fma_f32 v[66:67], v[20:21], v[110:111], v[66:67] op_sel:[0,0,0] op_sel_hi:[0,1,1]
	v_pk_fma_f32 v[64:65], v[12:13], v[96:97], v[64:65] op_sel:[1,0,0] op_sel_hi:[1,1,1]
	v_pk_fma_f32 v[66:67], v[20:21], v[112:113], v[66:67] op_sel:[1,0,0] op_sel_hi:[1,1,1]
	v_pk_fma_f32 v[64:65], v[14:15], v[98:99], v[64:65] op_sel:[0,0,0] op_sel_hi:[0,1,1]
	v_pk_fma_f32 v[66:67], v[22:23], v[114:115], v[66:67] op_sel:[0,0,0] op_sel_hi:[0,1,1]
	v_pk_fma_f32 v[64:65], v[14:15], v[100:101], v[64:65] op_sel:[1,0,0] op_sel_hi:[1,1,1]
	v_pk_fma_f32 v[66:67], v[22:23], v[116:117], v[66:67] op_sel:[1,0,0] op_sel_hi:[1,1,1]
	v_lshlrev_b32_e32 v148, 16, v24
	v_pk_add_f32 v[64:65], v[64:65], v[66:67]
	v_and_b32_e32 v149, 0xffff0000, v24
	s_waitcnt lgkmcnt(0)
	v_pk_mul_f32 v[0:1], v[0:1], v[240:241]
	v_pk_mul_f32 v[2:3], v[2:3], v[242:243]
	v_pk_mul_f32 v[4:5], v[4:5], v[240:241]
	v_pk_mul_f32 v[6:7], v[6:7], v[242:243]
	s_waitcnt vmcnt(16)
	s_nop 0
	v_mfma_f32_16x16x32_bf16 v[0:3], v[154:157], v[32:35], v[0:3]
	v_mfma_f32_16x16x32_bf16 v[4:7], v[154:157], v[40:43], v[4:7]
	v_mfma_f32_16x16x32_bf16 v[0:3], v[236:239], v[36:39], v[0:3]
	v_mfma_f32_16x16x32_bf16 v[4:7], v[236:239], v[44:47], v[4:7]
	v_mul_f32_e64 v68, |v64|, v220
	v_mul_f32_e64 v69, |v65|, v220
	v_exp_f32_e32 v68, v68
	v_exp_f32_e32 v69, v69
	v_min_f32_e32 v70, 0, v64
	v_min_f32_e32 v71, 0, v65
	v_pk_add_f32 v[68:69], v[68:69], v[222:223]
	s_nop 0
	v_log_f32_e32 v138, v68
	v_log_f32_e32 v139, v69
	s_nop 0
	v_pk_mul_f32 v[140:141], v[138:139], v[224:225]
	s_nop 0
	v_pk_fma_f32 v[142:143], v[138:139], v[224:225], v[140:141] neg_lo:[0,0,1] neg_hi:[0,0,1]
	s_nop 0
	v_pk_fma_f32 v[142:143], v[138:139], v[226:227], v[142:143]
	s_nop 0
	v_pk_fma_f32 v[142:143], v[138:139], v[224:225], v[142:143]
	s_nop 0
	v_pk_add_f32 v[144:145], v[70:71], v[142:143] neg_lo:[0,1] neg_hi:[0,1]
	s_nop 0
	v_pk_mul_f32 v[144:145], v[144:145], v[214:215]
	v_cvt_pk_bf16_f32 v244, v0, v1
	v_cvt_pk_bf16_f32 v245, v2, v3
	v_cvt_pk_bf16_f32 v246, v4, v5
	v_cvt_pk_bf16_f32 v247, v6, v7
	global_store_dwordx2 v234, v[244:245], s[100:101]
	global_store_dwordx2 v235, v[246:247], s[100:101]
	s_add_u32 s100, s100, 0x40000
	s_addc_u32 s101, s101, 0
	v_add_f32_dpp v144, v144, v144 row_shr:1 row_mask:0xf bank_mask:0xf
	v_add_f32_dpp v145, v145, v145 row_shr:1 row_mask:0xf bank_mask:0xf
	s_nop 0
	v_add_f32_dpp v144, v144, v144 row_shr:2 row_mask:0xf bank_mask:0xf
	v_add_f32_dpp v145, v145, v145 row_shr:2 row_mask:0xf bank_mask:0xf
	s_nop 0
	v_add_f32_dpp v144, v144, v144 row_shr:4 row_mask:0xf bank_mask:0xf
	v_add_f32_dpp v145, v145, v145 row_shr:4 row_mask:0xf bank_mask:0xf
	s_nop 0
	v_add_f32_dpp v144, v144, v144 row_shr:8 row_mask:0xf bank_mask:0xf
	v_add_f32_dpp v145, v145, v145 row_shr:8 row_mask:0xf bank_mask:0xf
	s_nop 0
	v_add_f32_dpp v144, v144, v144 row_bcast:15 row_mask:0xa bank_mask:0xf
	v_add_f32_dpp v145, v145, v145 row_bcast:15 row_mask:0xa bank_mask:0xf
	s_nop 0
	v_add_f32_dpp v144, v144, v144 row_bcast:31 row_mask:0xc bank_mask:0xf
	v_add_f32_dpp v145, v145, v145 row_bcast:31 row_mask:0xc bank_mask:0xf
	s_nop 0
	v_readlane_b32 s98, v144, 63
	v_readlane_b32 s99, v145, 63
	s_nop 1
	v_pk_add_f32 v[146:147], s[98:99], v[144:145] neg_lo:[0,1] neg_hi:[0,1]
	v_mul_f32_e64 v152, s98, v228
	v_mul_f32_e64 v153, s99, v228
	v_pk_mul_f32 v[146:147], v[146:147], v[228:229]
	v_exp_f32_e32 v152, v152
	v_exp_f32_e32 v153, v153
	v_exp_f32_e32 v146, v146
	v_exp_f32_e32 v147, v147
	s_nop 0
	v_pk_mul_f32 v[146:147], v[146:147], v[148:149]
	s_nop 0
	v_cvt_pk_bf16_f32 v150, v146, v147
	s_nop 0
	ds_write_b16 v172, v150 offset:2048
	ds_write_b16_d16_hi v172, v150 offset:2176
	s_and_saveexec_b64 s[20:21], vcc
	ds_write_b64 v163, v[152:153] offset:4160
	s_mov_b64 exec, s[20:21]
	s_waitcnt vmcnt(22)
	ds_write_b64 v28, v[56:57] offset:0
	ds_write_b32 v30, v58 offset:0
	s_waitcnt lgkmcnt(0)
	s_barrier
; DI bf16_t f2bf(float x) { return (bf16_t)(pk2(x, 0.f) & 0xffffu); }
;     ...
;         for (int n = 0; n < 64; ++n) {
;             const int buf = n & 1;
;             f32x4 a4[4]; bf16x8 vfr[2][2];
; #pragma unroll
;             for (int q = 0; q < 4; ++q) a4[q] = a4n[q];
;             const unsigned kraw = krawn;
; #pragma unroll
;             for (int e = 0; e < 2; ++e)
; #pragma unroll
;                 for (int ks = 0; ks < 2; ++ks) vfr[e][ks] = vfrn[e][ks];
;             if (n + 1 < 64) ldchunk(n + 1);
;             float cum[2];
; #pragma unroll
;             for (int e = 0; e < 2; ++e) {
;                 float z = bb[e];
; #pragma unroll
;                 for (int q = 0; q < 4; ++q) { z += a4[q].x * wa[e][4 * q] + a4[q].y * wa[e][4 * q + 1] + a4[q].z * wa[e][4 * q + 2] + a4[q].w * wa[e][4 * q + 3]; }
;                 cum[e] = (fminf(z, 0.f) - __logf(1.f + __expf(-fabsf(z)))) * (1.f / 16.f);
;             }
; #pragma unroll
;             for (int o = 1; o < 64; o <<= 1) {
;                 const float t0 = __shfl_up(cum[0], o), t1 = __shfl_up(cum[1], o);
;                 if (l >= o) { cum[0] += t0; cum[1] += t1; }
;             }
;             const float tot0 = __shfl(cum[0], 63), tot1 = __shfl(cum[1], 63);
;             kdl[(buf * 16 + 2 * w) * 64 + l] = f2bf(bf2f(kraw & 0xffffu) * __expf(tot0 - cum[0]));
;             kdl[(buf * 16 + 2 * w + 1) * 64 + l] = f2bf(bf2f(kraw >> 16) * __expf(tot1 - cum[1]));
;             if (l == 0) { decl[buf * 16 + 2 * w] = __expf(tot0); decl[buf * 16 + 2 * w + 1] = __expf(tot1); }
;             __syncthreads();
;             const f32x4 d4 = *(const f32x4*)(decl + buf * 16 + (l >> 4) * 4);
; #pragma unroll
;             for (int e = 0; e < 2; ++e) acc[e] = acc[e] * d4;
; #pragma unroll
;             for (int ks = 0; ks < 2; ++ks) {
;                 const bf16x8 af = *(const bf16x8*)(kdl + (buf * 16 + (l & 15)) * 64 + ks * 32 + (l >> 4) * 8);
; #pragma unroll
;                 for (int e = 0; e < 2; ++e) acc[e] = MFMA16(af, vfr[e][ks], acc[e]);
;             }
;             const int cidx = b * 64 + n;
; #pragma unroll
;             for (int e = 0; e < 2; ++e) {
;                 const int vv = (2 * w + e) * 16 + (l & 15);
;                 *(u32x2*)(ST + (((size_t)(cidx * 4 + hh)) * 256 + vv) * 128 + ksl * 16 + (l >> 4) * 4) = pk4(acc[e].x, acc[e].y, acc[e].z, acc[e].w);
;             }
;         }
	ds_read_b128 v[8:11], v29 offset:0
	ds_read_b128 v[12:15], v29 offset:16
	ds_read_b128 v[16:19], v29 offset:32
	ds_read_b128 v[20:23], v29 offset:48
	ds_read_b32 v24, v31 offset:0
	global_load_dwordx2 v[56:57], v230, s[26:27]
	global_load_dword v58, v231, s[58:59]
	s_add_u32 s26, s26, 0x1000
	s_addc_u32 s27, s27, 0
	s_add_u32 s58, s58, 0x10000
	s_addc_u32 s59, s59, 0
	v_xor_b32_e32 v26, s57, v25
	v_add_u32_e32 v59, v26, v232
	v_add_u32_e32 v63, 0x20000, v59
	global_load_dwordx4 v[32:35], v59, s[34:35]
	global_load_dwordx4 v[36:39], v59, s[34:35] offset:64
	global_load_dwordx4 v[40:43], v63, s[34:35]
	global_load_dwordx4 v[44:47], v63, s[34:35] offset:64
	s_add_u32 s57, s57, 0x80
	ds_read_b128 v[154:157], v75 offset:2048
	ds_read_b128 v[240:243], v164 offset:4160
	ds_read_b128 v[236:239], v75 offset:2112
	s_waitcnt lgkmcnt(3)
	v_pk_fma_f32 v[64:65], v[8:9], v[86:87], v[118:119] op_sel:[0,0,0] op_sel_hi:[0,1,1]
	v_pk_mul_f32 v[66:67], v[16:17], v[102:103] op_sel:[0,0] op_sel_hi:[0,1]
	v_pk_fma_f32 v[64:65], v[8:9], v[88:89], v[64:65] op_sel:[1,0,0] op_sel_hi:[1,1,1]
	v_pk_fma_f32 v[66:67], v[16:17], v[104:105], v[66:67] op_sel:[1,0,0] op_sel_hi:[1,1,1]
	v_pk_fma_f32 v[64:65], v[10:11], v[90:91], v[64:65] op_sel:[0,0,0] op_sel_hi:[0,1,1]
	v_pk_fma_f32 v[66:67], v[18:19], v[106:107], v[66:67] op_sel:[0,0,0] op_sel_hi:[0,1,1]
	v_pk_fma_f32 v[64:65], v[10:11], v[92:93], v[64:65] op_sel:[1,0,0] op_sel_hi:[1,1,1]
	v_pk_fma_f32 v[66:67], v[18:19], v[108:109], v[66:67] op_sel:[1,0,0] op_sel_hi:[1,1,1]
	v_pk_fma_f32 v[64:65], v[12:13], v[94:95], v[64:65] op_sel:[0,0,0] op_sel_hi:[0,1,1]
	v_pk_fma_f32 v[66:67], v[20:21], v[110:111], v[66:67] op_sel:[0,0,0] op_sel_hi:[0,1,1]
	v_pk_fma_f32 v[64:65], v[12:13], v[96:97], v[64:65] op_sel:[1,0,0] op_sel_hi:[1,1,1]
	v_pk_fma_f32 v[66:67], v[20:21], v[112:113], v[66:67] op_sel:[1,0,0] op_sel_hi:[1,1,1]
	v_pk_fma_f32 v[64:65], v[14:15], v[98:99], v[64:65] op_sel:[0,0,0] op_sel_hi:[0,1,1]
	v_pk_fma_f32 v[66:67], v[22:23], v[114:115], v[66:67] op_sel:[0,0,0] op_sel_hi:[0,1,1]
	v_pk_fma_f32 v[64:65], v[14:15], v[100:101], v[64:65] op_sel:[1,0,0] op_sel_hi:[1,1,1]
	v_pk_fma_f32 v[66:67], v[22:23], v[116:117], v[66:67] op_sel:[1,0,0] op_sel_hi:[1,1,1]
	v_lshlrev_b32_e32 v148, 16, v24
	v_pk_add_f32 v[64:65], v[64:65], v[66:67]
	v_and_b32_e32 v149, 0xffff0000, v24
	s_waitcnt lgkmcnt(0)
	v_pk_mul_f32 v[0:1], v[0:1], v[240:241]
	v_pk_mul_f32 v[2:3], v[2:3], v[242:243]
	v_pk_mul_f32 v[4:5], v[4:5], v[240:241]
	v_pk_mul_f32 v[6:7], v[6:7], v[242:243]
	s_waitcnt vmcnt(16)
	s_nop 0
	v_mfma_f32_16x16x32_bf16 v[0:3], v[154:157], v[178:181], v[0:3]
	v_mfma_f32_16x16x32_bf16 v[4:7], v[154:157], v[186:189], v[4:7]
	v_mfma_f32_16x16x32_bf16 v[0:3], v[236:239], v[182:185], v[0:3]
	v_mfma_f32_16x16x32_bf16 v[4:7], v[236:239], v[190:193], v[4:7]
	v_mul_f32_e64 v68, |v64|, v220
	v_mul_f32_e64 v69, |v65|, v220
	v_exp_f32_e32 v68, v68
	v_exp_f32_e32 v69, v69
	v_min_f32_e32 v70, 0, v64
	v_min_f32_e32 v71, 0, v65
	v_pk_add_f32 v[68:69], v[68:69], v[222:223]
	s_nop 0
	v_log_f32_e32 v138, v68
	v_log_f32_e32 v139, v69
	s_nop 0
	v_pk_mul_f32 v[140:141], v[138:139], v[224:225]
	s_nop 0
	v_pk_fma_f32 v[142:143], v[138:139], v[224:225], v[140:141] neg_lo:[0,0,1] neg_hi:[0,0,1]
	s_nop 0
	v_pk_fma_f32 v[142:143], v[138:139], v[226:227], v[142:143]
	s_nop 0
	v_pk_fma_f32 v[142:143], v[138:139], v[224:225], v[142:143]
	s_nop 0
	v_pk_add_f32 v[144:145], v[70:71], v[142:143] neg_lo:[0,1] neg_hi:[0,1]
	s_nop 0
	v_pk_mul_f32 v[144:145], v[144:145], v[214:215]
	v_cvt_pk_bf16_f32 v244, v0, v1
	v_cvt_pk_bf16_f32 v245, v2, v3
	v_cvt_pk_bf16_f32 v246, v4, v5
	v_cvt_pk_bf16_f32 v247, v6, v7
	global_store_dwordx2 v234, v[244:245], s[100:101]
	global_store_dwordx2 v235, v[246:247], s[100:101]
	s_add_u32 s100, s100, 0x40000
	s_addc_u32 s101, s101, 0
	v_add_f32_dpp v144, v144, v144 row_shr:1 row_mask:0xf bank_mask:0xf
	v_add_f32_dpp v145, v145, v145 row_shr:1 row_mask:0xf bank_mask:0xf
	s_nop 0
	v_add_f32_dpp v144, v144, v144 row_shr:2 row_mask:0xf bank_mask:0xf
	v_add_f32_dpp v145, v145, v145 row_shr:2 row_mask:0xf bank_mask:0xf
	s_nop 0
	v_add_f32_dpp v144, v144, v144 row_shr:4 row_mask:0xf bank_mask:0xf
	v_add_f32_dpp v145, v145, v145 row_shr:4 row_mask:0xf bank_mask:0xf
	s_nop 0
	v_add_f32_dpp v144, v144, v144 row_shr:8 row_mask:0xf bank_mask:0xf
	v_add_f32_dpp v145, v145, v145 row_shr:8 row_mask:0xf bank_mask:0xf
	s_nop 0
	v_add_f32_dpp v144, v144, v144 row_bcast:15 row_mask:0xa bank_mask:0xf
	v_add_f32_dpp v145, v145, v145 row_bcast:15 row_mask:0xa bank_mask:0xf
	s_nop 0
	v_add_f32_dpp v144, v144, v144 row_bcast:31 row_mask:0xc bank_mask:0xf
	v_add_f32_dpp v145, v145, v145 row_bcast:31 row_mask:0xc bank_mask:0xf
	s_nop 0
	v_readlane_b32 s98, v144, 63
	v_readlane_b32 s99, v145, 63
	s_nop 1
	v_pk_add_f32 v[146:147], s[98:99], v[144:145] neg_lo:[0,1] neg_hi:[0,1]
	v_mul_f32_e64 v152, s98, v228
	v_mul_f32_e64 v153, s99, v228
	v_pk_mul_f32 v[146:147], v[146:147], v[228:229]
	v_exp_f32_e32 v152, v152
	v_exp_f32_e32 v153, v153
	v_exp_f32_e32 v146, v146
	v_exp_f32_e32 v147, v147
	s_nop 0
	v_pk_mul_f32 v[146:147], v[146:147], v[148:149]
	s_nop 0
	v_cvt_pk_bf16_f32 v150, v146, v147
	s_nop 0
	ds_write_b16 v172, v150 offset:0
	ds_write_b16_d16_hi v172, v150 offset:128
	s_and_saveexec_b64 s[20:21], vcc
	ds_write_b64 v163, v[152:153] offset:4096
	s_mov_b64 exec, s[20:21]
	s_waitcnt vmcnt(22)
	ds_write_b64 v28, v[48:49] offset:5120
	ds_write_b32 v30, v50 offset:2080
	s_waitcnt lgkmcnt(0)
	s_barrier
; DI bf16_t f2bf(float x) { return (bf16_t)(pk2(x, 0.f) & 0xffffu); }
;     ...
;         for (int n = 0; n < 64; ++n) {
;             const int buf = n & 1;
;             f32x4 a4[4]; bf16x8 vfr[2][2];
; #pragma unroll
;             for (int q = 0; q < 4; ++q) a4[q] = a4n[q];
;             const unsigned kraw = krawn;
; #pragma unroll
;             for (int e = 0; e < 2; ++e)
; #pragma unroll
;                 for (int ks = 0; ks < 2; ++ks) vfr[e][ks] = vfrn[e][ks];
;             if (n + 1 < 64) ldchunk(n + 1);
;             float cum[2];
; #pragma unroll
;             for (int e = 0; e < 2; ++e) {
;                 float z = bb[e];
; #pragma unroll
;                 for (int q = 0; q < 4; ++q) { z += a4[q].x * wa[e][4 * q] + a4[q].y * wa[e][4 * q + 1] + a4[q].z * wa[e][4 * q + 2] + a4[q].w * wa[e][4 * q + 3]; }
;                 cum[e] = (fminf(z, 0.f) - __logf(1.f + __expf(-fabsf(z)))) * (1.f / 16.f);
;             }
; #pragma unroll
;             for (int o = 1; o < 64; o <<= 1) {
;                 const float t0 = __shfl_up(cum[0], o), t1 = __shfl_up(cum[1], o);
;                 if (l >= o) { cum[0] += t0; cum[1] += t1; }
;             }
;             const float tot0 = __shfl(cum[0], 63), tot1 = __shfl(cum[1], 63);
;             kdl[(buf * 16 + 2 * w) * 64 + l] = f2bf(bf2f(kraw & 0xffffu) * __expf(tot0 - cum[0]));
;             kdl[(buf * 16 + 2 * w + 1) * 64 + l] = f2bf(bf2f(kraw >> 16) * __expf(tot1 - cum[1]));
;             if (l == 0) { decl[buf * 16 + 2 * w] = __expf(tot0); decl[buf * 16 + 2 * w + 1] = __expf(tot1); }
;             __syncthreads();
;             const f32x4 d4 = *(const f32x4*)(decl + buf * 16 + (l >> 4) * 4);
; #pragma unroll
;             for (int e = 0; e < 2; ++e) acc[e] = acc[e] * d4;
; #pragma unroll
;             for (int ks = 0; ks < 2; ++ks) {
;                 const bf16x8 af = *(const bf16x8*)(kdl + (buf * 16 + (l & 15)) * 64 + ks * 32 + (l >> 4) * 8);
; #pragma unroll
;                 for (int e = 0; e < 2; ++e) acc[e] = MFMA16(af, vfr[e][ks], acc[e]);
;             }
;             const int cidx = b * 64 + n;
; #pragma unroll
;             for (int e = 0; e < 2; ++e) {
;                 const int vv = (2 * w + e) * 16 + (l & 15);
;                 *(u32x2*)(ST + (((size_t)(cidx * 4 + hh)) * 256 + vv) * 128 + ksl * 16 + (l >> 4) * 4) = pk4(acc[e].x, acc[e].y, acc[e].z, acc[e].w);
;             }
;         }
	ds_read_b128 v[8:11], v29 offset:5120
	ds_read_b128 v[12:15], v29 offset:5136
	ds_read_b128 v[16:19], v29 offset:5152
	ds_read_b128 v[20:23], v29 offset:5168
	ds_read_b32 v24, v31 offset:2080
	global_load_dwordx2 v[48:49], v230, s[26:27]
	global_load_dword v50, v231, s[58:59]
	s_add_u32 s26, s26, 0x1000
	s_addc_u32 s27, s27, 0
	s_add_u32 s58, s58, 0x10000
	s_addc_u32 s59, s59, 0
	v_xor_b32_e32 v26, s57, v25
	v_add_u32_e32 v59, v26, v232
	v_add_u32_e32 v63, 0x20000, v59
	global_load_dwordx4 v[178:181], v59, s[34:35]
	global_load_dwordx4 v[182:185], v59, s[34:35] offset:64
	global_load_dwordx4 v[186:189], v63, s[34:35]
	global_load_dwordx4 v[190:193], v63, s[34:35] offset:64
	s_add_u32 s57, s57, 0x80
	ds_read_b128 v[154:157], v75 offset:0
	ds_read_b128 v[240:243], v164 offset:4096
	ds_read_b128 v[236:239], v75 offset:64
	s_waitcnt lgkmcnt(3)
	v_pk_fma_f32 v[64:65], v[8:9], v[86:87], v[118:119] op_sel:[0,0,0] op_sel_hi:[0,1,1]
	v_pk_mul_f32 v[66:67], v[16:17], v[102:103] op_sel:[0,0] op_sel_hi:[0,1]
	v_pk_fma_f32 v[64:65], v[8:9], v[88:89], v[64:65] op_sel:[1,0,0] op_sel_hi:[1,1,1]
	v_pk_fma_f32 v[66:67], v[16:17], v[104:105], v[66:67] op_sel:[1,0,0] op_sel_hi:[1,1,1]
	v_pk_fma_f32 v[64:65], v[10:11], v[90:91], v[64:65] op_sel:[0,0,0] op_sel_hi:[0,1,1]
	v_pk_fma_f32 v[66:67], v[18:19], v[106:107], v[66:67] op_sel:[0,0,0] op_sel_hi:[0,1,1]
	v_pk_fma_f32 v[64:65], v[10:11], v[92:93], v[64:65] op_sel:[1,0,0] op_sel_hi:[1,1,1]
	v_pk_fma_f32 v[66:67], v[18:19], v[108:109], v[66:67] op_sel:[1,0,0] op_sel_hi:[1,1,1]
	v_pk_fma_f32 v[64:65], v[12:13], v[94:95], v[64:65] op_sel:[0,0,0] op_sel_hi:[0,1,1]
	v_pk_fma_f32 v[66:67], v[20:21], v[110:111], v[66:67] op_sel:[0,0,0] op_sel_hi:[0,1,1]
	v_pk_fma_f32 v[64:65], v[12:13], v[96:97], v[64:65] op_sel:[1,0,0] op_sel_hi:[1,1,1]
	v_pk_fma_f32 v[66:67], v[20:21], v[112:113], v[66:67] op_sel:[1,0,0] op_sel_hi:[1,1,1]
	v_pk_fma_f32 v[64:65], v[14:15], v[98:99], v[64:65] op_sel:[0,0,0] op_sel_hi:[0,1,1]
	v_pk_fma_f32 v[66:67], v[22:23], v[114:115], v[66:67] op_sel:[0,0,0] op_sel_hi:[0,1,1]
	v_pk_fma_f32 v[64:65], v[14:15], v[100:101], v[64:65] op_sel:[1,0,0] op_sel_hi:[1,1,1]
	v_pk_fma_f32 v[66:67], v[22:23], v[116:117], v[66:67] op_sel:[1,0,0] op_sel_hi:[1,1,1]
	v_lshlrev_b32_e32 v148, 16, v24
	v_pk_add_f32 v[64:65], v[64:65], v[66:67]
	v_and_b32_e32 v149, 0xffff0000, v24
	s_waitcnt lgkmcnt(0)
	v_pk_mul_f32 v[0:1], v[0:1], v[240:241]
	v_pk_mul_f32 v[2:3], v[2:3], v[242:243]
	v_pk_mul_f32 v[4:5], v[4:5], v[240:241]
	v_pk_mul_f32 v[6:7], v[6:7], v[242:243]
	s_waitcnt vmcnt(16)
	s_nop 0
	v_mfma_f32_16x16x32_bf16 v[0:3], v[154:157], v[194:197], v[0:3]
	v_mfma_f32_16x16x32_bf16 v[4:7], v[154:157], v[202:205], v[4:7]
	v_mfma_f32_16x16x32_bf16 v[0:3], v[236:239], v[198:201], v[0:3]
	v_mfma_f32_16x16x32_bf16 v[4:7], v[236:239], v[206:209], v[4:7]
	v_mul_f32_e64 v68, |v64|, v220
	v_mul_f32_e64 v69, |v65|, v220
	v_exp_f32_e32 v68, v68
	v_exp_f32_e32 v69, v69
	v_min_f32_e32 v70, 0, v64
	v_min_f32_e32 v71, 0, v65
	v_pk_add_f32 v[68:69], v[68:69], v[222:223]
	s_nop 0
	v_log_f32_e32 v138, v68
	v_log_f32_e32 v139, v69
	s_nop 0
	v_pk_mul_f32 v[140:141], v[138:139], v[224:225]
	s_nop 0
	v_pk_fma_f32 v[142:143], v[138:139], v[224:225], v[140:141] neg_lo:[0,0,1] neg_hi:[0,0,1]
	s_nop 0
	v_pk_fma_f32 v[142:143], v[138:139], v[226:227], v[142:143]
	s_nop 0
	v_pk_fma_f32 v[142:143], v[138:139], v[224:225], v[142:143]
	s_nop 0
	v_pk_add_f32 v[144:145], v[70:71], v[142:143] neg_lo:[0,1] neg_hi:[0,1]
	s_nop 0
	v_pk_mul_f32 v[144:145], v[144:145], v[214:215]
	v_cvt_pk_bf16_f32 v244, v0, v1
	v_cvt_pk_bf16_f32 v245, v2, v3
	v_cvt_pk_bf16_f32 v246, v4, v5
	v_cvt_pk_bf16_f32 v247, v6, v7
	global_store_dwordx2 v234, v[244:245], s[100:101]
	global_store_dwordx2 v235, v[246:247], s[100:101]
	s_add_u32 s100, s100, 0x40000
	s_addc_u32 s101, s101, 0
	v_add_f32_dpp v144, v144, v144 row_shr:1 row_mask:0xf bank_mask:0xf
	v_add_f32_dpp v145, v145, v145 row_shr:1 row_mask:0xf bank_mask:0xf
	s_nop 0
	v_add_f32_dpp v144, v144, v144 row_shr:2 row_mask:0xf bank_mask:0xf
	v_add_f32_dpp v145, v145, v145 row_shr:2 row_mask:0xf bank_mask:0xf
	s_nop 0
	v_add_f32_dpp v144, v144, v144 row_shr:4 row_mask:0xf bank_mask:0xf
	v_add_f32_dpp v145, v145, v145 row_shr:4 row_mask:0xf bank_mask:0xf
	s_nop 0
	v_add_f32_dpp v144, v144, v144 row_shr:8 row_mask:0xf bank_mask:0xf
	v_add_f32_dpp v145, v145, v145 row_shr:8 row_mask:0xf bank_mask:0xf
	s_nop 0
	v_add_f32_dpp v144, v144, v144 row_bcast:15 row_mask:0xa bank_mask:0xf
	v_add_f32_dpp v145, v145, v145 row_bcast:15 row_mask:0xa bank_mask:0xf
	s_nop 0
	v_add_f32_dpp v144, v144, v144 row_bcast:31 row_mask:0xc bank_mask:0xf
	v_add_f32_dpp v145, v145, v145 row_bcast:31 row_mask:0xc bank_mask:0xf
	s_nop 0
	v_readlane_b32 s98, v144, 63
	v_readlane_b32 s99, v145, 63
	s_nop 1
	v_pk_add_f32 v[146:147], s[98:99], v[144:145] neg_lo:[0,1] neg_hi:[0,1]
	v_mul_f32_e64 v152, s98, v228
	v_mul_f32_e64 v153, s99, v228
	v_pk_mul_f32 v[146:147], v[146:147], v[228:229]
	v_exp_f32_e32 v152, v152
	v_exp_f32_e32 v153, v153
	v_exp_f32_e32 v146, v146
	v_exp_f32_e32 v147, v147
	s_nop 0
	v_pk_mul_f32 v[146:147], v[146:147], v[148:149]
	s_nop 0
	v_cvt_pk_bf16_f32 v150, v146, v147
	s_nop 0
	ds_write_b16 v172, v150 offset:2048
	ds_write_b16_d16_hi v172, v150 offset:2176
	s_and_saveexec_b64 s[20:21], vcc
	ds_write_b64 v163, v[152:153] offset:4160
	s_mov_b64 exec, s[20:21]
	s_waitcnt vmcnt(22)
	ds_write_b64 v28, v[52:53] offset:0
	ds_write_b32 v30, v54 offset:0
	s_waitcnt lgkmcnt(0)
	s_barrier
; DI bf16_t f2bf(float x) { return (bf16_t)(pk2(x, 0.f) & 0xffffu); }
;     ...
;         for (int n = 0; n < 64; ++n) {
;             const int buf = n & 1;
;             f32x4 a4[4]; bf16x8 vfr[2][2];
; #pragma unroll
;             for (int q = 0; q < 4; ++q) a4[q] = a4n[q];
;             const unsigned kraw = krawn;
; #pragma unroll
;             for (int e = 0; e < 2; ++e)
; #pragma unroll
;                 for (int ks = 0; ks < 2; ++ks) vfr[e][ks] = vfrn[e][ks];
;             if (n + 1 < 64) ldchunk(n + 1);
;             float cum[2];
; #pragma unroll
;             for (int e = 0; e < 2; ++e) {
;                 float z = bb[e];
; #pragma unroll
;                 for (int q = 0; q < 4; ++q) { z += a4[q].x * wa[e][4 * q] + a4[q].y * wa[e][4 * q + 1] + a4[q].z * wa[e][4 * q + 2] + a4[q].w * wa[e][4 * q + 3]; }
;                 cum[e] = (fminf(z, 0.f) - __logf(1.f + __expf(-fabsf(z)))) * (1.f / 16.f);
;             }
; #pragma unroll
;             for (int o = 1; o < 64; o <<= 1) {
;                 const float t0 = __shfl_up(cum[0], o), t1 = __shfl_up(cum[1], o);
;                 if (l >= o) { cum[0] += t0; cum[1] += t1; }
;             }
;             const float tot0 = __shfl(cum[0], 63), tot1 = __shfl(cum[1], 63);
;             kdl[(buf * 16 + 2 * w) * 64 + l] = f2bf(bf2f(kraw & 0xffffu) * __expf(tot0 - cum[0]));
;             kdl[(buf * 16 + 2 * w + 1) * 64 + l] = f2bf(bf2f(kraw >> 16) * __expf(tot1 - cum[1]));
;             if (l == 0) { decl[buf * 16 + 2 * w] = __expf(tot0); decl[buf * 16 + 2 * w + 1] = __expf(tot1); }
;             __syncthreads();
;             const f32x4 d4 = *(const f32x4*)(decl + buf * 16 + (l >> 4) * 4);
; #pragma unroll
;             for (int e = 0; e < 2; ++e) acc[e] = acc[e] * d4;
; #pragma unroll
;             for (int ks = 0; ks < 2; ++ks) {
;                 const bf16x8 af = *(const bf16x8*)(kdl + (buf * 16 + (l & 15)) * 64 + ks * 32 + (l >> 4) * 8);
; #pragma unroll
;                 for (int e = 0; e < 2; ++e) acc[e] = MFMA16(af, vfr[e][ks], acc[e]);
;             }
;             const int cidx = b * 64 + n;
; #pragma unroll
;             for (int e = 0; e < 2; ++e) {
;                 const int vv = (2 * w + e) * 16 + (l & 15);
;                 *(u32x2*)(ST + (((size_t)(cidx * 4 + hh)) * 256 + vv) * 128 + ksl * 16 + (l >> 4) * 4) = pk4(acc[e].x, acc[e].y, acc[e].z, acc[e].w);
;             }
;         }
	ds_read_b128 v[8:11], v29 offset:0
	ds_read_b128 v[12:15], v29 offset:16
	ds_read_b128 v[16:19], v29 offset:32
	ds_read_b128 v[20:23], v29 offset:48
	ds_read_b32 v24, v31 offset:0
	global_load_dwordx2 v[52:53], v230, s[26:27]
	global_load_dword v54, v231, s[58:59]
	s_add_u32 s26, s26, 0x1000
	s_addc_u32 s27, s27, 0
	s_add_u32 s58, s58, 0x10000
	s_addc_u32 s59, s59, 0
	v_xor_b32_e32 v26, s57, v25
	v_add_u32_e32 v59, v26, v232
	v_add_u32_e32 v63, 0x20000, v59
	global_load_dwordx4 v[194:197], v59, s[34:35]
	global_load_dwordx4 v[198:201], v59, s[34:35] offset:64
	global_load_dwordx4 v[202:205], v63, s[34:35]
	global_load_dwordx4 v[206:209], v63, s[34:35] offset:64
	s_add_u32 s57, s57, 0x80
	ds_read_b128 v[154:157], v75 offset:2048
	ds_read_b128 v[240:243], v164 offset:4160
	ds_read_b128 v[236:239], v75 offset:2112
	s_waitcnt lgkmcnt(3)
	v_pk_fma_f32 v[64:65], v[8:9], v[86:87], v[118:119] op_sel:[0,0,0] op_sel_hi:[0,1,1]
	v_pk_mul_f32 v[66:67], v[16:17], v[102:103] op_sel:[0,0] op_sel_hi:[0,1]
	v_pk_fma_f32 v[64:65], v[8:9], v[88:89], v[64:65] op_sel:[1,0,0] op_sel_hi:[1,1,1]
	v_pk_fma_f32 v[66:67], v[16:17], v[104:105], v[66:67] op_sel:[1,0,0] op_sel_hi:[1,1,1]
	v_pk_fma_f32 v[64:65], v[10:11], v[90:91], v[64:65] op_sel:[0,0,0] op_sel_hi:[0,1,1]
	v_pk_fma_f32 v[66:67], v[18:19], v[106:107], v[66:67] op_sel:[0,0,0] op_sel_hi:[0,1,1]
	v_pk_fma_f32 v[64:65], v[10:11], v[92:93], v[64:65] op_sel:[1,0,0] op_sel_hi:[1,1,1]
	v_pk_fma_f32 v[66:67], v[18:19], v[108:109], v[66:67] op_sel:[1,0,0] op_sel_hi:[1,1,1]
	v_pk_fma_f32 v[64:65], v[12:13], v[94:95], v[64:65] op_sel:[0,0,0] op_sel_hi:[0,1,1]
	v_pk_fma_f32 v[66:67], v[20:21], v[110:111], v[66:67] op_sel:[0,0,0] op_sel_hi:[0,1,1]
	v_pk_fma_f32 v[64:65], v[12:13], v[96:97], v[64:65] op_sel:[1,0,0] op_sel_hi:[1,1,1]
	v_pk_fma_f32 v[66:67], v[20:21], v[112:113], v[66:67] op_sel:[1,0,0] op_sel_hi:[1,1,1]
	v_pk_fma_f32 v[64:65], v[14:15], v[98:99], v[64:65] op_sel:[0,0,0] op_sel_hi:[0,1,1]
	v_pk_fma_f32 v[66:67], v[22:23], v[114:115], v[66:67] op_sel:[0,0,0] op_sel_hi:[0,1,1]
	v_pk_fma_f32 v[64:65], v[14:15], v[100:101], v[64:65] op_sel:[1,0,0] op_sel_hi:[1,1,1]
	v_pk_fma_f32 v[66:67], v[22:23], v[116:117], v[66:67] op_sel:[1,0,0] op_sel_hi:[1,1,1]
	v_lshlrev_b32_e32 v148, 16, v24
	v_pk_add_f32 v[64:65], v[64:65], v[66:67]
	v_and_b32_e32 v149, 0xffff0000, v24
	s_waitcnt lgkmcnt(0)
	v_pk_mul_f32 v[0:1], v[0:1], v[240:241]
	v_pk_mul_f32 v[2:3], v[2:3], v[242:243]
	v_pk_mul_f32 v[4:5], v[4:5], v[240:241]
	v_pk_mul_f32 v[6:7], v[6:7], v[242:243]
	s_waitcnt vmcnt(16)
	s_nop 0
	v_mfma_f32_16x16x32_bf16 v[0:3], v[154:157], v[32:35], v[0:3]
	v_mfma_f32_16x16x32_bf16 v[4:7], v[154:157], v[40:43], v[4:7]
	v_mfma_f32_16x16x32_bf16 v[0:3], v[236:239], v[36:39], v[0:3]
	v_mfma_f32_16x16x32_bf16 v[4:7], v[236:239], v[44:47], v[4:7]
	v_mul_f32_e64 v68, |v64|, v220
	v_mul_f32_e64 v69, |v65|, v220
	v_exp_f32_e32 v68, v68
	v_exp_f32_e32 v69, v69
	v_min_f32_e32 v70, 0, v64
	v_min_f32_e32 v71, 0, v65
	v_pk_add_f32 v[68:69], v[68:69], v[222:223]
	s_nop 0
	v_log_f32_e32 v138, v68
	v_log_f32_e32 v139, v69
	s_nop 0
	v_pk_mul_f32 v[140:141], v[138:139], v[224:225]
	s_nop 0
	v_pk_fma_f32 v[142:143], v[138:139], v[224:225], v[140:141] neg_lo:[0,0,1] neg_hi:[0,0,1]
	s_nop 0
	v_pk_fma_f32 v[142:143], v[138:139], v[226:227], v[142:143]
	s_nop 0
	v_pk_fma_f32 v[142:143], v[138:139], v[224:225], v[142:143]
	s_nop 0
	v_pk_add_f32 v[144:145], v[70:71], v[142:143] neg_lo:[0,1] neg_hi:[0,1]
	s_nop 0
	v_pk_mul_f32 v[144:145], v[144:145], v[214:215]
	v_cvt_pk_bf16_f32 v244, v0, v1
	v_cvt_pk_bf16_f32 v245, v2, v3
	v_cvt_pk_bf16_f32 v246, v4, v5
	v_cvt_pk_bf16_f32 v247, v6, v7
	global_store_dwordx2 v234, v[244:245], s[100:101]
	global_store_dwordx2 v235, v[246:247], s[100:101]
	s_add_u32 s100, s100, 0x40000
	s_addc_u32 s101, s101, 0
	v_add_f32_dpp v144, v144, v144 row_shr:1 row_mask:0xf bank_mask:0xf
	v_add_f32_dpp v145, v145, v145 row_shr:1 row_mask:0xf bank_mask:0xf
	s_nop 0
	v_add_f32_dpp v144, v144, v144 row_shr:2 row_mask:0xf bank_mask:0xf
	v_add_f32_dpp v145, v145, v145 row_shr:2 row_mask:0xf bank_mask:0xf
	s_nop 0
	v_add_f32_dpp v144, v144, v144 row_shr:4 row_mask:0xf bank_mask:0xf
	v_add_f32_dpp v145, v145, v145 row_shr:4 row_mask:0xf bank_mask:0xf
	s_nop 0
	v_add_f32_dpp v144, v144, v144 row_shr:8 row_mask:0xf bank_mask:0xf
	v_add_f32_dpp v145, v145, v145 row_shr:8 row_mask:0xf bank_mask:0xf
	s_nop 0
	v_add_f32_dpp v144, v144, v144 row_bcast:15 row_mask:0xa bank_mask:0xf
	v_add_f32_dpp v145, v145, v145 row_bcast:15 row_mask:0xa bank_mask:0xf
	s_nop 0
	v_add_f32_dpp v144, v144, v144 row_bcast:31 row_mask:0xc bank_mask:0xf
	v_add_f32_dpp v145, v145, v145 row_bcast:31 row_mask:0xc bank_mask:0xf
	s_nop 0
	v_readlane_b32 s98, v144, 63
	v_readlane_b32 s99, v145, 63
	s_nop 1
	v_pk_add_f32 v[146:147], s[98:99], v[144:145] neg_lo:[0,1] neg_hi:[0,1]
	v_mul_f32_e64 v152, s98, v228
	v_mul_f32_e64 v153, s99, v228
	v_pk_mul_f32 v[146:147], v[146:147], v[228:229]
	v_exp_f32_e32 v152, v152
	v_exp_f32_e32 v153, v153
	v_exp_f32_e32 v146, v146
	v_exp_f32_e32 v147, v147
	s_nop 0
	v_pk_mul_f32 v[146:147], v[146:147], v[148:149]
	s_nop 0
	v_cvt_pk_bf16_f32 v150, v146, v147
	s_nop 0
	ds_write_b16 v172, v150 offset:0
	ds_write_b16_d16_hi v172, v150 offset:128
	s_and_saveexec_b64 s[20:21], vcc
	ds_write_b64 v163, v[152:153] offset:4096
	s_mov_b64 exec, s[20:21]
	s_waitcnt vmcnt(22)
	ds_write_b64 v28, v[56:57] offset:5120
	ds_write_b32 v30, v58 offset:2080
	s_waitcnt lgkmcnt(0)
	s_barrier
; DI bf16_t f2bf(float x) { return (bf16_t)(pk2(x, 0.f) & 0xffffu); }
;     ...
;         for (int n = 0; n < 64; ++n) {
;             const int buf = n & 1;
;             f32x4 a4[4]; bf16x8 vfr[2][2];
; #pragma unroll
;             for (int q = 0; q < 4; ++q) a4[q] = a4n[q];
;             const unsigned kraw = krawn;
; #pragma unroll
;             for (int e = 0; e < 2; ++e)
; #pragma unroll
;                 for (int ks = 0; ks < 2; ++ks) vfr[e][ks] = vfrn[e][ks];
;             if (n + 1 < 64) ldchunk(n + 1);
;             float cum[2];
; #pragma unroll
;             for (int e = 0; e < 2; ++e) {
;                 float z = bb[e];
; #pragma unroll
;                 for (int q = 0; q < 4; ++q) { z += a4[q].x * wa[e][4 * q] + a4[q].y * wa[e][4 * q + 1] + a4[q].z * wa[e][4 * q + 2] + a4[q].w * wa[e][4 * q + 3]; }
;                 cum[e] = (fminf(z, 0.f) - __logf(1.f + __expf(-fabsf(z)))) * (1.f / 16.f);
;             }
; #pragma unroll
;             for (int o = 1; o < 64; o <<= 1) {
;                 const float t0 = __shfl_up(cum[0], o), t1 = __shfl_up(cum[1], o);
;                 if (l >= o) { cum[0] += t0; cum[1] += t1; }
;             }
;             const float tot0 = __shfl(cum[0], 63), tot1 = __shfl(cum[1], 63);
;             kdl[(buf * 16 + 2 * w) * 64 + l] = f2bf(bf2f(kraw & 0xffffu) * __expf(tot0 - cum[0]));
;             kdl[(buf * 16 + 2 * w + 1) * 64 + l] = f2bf(bf2f(kraw >> 16) * __expf(tot1 - cum[1]));
;             if (l == 0) { decl[buf * 16 + 2 * w] = __expf(tot0); decl[buf * 16 + 2 * w + 1] = __expf(tot1); }
;             __syncthreads();
;             const f32x4 d4 = *(const f32x4*)(decl + buf * 16 + (l >> 4) * 4);
; #pragma unroll
;             for (int e = 0; e < 2; ++e) acc[e] = acc[e] * d4;
; #pragma unroll
;             for (int ks = 0; ks < 2; ++ks) {
;                 const bf16x8 af = *(const bf16x8*)(kdl + (buf * 16 + (l & 15)) * 64 + ks * 32 + (l >> 4) * 8);
; #pragma unroll
;                 for (int e = 0; e < 2; ++e) acc[e] = MFMA16(af, vfr[e][ks], acc[e]);
;             }
;             const int cidx = b * 64 + n;
; #pragma unroll
;             for (int e = 0; e < 2; ++e) {
;                 const int vv = (2 * w + e) * 16 + (l & 15);
;                 *(u32x2*)(ST + (((size_t)(cidx * 4 + hh)) * 256 + vv) * 128 + ksl * 16 + (l >> 4) * 4) = pk4(acc[e].x, acc[e].y, acc[e].z, acc[e].w);
;             }
;         }
	ds_read_b128 v[8:11], v29 offset:5120
	ds_read_b128 v[12:15], v29 offset:5136
	ds_read_b128 v[16:19], v29 offset:5152
	ds_read_b128 v[20:23], v29 offset:5168
	ds_read_b32 v24, v31 offset:2080
	global_load_dwordx2 v[56:57], v230, s[26:27]
	global_load_dword v58, v231, s[58:59]
	s_add_u32 s26, s26, 0x1000
	s_addc_u32 s27, s27, 0
	s_add_u32 s58, s58, 0x10000
	s_addc_u32 s59, s59, 0
	v_xor_b32_e32 v26, s57, v25
	v_add_u32_e32 v59, v26, v232
	v_add_u32_e32 v63, 0x20000, v59
	global_load_dwordx4 v[32:35], v59, s[34:35]
	global_load_dwordx4 v[36:39], v59, s[34:35] offset:64
	global_load_dwordx4 v[40:43], v63, s[34:35]
	global_load_dwordx4 v[44:47], v63, s[34:35] offset:64
	s_add_u32 s57, s57, 0x80
	ds_read_b128 v[154:157], v75 offset:0
	ds_read_b128 v[240:243], v164 offset:4096
	ds_read_b128 v[236:239], v75 offset:64
	s_waitcnt lgkmcnt(3)
	v_pk_fma_f32 v[64:65], v[8:9], v[86:87], v[118:119] op_sel:[0,0,0] op_sel_hi:[0,1,1]
	v_pk_mul_f32 v[66:67], v[16:17], v[102:103] op_sel:[0,0] op_sel_hi:[0,1]
	v_pk_fma_f32 v[64:65], v[8:9], v[88:89], v[64:65] op_sel:[1,0,0] op_sel_hi:[1,1,1]
	v_pk_fma_f32 v[66:67], v[16:17], v[104:105], v[66:67] op_sel:[1,0,0] op_sel_hi:[1,1,1]
	v_pk_fma_f32 v[64:65], v[10:11], v[90:91], v[64:65] op_sel:[0,0,0] op_sel_hi:[0,1,1]
	v_pk_fma_f32 v[66:67], v[18:19], v[106:107], v[66:67] op_sel:[0,0,0] op_sel_hi:[0,1,1]
	v_pk_fma_f32 v[64:65], v[10:11], v[92:93], v[64:65] op_sel:[1,0,0] op_sel_hi:[1,1,1]
	v_pk_fma_f32 v[66:67], v[18:19], v[108:109], v[66:67] op_sel:[1,0,0] op_sel_hi:[1,1,1]
	v_pk_fma_f32 v[64:65], v[12:13], v[94:95], v[64:65] op_sel:[0,0,0] op_sel_hi:[0,1,1]
	v_pk_fma_f32 v[66:67], v[20:21], v[110:111], v[66:67] op_sel:[0,0,0] op_sel_hi:[0,1,1]
	v_pk_fma_f32 v[64:65], v[12:13], v[96:97], v[64:65] op_sel:[1,0,0] op_sel_hi:[1,1,1]
	v_pk_fma_f32 v[66:67], v[20:21], v[112:113], v[66:67] op_sel:[1,0,0] op_sel_hi:[1,1,1]
	v_pk_fma_f32 v[64:65], v[14:15], v[98:99], v[64:65] op_sel:[0,0,0] op_sel_hi:[0,1,1]
	v_pk_fma_f32 v[66:67], v[22:23], v[114:115], v[66:67] op_sel:[0,0,0] op_sel_hi:[0,1,1]
	v_pk_fma_f32 v[64:65], v[14:15], v[100:101], v[64:65] op_sel:[1,0,0] op_sel_hi:[1,1,1]
	v_pk_fma_f32 v[66:67], v[22:23], v[116:117], v[66:67] op_sel:[1,0,0] op_sel_hi:[1,1,1]
	v_lshlrev_b32_e32 v148, 16, v24
	v_pk_add_f32 v[64:65], v[64:65], v[66:67]
	v_and_b32_e32 v149, 0xffff0000, v24
	s_waitcnt lgkmcnt(0)
	v_pk_mul_f32 v[0:1], v[0:1], v[240:241]
	v_pk_mul_f32 v[2:3], v[2:3], v[242:243]
	v_pk_mul_f32 v[4:5], v[4:5], v[240:241]
	v_pk_mul_f32 v[6:7], v[6:7], v[242:243]
	s_waitcnt vmcnt(16)
	s_nop 0
	v_mfma_f32_16x16x32_bf16 v[0:3], v[154:157], v[178:181], v[0:3]
	v_mfma_f32_16x16x32_bf16 v[4:7], v[154:157], v[186:189], v[4:7]
	v_mfma_f32_16x16x32_bf16 v[0:3], v[236:239], v[182:185], v[0:3]
	v_mfma_f32_16x16x32_bf16 v[4:7], v[236:239], v[190:193], v[4:7]
	v_mul_f32_e64 v68, |v64|, v220
	v_mul_f32_e64 v69, |v65|, v220
	v_exp_f32_e32 v68, v68
	v_exp_f32_e32 v69, v69
	v_min_f32_e32 v70, 0, v64
	v_min_f32_e32 v71, 0, v65
	v_pk_add_f32 v[68:69], v[68:69], v[222:223]
	s_nop 0
	v_log_f32_e32 v138, v68
	v_log_f32_e32 v139, v69
	s_nop 0
	v_pk_mul_f32 v[140:141], v[138:139], v[224:225]
	s_nop 0
	v_pk_fma_f32 v[142:143], v[138:139], v[224:225], v[140:141] neg_lo:[0,0,1] neg_hi:[0,0,1]
	s_nop 0
	v_pk_fma_f32 v[142:143], v[138:139], v[226:227], v[142:143]
	s_nop 0
	v_pk_fma_f32 v[142:143], v[138:139], v[224:225], v[142:143]
	s_nop 0
	v_pk_add_f32 v[144:145], v[70:71], v[142:143] neg_lo:[0,1] neg_hi:[0,1]
	s_nop 0
	v_pk_mul_f32 v[144:145], v[144:145], v[214:215]
	v_cvt_pk_bf16_f32 v244, v0, v1
	v_cvt_pk_bf16_f32 v245, v2, v3
	v_cvt_pk_bf16_f32 v246, v4, v5
	v_cvt_pk_bf16_f32 v247, v6, v7
	global_store_dwordx2 v234, v[244:245], s[100:101]
	global_store_dwordx2 v235, v[246:247], s[100:101]
	s_add_u32 s100, s100, 0x40000
	s_addc_u32 s101, s101, 0
	v_add_f32_dpp v144, v144, v144 row_shr:1 row_mask:0xf bank_mask:0xf
	v_add_f32_dpp v145, v145, v145 row_shr:1 row_mask:0xf bank_mask:0xf
	s_nop 0
	v_add_f32_dpp v144, v144, v144 row_shr:2 row_mask:0xf bank_mask:0xf
	v_add_f32_dpp v145, v145, v145 row_shr:2 row_mask:0xf bank_mask:0xf
	s_nop 0
	v_add_f32_dpp v144, v144, v144 row_shr:4 row_mask:0xf bank_mask:0xf
	v_add_f32_dpp v145, v145, v145 row_shr:4 row_mask:0xf bank_mask:0xf
	s_nop 0
	v_add_f32_dpp v144, v144, v144 row_shr:8 row_mask:0xf bank_mask:0xf
	v_add_f32_dpp v145, v145, v145 row_shr:8 row_mask:0xf bank_mask:0xf
	s_nop 0
	v_add_f32_dpp v144, v144, v144 row_bcast:15 row_mask:0xa bank_mask:0xf
	v_add_f32_dpp v145, v145, v145 row_bcast:15 row_mask:0xa bank_mask:0xf
	s_nop 0
	v_add_f32_dpp v144, v144, v144 row_bcast:31 row_mask:0xc bank_mask:0xf
	v_add_f32_dpp v145, v145, v145 row_bcast:31 row_mask:0xc bank_mask:0xf
	s_nop 0
	v_readlane_b32 s98, v144, 63
	v_readlane_b32 s99, v145, 63
	s_nop 1
	v_pk_add_f32 v[146:147], s[98:99], v[144:145] neg_lo:[0,1] neg_hi:[0,1]
	v_mul_f32_e64 v152, s98, v228
	v_mul_f32_e64 v153, s99, v228
	v_pk_mul_f32 v[146:147], v[146:147], v[228:229]
	v_exp_f32_e32 v152, v152
	v_exp_f32_e32 v153, v153
	v_exp_f32_e32 v146, v146
	v_exp_f32_e32 v147, v147
	s_nop 0
	v_pk_mul_f32 v[146:147], v[146:147], v[148:149]
	s_nop 0
	v_cvt_pk_bf16_f32 v150, v146, v147
	s_nop 0
	ds_write_b16 v172, v150 offset:2048
	ds_write_b16_d16_hi v172, v150 offset:2176
	s_and_saveexec_b64 s[20:21], vcc
	ds_write_b64 v163, v[152:153] offset:4160
	s_mov_b64 exec, s[20:21]
	s_waitcnt vmcnt(22)
	ds_write_b64 v28, v[48:49] offset:0
	ds_write_b32 v30, v50 offset:0
	s_waitcnt lgkmcnt(0)
	s_barrier
	ds_read_b128 v[8:11], v29 offset:0
	ds_read_b128 v[12:15], v29 offset:16
	ds_read_b128 v[16:19], v29 offset:32
	ds_read_b128 v[20:23], v29 offset:48
	ds_read_b32 v24, v31 offset:0
	s_sub_u32 s28, s28, 1
	s_cmp_lg_u32 s28, 0
	s_cbranch_scc1 .Lgscan_loop
; DI bf16_t f2bf(float x) { return (bf16_t)(pk2(x, 0.f) & 0xffffu); }
;     ...
;         for (int n = 0; n < 64; ++n) {
;             const int buf = n & 1;
;             f32x4 a4[4]; bf16x8 vfr[2][2];
; #pragma unroll
;             for (int q = 0; q < 4; ++q) a4[q] = a4n[q];
;             const unsigned kraw = krawn;
; #pragma unroll
;             for (int e = 0; e < 2; ++e)
; #pragma unroll
;                 for (int ks = 0; ks < 2; ++ks) vfr[e][ks] = vfrn[e][ks];
;             if (n + 1 < 64) ldchunk(n + 1);
;             float cum[2];
; #pragma unroll
;             for (int e = 0; e < 2; ++e) {
;                 float z = bb[e];
; #pragma unroll
;                 for (int q = 0; q < 4; ++q) { z += a4[q].x * wa[e][4 * q] + a4[q].y * wa[e][4 * q + 1] + a4[q].z * wa[e][4 * q + 2] + a4[q].w * wa[e][4 * q + 3]; }
;                 cum[e] = (fminf(z, 0.f) - __logf(1.f + __expf(-fabsf(z)))) * (1.f / 16.f);
;             }
; #pragma unroll
;             for (int o = 1; o < 64; o <<= 1) {
;                 const float t0 = __shfl_up(cum[0], o), t1 = __shfl_up(cum[1], o);
;                 if (l >= o) { cum[0] += t0; cum[1] += t1; }
;             }
;             const float tot0 = __shfl(cum[0], 63), tot1 = __shfl(cum[1], 63);
;             kdl[(buf * 16 + 2 * w) * 64 + l] = f2bf(bf2f(kraw & 0xffffu) * __expf(tot0 - cum[0]));
;             kdl[(buf * 16 + 2 * w + 1) * 64 + l] = f2bf(bf2f(kraw >> 16) * __expf(tot1 - cum[1]));
;             if (l == 0) { decl[buf * 16 + 2 * w] = __expf(tot0); decl[buf * 16 + 2 * w + 1] = __expf(tot1); }
;             __syncthreads();
;             const f32x4 d4 = *(const f32x4*)(decl + buf * 16 + (l >> 4) * 4);
; #pragma unroll
;             for (int e = 0; e < 2; ++e) acc[e] = acc[e] * d4;
; #pragma unroll
;             for (int ks = 0; ks < 2; ++ks) {
;                 const bf16x8 af = *(const bf16x8*)(kdl + (buf * 16 + (l & 15)) * 64 + ks * 32 + (l >> 4) * 8);
; #pragma unroll
;                 for (int e = 0; e < 2; ++e) acc[e] = MFMA16(af, vfr[e][ks], acc[e]);
;             }
;             const int cidx = b * 64 + n;
; #pragma unroll
;             for (int e = 0; e < 2; ++e) {
;                 const int vv = (2 * w + e) * 16 + (l & 15);
;                 *(u32x2*)(ST + (((size_t)(cidx * 4 + hh)) * 256 + vv) * 128 + ksl * 16 + (l >> 4) * 4) = pk4(acc[e].x, acc[e].y, acc[e].z, acc[e].w);
;             }
;         }
	global_load_dwordx2 v[48:49], v230, s[26:27]
	global_load_dword v50, v231, s[58:59]
	s_add_u32 s26, s26, 0x1000
	s_addc_u32 s27, s27, 0
	s_add_u32 s58, s58, 0x10000
	s_addc_u32 s59, s59, 0
	v_xor_b32_e32 v26, s57, v25
	v_add_u32_e32 v59, v26, v232
	v_add_u32_e32 v63, 0x20000, v59
	global_load_dwordx4 v[178:181], v59, s[34:35]
	global_load_dwordx4 v[182:185], v59, s[34:35] offset:64
	global_load_dwordx4 v[186:189], v63, s[34:35]
	global_load_dwordx4 v[190:193], v63, s[34:35] offset:64
	s_add_u32 s57, s57, 0x80
	ds_read_b128 v[154:157], v75 offset:2048
	ds_read_b128 v[240:243], v164 offset:4160
	ds_read_b128 v[236:239], v75 offset:2112
	s_waitcnt lgkmcnt(3)
	v_pk_fma_f32 v[64:65], v[8:9], v[86:87], v[118:119] op_sel:[0,0,0] op_sel_hi:[0,1,1]
	v_pk_mul_f32 v[66:67], v[16:17], v[102:103] op_sel:[0,0] op_sel_hi:[0,1]
	v_pk_fma_f32 v[64:65], v[8:9], v[88:89], v[64:65] op_sel:[1,0,0] op_sel_hi:[1,1,1]
	v_pk_fma_f32 v[66:67], v[16:17], v[104:105], v[66:67] op_sel:[1,0,0] op_sel_hi:[1,1,1]
	v_pk_fma_f32 v[64:65], v[10:11], v[90:91], v[64:65] op_sel:[0,0,0] op_sel_hi:[0,1,1]
	v_pk_fma_f32 v[66:67], v[18:19], v[106:107], v[66:67] op_sel:[0,0,0] op_sel_hi:[0,1,1]
	v_pk_fma_f32 v[64:65], v[10:11], v[92:93], v[64:65] op_sel:[1,0,0] op_sel_hi:[1,1,1]
	v_pk_fma_f32 v[66:67], v[18:19], v[108:109], v[66:67] op_sel:[1,0,0] op_sel_hi:[1,1,1]
	v_pk_fma_f32 v[64:65], v[12:13], v[94:95], v[64:65] op_sel:[0,0,0] op_sel_hi:[0,1,1]
	v_pk_fma_f32 v[66:67], v[20:21], v[110:111], v[66:67] op_sel:[0,0,0] op_sel_hi:[0,1,1]
	v_pk_fma_f32 v[64:65], v[12:13], v[96:97], v[64:65] op_sel:[1,0,0] op_sel_hi:[1,1,1]
	v_pk_fma_f32 v[66:67], v[20:21], v[112:113], v[66:67] op_sel:[1,0,0] op_sel_hi:[1,1,1]
	v_pk_fma_f32 v[64:65], v[14:15], v[98:99], v[64:65] op_sel:[0,0,0] op_sel_hi:[0,1,1]
	v_pk_fma_f32 v[66:67], v[22:23], v[114:115], v[66:67] op_sel:[0,0,0] op_sel_hi:[0,1,1]
	v_pk_fma_f32 v[64:65], v[14:15], v[100:101], v[64:65] op_sel:[1,0,0] op_sel_hi:[1,1,1]
	v_pk_fma_f32 v[66:67], v[22:23], v[116:117], v[66:67] op_sel:[1,0,0] op_sel_hi:[1,1,1]
	v_lshlrev_b32_e32 v148, 16, v24
	v_pk_add_f32 v[64:65], v[64:65], v[66:67]
	v_and_b32_e32 v149, 0xffff0000, v24
	s_waitcnt lgkmcnt(0)
	v_pk_mul_f32 v[0:1], v[0:1], v[240:241]
	v_pk_mul_f32 v[2:3], v[2:3], v[242:243]
	v_pk_mul_f32 v[4:5], v[4:5], v[240:241]
	v_pk_mul_f32 v[6:7], v[6:7], v[242:243]
	s_waitcnt vmcnt(16)
	s_nop 0
	v_mfma_f32_16x16x32_bf16 v[0:3], v[154:157], v[194:197], v[0:3]
	v_mfma_f32_16x16x32_bf16 v[4:7], v[154:157], v[202:205], v[4:7]
	v_mfma_f32_16x16x32_bf16 v[0:3], v[236:239], v[198:201], v[0:3]
	v_mfma_f32_16x16x32_bf16 v[4:7], v[236:239], v[206:209], v[4:7]
	v_mul_f32_e64 v68, |v64|, v220
	v_mul_f32_e64 v69, |v65|, v220
	v_exp_f32_e32 v68, v68
	v_exp_f32_e32 v69, v69
	v_min_f32_e32 v70, 0, v64
	v_min_f32_e32 v71, 0, v65
	v_pk_add_f32 v[68:69], v[68:69], v[222:223]
	s_nop 0
	v_log_f32_e32 v138, v68
	v_log_f32_e32 v139, v69
	s_nop 0
	v_pk_mul_f32 v[140:141], v[138:139], v[224:225]
	s_nop 0
	v_pk_fma_f32 v[142:143], v[138:139], v[224:225], v[140:141] neg_lo:[0,0,1] neg_hi:[0,0,1]
	s_nop 0
	v_pk_fma_f32 v[142:143], v[138:139], v[226:227], v[142:143]
	s_nop 0
	v_pk_fma_f32 v[142:143], v[138:139], v[224:225], v[142:143]
	s_nop 0
	v_pk_add_f32 v[144:145], v[70:71], v[142:143] neg_lo:[0,1] neg_hi:[0,1]
	s_nop 0
	v_pk_mul_f32 v[144:145], v[144:145], v[214:215]
	v_cvt_pk_bf16_f32 v244, v0, v1
	v_cvt_pk_bf16_f32 v245, v2, v3
	v_cvt_pk_bf16_f32 v246, v4, v5
	v_cvt_pk_bf16_f32 v247, v6, v7
	global_store_dwordx2 v234, v[244:245], s[100:101]
	global_store_dwordx2 v235, v[246:247], s[100:101]
	s_add_u32 s100, s100, 0x40000
	s_addc_u32 s101, s101, 0
	v_add_f32_dpp v144, v144, v144 row_shr:1 row_mask:0xf bank_mask:0xf
	v_add_f32_dpp v145, v145, v145 row_shr:1 row_mask:0xf bank_mask:0xf
	s_nop 0
	v_add_f32_dpp v144, v144, v144 row_shr:2 row_mask:0xf bank_mask:0xf
	v_add_f32_dpp v145, v145, v145 row_shr:2 row_mask:0xf bank_mask:0xf
	s_nop 0
	v_add_f32_dpp v144, v144, v144 row_shr:4 row_mask:0xf bank_mask:0xf
	v_add_f32_dpp v145, v145, v145 row_shr:4 row_mask:0xf bank_mask:0xf
	s_nop 0
	v_add_f32_dpp v144, v144, v144 row_shr:8 row_mask:0xf bank_mask:0xf
	v_add_f32_dpp v145, v145, v145 row_shr:8 row_mask:0xf bank_mask:0xf
	s_nop 0
	v_add_f32_dpp v144, v144, v144 row_bcast:15 row_mask:0xa bank_mask:0xf
	v_add_f32_dpp v145, v145, v145 row_bcast:15 row_mask:0xa bank_mask:0xf
	s_nop 0
	v_add_f32_dpp v144, v144, v144 row_bcast:31 row_mask:0xc bank_mask:0xf
	v_add_f32_dpp v145, v145, v145 row_bcast:31 row_mask:0xc bank_mask:0xf
	s_nop 0
	v_readlane_b32 s98, v144, 63
	v_readlane_b32 s99, v145, 63
	s_nop 1
	v_pk_add_f32 v[146:147], s[98:99], v[144:145] neg_lo:[0,1] neg_hi:[0,1]
	v_mul_f32_e64 v152, s98, v228
	v_mul_f32_e64 v153, s99, v228
	v_pk_mul_f32 v[146:147], v[146:147], v[228:229]
	v_exp_f32_e32 v152, v152
	v_exp_f32_e32 v153, v153
	v_exp_f32_e32 v146, v146
	v_exp_f32_e32 v147, v147
	s_nop 0
	v_pk_mul_f32 v[146:147], v[146:147], v[148:149]
	s_nop 0
	v_cvt_pk_bf16_f32 v150, v146, v147
	s_nop 0
	ds_write_b16 v172, v150 offset:0
	ds_write_b16_d16_hi v172, v150 offset:128
	s_and_saveexec_b64 s[20:21], vcc
	ds_write_b64 v163, v[152:153] offset:4096
	s_mov_b64 exec, s[20:21]
	s_waitcnt vmcnt(22)
	ds_write_b64 v28, v[52:53] offset:5120
	ds_write_b32 v30, v54 offset:2080
	s_waitcnt lgkmcnt(0)
	s_barrier
; DI bf16_t f2bf(float x) { return (bf16_t)(pk2(x, 0.f) & 0xffffu); }
;     ...
;         for (int n = 0; n < 64; ++n) {
;             const int buf = n & 1;
;             f32x4 a4[4]; bf16x8 vfr[2][2];
; #pragma unroll
;             for (int q = 0; q < 4; ++q) a4[q] = a4n[q];
;             const unsigned kraw = krawn;
; #pragma unroll
;             for (int e = 0; e < 2; ++e)
; #pragma unroll
;                 for (int ks = 0; ks < 2; ++ks) vfr[e][ks] = vfrn[e][ks];
;             if (n + 1 < 64) ldchunk(n + 1);
;             float cum[2];
; #pragma unroll
;             for (int e = 0; e < 2; ++e) {
;                 float z = bb[e];
; #pragma unroll
;                 for (int q = 0; q < 4; ++q) { z += a4[q].x * wa[e][4 * q] + a4[q].y * wa[e][4 * q + 1] + a4[q].z * wa[e][4 * q + 2] + a4[q].w * wa[e][4 * q + 3]; }
;                 cum[e] = (fminf(z, 0.f) - __logf(1.f + __expf(-fabsf(z)))) * (1.f / 16.f);
;             }
; #pragma unroll
;             for (int o = 1; o < 64; o <<= 1) {
;                 const float t0 = __shfl_up(cum[0], o), t1 = __shfl_up(cum[1], o);
;                 if (l >= o) { cum[0] += t0; cum[1] += t1; }
;             }
;             const float tot0 = __shfl(cum[0], 63), tot1 = __shfl(cum[1], 63);
;             kdl[(buf * 16 + 2 * w) * 64 + l] = f2bf(bf2f(kraw & 0xffffu) * __expf(tot0 - cum[0]));
;             kdl[(buf * 16 + 2 * w + 1) * 64 + l] = f2bf(bf2f(kraw >> 16) * __expf(tot1 - cum[1]));
;             if (l == 0) { decl[buf * 16 + 2 * w] = __expf(tot0); decl[buf * 16 + 2 * w + 1] = __expf(tot1); }
;             __syncthreads();
;             const f32x4 d4 = *(const f32x4*)(decl + buf * 16 + (l >> 4) * 4);
; #pragma unroll
;             for (int e = 0; e < 2; ++e) acc[e] = acc[e] * d4;
; #pragma unroll
;             for (int ks = 0; ks < 2; ++ks) {
;                 const bf16x8 af = *(const bf16x8*)(kdl + (buf * 16 + (l & 15)) * 64 + ks * 32 + (l >> 4) * 8);
; #pragma unroll
;                 for (int e = 0; e < 2; ++e) acc[e] = MFMA16(af, vfr[e][ks], acc[e]);
;             }
;             const int cidx = b * 64 + n;
; #pragma unroll
;             for (int e = 0; e < 2; ++e) {
;                 const int vv = (2 * w + e) * 16 + (l & 15);
;                 *(u32x2*)(ST + (((size_t)(cidx * 4 + hh)) * 256 + vv) * 128 + ksl * 16 + (l >> 4) * 4) = pk4(acc[e].x, acc[e].y, acc[e].z, acc[e].w);
;             }
;         }
	ds_read_b128 v[8:11], v29 offset:5120
	ds_read_b128 v[12:15], v29 offset:5136
	ds_read_b128 v[16:19], v29 offset:5152
	ds_read_b128 v[20:23], v29 offset:5168
	ds_read_b32 v24, v31 offset:2080
	v_xor_b32_e32 v26, s57, v25
	v_add_u32_e32 v59, v26, v232
	v_add_u32_e32 v63, 0x20000, v59
	global_load_dwordx4 v[194:197], v59, s[34:35]
	global_load_dwordx4 v[198:201], v59, s[34:35] offset:64
	global_load_dwordx4 v[202:205], v63, s[34:35]
	global_load_dwordx4 v[206:209], v63, s[34:35] offset:64
	s_add_u32 s57, s57, 0x80
	ds_read_b128 v[154:157], v75 offset:0
	ds_read_b128 v[240:243], v164 offset:4096
	ds_read_b128 v[236:239], v75 offset:64
	s_waitcnt lgkmcnt(3)
	v_pk_fma_f32 v[64:65], v[8:9], v[86:87], v[118:119] op_sel:[0,0,0] op_sel_hi:[0,1,1]
	v_pk_mul_f32 v[66:67], v[16:17], v[102:103] op_sel:[0,0] op_sel_hi:[0,1]
	v_pk_fma_f32 v[64:65], v[8:9], v[88:89], v[64:65] op_sel:[1,0,0] op_sel_hi:[1,1,1]
	v_pk_fma_f32 v[66:67], v[16:17], v[104:105], v[66:67] op_sel:[1,0,0] op_sel_hi:[1,1,1]
	v_pk_fma_f32 v[64:65], v[10:11], v[90:91], v[64:65] op_sel:[0,0,0] op_sel_hi:[0,1,1]
	v_pk_fma_f32 v[66:67], v[18:19], v[106:107], v[66:67] op_sel:[0,0,0] op_sel_hi:[0,1,1]
	v_pk_fma_f32 v[64:65], v[10:11], v[92:93], v[64:65] op_sel:[1,0,0] op_sel_hi:[1,1,1]
	v_pk_fma_f32 v[66:67], v[18:19], v[108:109], v[66:67] op_sel:[1,0,0] op_sel_hi:[1,1,1]
	v_pk_fma_f32 v[64:65], v[12:13], v[94:95], v[64:65] op_sel:[0,0,0] op_sel_hi:[0,1,1]
	v_pk_fma_f32 v[66:67], v[20:21], v[110:111], v[66:67] op_sel:[0,0,0] op_sel_hi:[0,1,1]
	v_pk_fma_f32 v[64:65], v[12:13], v[96:97], v[64:65] op_sel:[1,0,0] op_sel_hi:[1,1,1]
	v_pk_fma_f32 v[66:67], v[20:21], v[112:113], v[66:67] op_sel:[1,0,0] op_sel_hi:[1,1,1]
	v_pk_fma_f32 v[64:65], v[14:15], v[98:99], v[64:65] op_sel:[0,0,0] op_sel_hi:[0,1,1]
	v_pk_fma_f32 v[66:67], v[22:23], v[114:115], v[66:67] op_sel:[0,0,0] op_sel_hi:[0,1,1]
	v_pk_fma_f32 v[64:65], v[14:15], v[100:101], v[64:65] op_sel:[1,0,0] op_sel_hi:[1,1,1]
	v_pk_fma_f32 v[66:67], v[22:23], v[116:117], v[66:67] op_sel:[1,0,0] op_sel_hi:[1,1,1]
	v_lshlrev_b32_e32 v148, 16, v24
	v_pk_add_f32 v[64:65], v[64:65], v[66:67]
	v_and_b32_e32 v149, 0xffff0000, v24
	s_waitcnt lgkmcnt(0)
	v_pk_mul_f32 v[0:1], v[0:1], v[240:241]
	v_pk_mul_f32 v[2:3], v[2:3], v[242:243]
	v_pk_mul_f32 v[4:5], v[4:5], v[240:241]
	v_pk_mul_f32 v[6:7], v[6:7], v[242:243]
	s_waitcnt vmcnt(14)
	s_nop 0
	v_mfma_f32_16x16x32_bf16 v[0:3], v[154:157], v[32:35], v[0:3]
	v_mfma_f32_16x16x32_bf16 v[4:7], v[154:157], v[40:43], v[4:7]
	v_mfma_f32_16x16x32_bf16 v[0:3], v[236:239], v[36:39], v[0:3]
	v_mfma_f32_16x16x32_bf16 v[4:7], v[236:239], v[44:47], v[4:7]
	v_mul_f32_e64 v68, |v64|, v220
	v_mul_f32_e64 v69, |v65|, v220
	v_exp_f32_e32 v68, v68
	v_exp_f32_e32 v69, v69
	v_min_f32_e32 v70, 0, v64
	v_min_f32_e32 v71, 0, v65
	v_pk_add_f32 v[68:69], v[68:69], v[222:223]
	s_nop 0
	v_log_f32_e32 v138, v68
	v_log_f32_e32 v139, v69
	s_nop 0
	v_pk_mul_f32 v[140:141], v[138:139], v[224:225]
	s_nop 0
	v_pk_fma_f32 v[142:143], v[138:139], v[224:225], v[140:141] neg_lo:[0,0,1] neg_hi:[0,0,1]
	s_nop 0
	v_pk_fma_f32 v[142:143], v[138:139], v[226:227], v[142:143]
	s_nop 0
	v_pk_fma_f32 v[142:143], v[138:139], v[224:225], v[142:143]
	s_nop 0
	v_pk_add_f32 v[144:145], v[70:71], v[142:143] neg_lo:[0,1] neg_hi:[0,1]
	s_nop 0
	v_pk_mul_f32 v[144:145], v[144:145], v[214:215]
	v_cvt_pk_bf16_f32 v244, v0, v1
	v_cvt_pk_bf16_f32 v245, v2, v3
	v_cvt_pk_bf16_f32 v246, v4, v5
	v_cvt_pk_bf16_f32 v247, v6, v7
	global_store_dwordx2 v234, v[244:245], s[100:101]
	global_store_dwordx2 v235, v[246:247], s[100:101]
	s_add_u32 s100, s100, 0x40000
	s_addc_u32 s101, s101, 0
	v_add_f32_dpp v144, v144, v144 row_shr:1 row_mask:0xf bank_mask:0xf
	v_add_f32_dpp v145, v145, v145 row_shr:1 row_mask:0xf bank_mask:0xf
	s_nop 0
	v_add_f32_dpp v144, v144, v144 row_shr:2 row_mask:0xf bank_mask:0xf
	v_add_f32_dpp v145, v145, v145 row_shr:2 row_mask:0xf bank_mask:0xf
	s_nop 0
	v_add_f32_dpp v144, v144, v144 row_shr:4 row_mask:0xf bank_mask:0xf
	v_add_f32_dpp v145, v145, v145 row_shr:4 row_mask:0xf bank_mask:0xf
	s_nop 0
	v_add_f32_dpp v144, v144, v144 row_shr:8 row_mask:0xf bank_mask:0xf
	v_add_f32_dpp v145, v145, v145 row_shr:8 row_mask:0xf bank_mask:0xf
	s_nop 0
	v_add_f32_dpp v144, v144, v144 row_bcast:15 row_mask:0xa bank_mask:0xf
	v_add_f32_dpp v145, v145, v145 row_bcast:15 row_mask:0xa bank_mask:0xf
	s_nop 0
	v_add_f32_dpp v144, v144, v144 row_bcast:31 row_mask:0xc bank_mask:0xf
	v_add_f32_dpp v145, v145, v145 row_bcast:31 row_mask:0xc bank_mask:0xf
	s_nop 0
	v_readlane_b32 s98, v144, 63
	v_readlane_b32 s99, v145, 63
	s_nop 1
	v_pk_add_f32 v[146:147], s[98:99], v[144:145] neg_lo:[0,1] neg_hi:[0,1]
	v_mul_f32_e64 v152, s98, v228
	v_mul_f32_e64 v153, s99, v228
	v_pk_mul_f32 v[146:147], v[146:147], v[228:229]
	v_exp_f32_e32 v152, v152
	v_exp_f32_e32 v153, v153
	v_exp_f32_e32 v146, v146
	v_exp_f32_e32 v147, v147
	s_nop 0
	v_pk_mul_f32 v[146:147], v[146:147], v[148:149]
	s_nop 0
	v_cvt_pk_bf16_f32 v150, v146, v147
	s_nop 0
	ds_write_b16 v172, v150 offset:2048
	ds_write_b16_d16_hi v172, v150 offset:2176
	s_and_saveexec_b64 s[20:21], vcc
	ds_write_b64 v163, v[152:153] offset:4160
	s_mov_b64 exec, s[20:21]
	s_waitcnt vmcnt(20)
	ds_write_b64 v28, v[56:57] offset:0
	ds_write_b32 v30, v58 offset:0
	s_waitcnt lgkmcnt(0)
	s_barrier
; DI bf16_t f2bf(float x) { return (bf16_t)(pk2(x, 0.f) & 0xffffu); }
;     ...
;         for (int n = 0; n < 64; ++n) {
;             const int buf = n & 1;
;             f32x4 a4[4]; bf16x8 vfr[2][2];
; #pragma unroll
;             for (int q = 0; q < 4; ++q) a4[q] = a4n[q];
;             const unsigned kraw = krawn;
; #pragma unroll
;             for (int e = 0; e < 2; ++e)
; #pragma unroll
;                 for (int ks = 0; ks < 2; ++ks) vfr[e][ks] = vfrn[e][ks];
;             if (n + 1 < 64) ldchunk(n + 1);
;             float cum[2];
; #pragma unroll
;             for (int e = 0; e < 2; ++e) {
;                 float z = bb[e];
; #pragma unroll
;                 for (int q = 0; q < 4; ++q) { z += a4[q].x * wa[e][4 * q] + a4[q].y * wa[e][4 * q + 1] + a4[q].z * wa[e][4 * q + 2] + a4[q].w * wa[e][4 * q + 3]; }
;                 cum[e] = (fminf(z, 0.f) - __logf(1.f + __expf(-fabsf(z)))) * (1.f / 16.f);
;             }
; #pragma unroll
;             for (int o = 1; o < 64; o <<= 1) {
;                 const float t0 = __shfl_up(cum[0], o), t1 = __shfl_up(cum[1], o);
;                 if (l >= o) { cum[0] += t0; cum[1] += t1; }
;             }
;             const float tot0 = __shfl(cum[0], 63), tot1 = __shfl(cum[1], 63);
;             kdl[(buf * 16 + 2 * w) * 64 + l] = f2bf(bf2f(kraw & 0xffffu) * __expf(tot0 - cum[0]));
;             kdl[(buf * 16 + 2 * w + 1) * 64 + l] = f2bf(bf2f(kraw >> 16) * __expf(tot1 - cum[1]));
;             if (l == 0) { decl[buf * 16 + 2 * w] = __expf(tot0); decl[buf * 16 + 2 * w + 1] = __expf(tot1); }
;             __syncthreads();
;             const f32x4 d4 = *(const f32x4*)(decl + buf * 16 + (l >> 4) * 4);
; #pragma unroll
;             for (int e = 0; e < 2; ++e) acc[e] = acc[e] * d4;
; #pragma unroll
;             for (int ks = 0; ks < 2; ++ks) {
;                 const bf16x8 af = *(const bf16x8*)(kdl + (buf * 16 + (l & 15)) * 64 + ks * 32 + (l >> 4) * 8);
; #pragma unroll
;                 for (int e = 0; e < 2; ++e) acc[e] = MFMA16(af, vfr[e][ks], acc[e]);
;             }
;             const int cidx = b * 64 + n;
; #pragma unroll
;             for (int e = 0; e < 2; ++e) {
;                 const int vv = (2 * w + e) * 16 + (l & 15);
;                 *(u32x2*)(ST + (((size_t)(cidx * 4 + hh)) * 256 + vv) * 128 + ksl * 16 + (l >> 4) * 4) = pk4(acc[e].x, acc[e].y, acc[e].z, acc[e].w);
;             }
;         }
	ds_read_b128 v[8:11], v29 offset:0
	ds_read_b128 v[12:15], v29 offset:16
	ds_read_b128 v[16:19], v29 offset:32
	ds_read_b128 v[20:23], v29 offset:48
	ds_read_b32 v24, v31 offset:0
	v_xor_b32_e32 v26, s57, v25
	v_add_u32_e32 v59, v26, v232
	v_add_u32_e32 v63, 0x20000, v59
	global_load_dwordx4 v[32:35], v59, s[34:35]
	global_load_dwordx4 v[36:39], v59, s[34:35] offset:64
	global_load_dwordx4 v[40:43], v63, s[34:35]
	global_load_dwordx4 v[44:47], v63, s[34:35] offset:64
	s_add_u32 s57, s57, 0x80
	ds_read_b128 v[154:157], v75 offset:2048
	ds_read_b128 v[240:243], v164 offset:4160
	ds_read_b128 v[236:239], v75 offset:2112
	s_waitcnt lgkmcnt(3)
	v_pk_fma_f32 v[64:65], v[8:9], v[86:87], v[118:119] op_sel:[0,0,0] op_sel_hi:[0,1,1]
	v_pk_mul_f32 v[66:67], v[16:17], v[102:103] op_sel:[0,0] op_sel_hi:[0,1]
	v_pk_fma_f32 v[64:65], v[8:9], v[88:89], v[64:65] op_sel:[1,0,0] op_sel_hi:[1,1,1]
	v_pk_fma_f32 v[66:67], v[16:17], v[104:105], v[66:67] op_sel:[1,0,0] op_sel_hi:[1,1,1]
	v_pk_fma_f32 v[64:65], v[10:11], v[90:91], v[64:65] op_sel:[0,0,0] op_sel_hi:[0,1,1]
	v_pk_fma_f32 v[66:67], v[18:19], v[106:107], v[66:67] op_sel:[0,0,0] op_sel_hi:[0,1,1]
	v_pk_fma_f32 v[64:65], v[10:11], v[92:93], v[64:65] op_sel:[1,0,0] op_sel_hi:[1,1,1]
	v_pk_fma_f32 v[66:67], v[18:19], v[108:109], v[66:67] op_sel:[1,0,0] op_sel_hi:[1,1,1]
	v_pk_fma_f32 v[64:65], v[12:13], v[94:95], v[64:65] op_sel:[0,0,0] op_sel_hi:[0,1,1]
	v_pk_fma_f32 v[66:67], v[20:21], v[110:111], v[66:67] op_sel:[0,0,0] op_sel_hi:[0,1,1]
	v_pk_fma_f32 v[64:65], v[12:13], v[96:97], v[64:65] op_sel:[1,0,0] op_sel_hi:[1,1,1]
	v_pk_fma_f32 v[66:67], v[20:21], v[112:113], v[66:67] op_sel:[1,0,0] op_sel_hi:[1,1,1]
	v_pk_fma_f32 v[64:65], v[14:15], v[98:99], v[64:65] op_sel:[0,0,0] op_sel_hi:[0,1,1]
	v_pk_fma_f32 v[66:67], v[22:23], v[114:115], v[66:67] op_sel:[0,0,0] op_sel_hi:[0,1,1]
	v_pk_fma_f32 v[64:65], v[14:15], v[100:101], v[64:65] op_sel:[1,0,0] op_sel_hi:[1,1,1]
	v_pk_fma_f32 v[66:67], v[22:23], v[116:117], v[66:67] op_sel:[1,0,0] op_sel_hi:[1,1,1]
	v_lshlrev_b32_e32 v148, 16, v24
	v_pk_add_f32 v[64:65], v[64:65], v[66:67]
	v_and_b32_e32 v149, 0xffff0000, v24
	s_waitcnt lgkmcnt(0)
	v_pk_mul_f32 v[0:1], v[0:1], v[240:241]
	v_pk_mul_f32 v[2:3], v[2:3], v[242:243]
	v_pk_mul_f32 v[4:5], v[4:5], v[240:241]
	v_pk_mul_f32 v[6:7], v[6:7], v[242:243]
	s_waitcnt vmcnt(12)
	s_nop 0
	v_mfma_f32_16x16x32_bf16 v[0:3], v[154:157], v[178:181], v[0:3]
	v_mfma_f32_16x16x32_bf16 v[4:7], v[154:157], v[186:189], v[4:7]
	v_mfma_f32_16x16x32_bf16 v[0:3], v[236:239], v[182:185], v[0:3]
	v_mfma_f32_16x16x32_bf16 v[4:7], v[236:239], v[190:193], v[4:7]
	v_mul_f32_e64 v68, |v64|, v220
	v_mul_f32_e64 v69, |v65|, v220
	v_exp_f32_e32 v68, v68
	v_exp_f32_e32 v69, v69
	v_min_f32_e32 v70, 0, v64
	v_min_f32_e32 v71, 0, v65
	v_pk_add_f32 v[68:69], v[68:69], v[222:223]
	s_nop 0
	v_log_f32_e32 v138, v68
	v_log_f32_e32 v139, v69
	s_nop 0
	v_pk_mul_f32 v[140:141], v[138:139], v[224:225]
	s_nop 0
	v_pk_fma_f32 v[142:143], v[138:139], v[224:225], v[140:141] neg_lo:[0,0,1] neg_hi:[0,0,1]
	s_nop 0
	v_pk_fma_f32 v[142:143], v[138:139], v[226:227], v[142:143]
	s_nop 0
	v_pk_fma_f32 v[142:143], v[138:139], v[224:225], v[142:143]
	s_nop 0
	v_pk_add_f32 v[144:145], v[70:71], v[142:143] neg_lo:[0,1] neg_hi:[0,1]
	s_nop 0
	v_pk_mul_f32 v[144:145], v[144:145], v[214:215]
	v_cvt_pk_bf16_f32 v244, v0, v1
	v_cvt_pk_bf16_f32 v245, v2, v3
	v_cvt_pk_bf16_f32 v246, v4, v5
	v_cvt_pk_bf16_f32 v247, v6, v7
	global_store_dwordx2 v234, v[244:245], s[100:101]
	global_store_dwordx2 v235, v[246:247], s[100:101]
	s_add_u32 s100, s100, 0x40000
	s_addc_u32 s101, s101, 0
	v_add_f32_dpp v144, v144, v144 row_shr:1 row_mask:0xf bank_mask:0xf
	v_add_f32_dpp v145, v145, v145 row_shr:1 row_mask:0xf bank_mask:0xf
	s_nop 0
	v_add_f32_dpp v144, v144, v144 row_shr:2 row_mask:0xf bank_mask:0xf
	v_add_f32_dpp v145, v145, v145 row_shr:2 row_mask:0xf bank_mask:0xf
	s_nop 0
	v_add_f32_dpp v144, v144, v144 row_shr:4 row_mask:0xf bank_mask:0xf
	v_add_f32_dpp v145, v145, v145 row_shr:4 row_mask:0xf bank_mask:0xf
	s_nop 0
	v_add_f32_dpp v144, v144, v144 row_shr:8 row_mask:0xf bank_mask:0xf
	v_add_f32_dpp v145, v145, v145 row_shr:8 row_mask:0xf bank_mask:0xf
	s_nop 0
	v_add_f32_dpp v144, v144, v144 row_bcast:15 row_mask:0xa bank_mask:0xf
	v_add_f32_dpp v145, v145, v145 row_bcast:15 row_mask:0xa bank_mask:0xf
	s_nop 0
	v_add_f32_dpp v144, v144, v144 row_bcast:31 row_mask:0xc bank_mask:0xf
	v_add_f32_dpp v145, v145, v145 row_bcast:31 row_mask:0xc bank_mask:0xf
	s_nop 0
	v_readlane_b32 s98, v144, 63
	v_readlane_b32 s99, v145, 63
	s_nop 1
	v_pk_add_f32 v[146:147], s[98:99], v[144:145] neg_lo:[0,1] neg_hi:[0,1]
	v_mul_f32_e64 v152, s98, v228
	v_mul_f32_e64 v153, s99, v228
	v_pk_mul_f32 v[146:147], v[146:147], v[228:229]
	v_exp_f32_e32 v152, v152
	v_exp_f32_e32 v153, v153
	v_exp_f32_e32 v146, v146
	v_exp_f32_e32 v147, v147
	s_nop 0
	v_pk_mul_f32 v[146:147], v[146:147], v[148:149]
	s_nop 0
	v_cvt_pk_bf16_f32 v150, v146, v147
	s_nop 0
	ds_write_b16 v172, v150 offset:0
	ds_write_b16_d16_hi v172, v150 offset:128
	s_and_saveexec_b64 s[20:21], vcc
	ds_write_b64 v163, v[152:153] offset:4096
	s_mov_b64 exec, s[20:21]
	s_waitcnt vmcnt(18)
	ds_write_b64 v28, v[48:49] offset:5120
	ds_write_b32 v30, v50 offset:2080
	s_waitcnt lgkmcnt(0)
	s_barrier
; DI bf16_t f2bf(float x) { return (bf16_t)(pk2(x, 0.f) & 0xffffu); }
;     ...
;         for (int n = 0; n < 64; ++n) {
;             const int buf = n & 1;
;             f32x4 a4[4]; bf16x8 vfr[2][2];
; #pragma unroll
;             for (int q = 0; q < 4; ++q) a4[q] = a4n[q];
;             const unsigned kraw = krawn;
; #pragma unroll
;             for (int e = 0; e < 2; ++e)
; #pragma unroll
;                 for (int ks = 0; ks < 2; ++ks) vfr[e][ks] = vfrn[e][ks];
;             if (n + 1 < 64) ldchunk(n + 1);
;             float cum[2];
; #pragma unroll
;             for (int e = 0; e < 2; ++e) {
;                 float z = bb[e];
; #pragma unroll
;                 for (int q = 0; q < 4; ++q) { z += a4[q].x * wa[e][4 * q] + a4[q].y * wa[e][4 * q + 1] + a4[q].z * wa[e][4 * q + 2] + a4[q].w * wa[e][4 * q + 3]; }
;                 cum[e] = (fminf(z, 0.f) - __logf(1.f + __expf(-fabsf(z)))) * (1.f / 16.f);
;             }
; #pragma unroll
;             for (int o = 1; o < 64; o <<= 1) {
;                 const float t0 = __shfl_up(cum[0], o), t1 = __shfl_up(cum[1], o);
;                 if (l >= o) { cum[0] += t0; cum[1] += t1; }
;             }
;             const float tot0 = __shfl(cum[0], 63), tot1 = __shfl(cum[1], 63);
;             kdl[(buf * 16 + 2 * w) * 64 + l] = f2bf(bf2f(kraw & 0xffffu) * __expf(tot0 - cum[0]));
;             kdl[(buf * 16 + 2 * w + 1) * 64 + l] = f2bf(bf2f(kraw >> 16) * __expf(tot1 - cum[1]));
;             if (l == 0) { decl[buf * 16 + 2 * w] = __expf(tot0); decl[buf * 16 + 2 * w + 1] = __expf(tot1); }
;             __syncthreads();
;             const f32x4 d4 = *(const f32x4*)(decl + buf * 16 + (l >> 4) * 4);
; #pragma unroll
;             for (int e = 0; e < 2; ++e) acc[e] = acc[e] * d4;
; #pragma unroll
;             for (int ks = 0; ks < 2; ++ks) {
;                 const bf16x8 af = *(const bf16x8*)(kdl + (buf * 16 + (l & 15)) * 64 + ks * 32 + (l >> 4) * 8);
; #pragma unroll
;                 for (int e = 0; e < 2; ++e) acc[e] = MFMA16(af, vfr[e][ks], acc[e]);
;             }
;             const int cidx = b * 64 + n;
; #pragma unroll
;             for (int e = 0; e < 2; ++e) {
;                 const int vv = (2 * w + e) * 16 + (l & 15);
;                 *(u32x2*)(ST + (((size_t)(cidx * 4 + hh)) * 256 + vv) * 128 + ksl * 16 + (l >> 4) * 4) = pk4(acc[e].x, acc[e].y, acc[e].z, acc[e].w);
;             }
;         }
	ds_read_b128 v[8:11], v29 offset:5120
	ds_read_b128 v[12:15], v29 offset:5136
	ds_read_b128 v[16:19], v29 offset:5152
	ds_read_b128 v[20:23], v29 offset:5168
	ds_read_b32 v24, v31 offset:2080
	ds_read_b128 v[154:157], v75 offset:0
	ds_read_b128 v[240:243], v164 offset:4096
	ds_read_b128 v[236:239], v75 offset:64
	s_waitcnt lgkmcnt(3)
	v_pk_fma_f32 v[64:65], v[8:9], v[86:87], v[118:119] op_sel:[0,0,0] op_sel_hi:[0,1,1]
	v_pk_mul_f32 v[66:67], v[16:17], v[102:103] op_sel:[0,0] op_sel_hi:[0,1]
	v_pk_fma_f32 v[64:65], v[8:9], v[88:89], v[64:65] op_sel:[1,0,0] op_sel_hi:[1,1,1]
	v_pk_fma_f32 v[66:67], v[16:17], v[104:105], v[66:67] op_sel:[1,0,0] op_sel_hi:[1,1,1]
	v_pk_fma_f32 v[64:65], v[10:11], v[90:91], v[64:65] op_sel:[0,0,0] op_sel_hi:[0,1,1]
	v_pk_fma_f32 v[66:67], v[18:19], v[106:107], v[66:67] op_sel:[0,0,0] op_sel_hi:[0,1,1]
	v_pk_fma_f32 v[64:65], v[10:11], v[92:93], v[64:65] op_sel:[1,0,0] op_sel_hi:[1,1,1]
	v_pk_fma_f32 v[66:67], v[18:19], v[108:109], v[66:67] op_sel:[1,0,0] op_sel_hi:[1,1,1]
	v_pk_fma_f32 v[64:65], v[12:13], v[94:95], v[64:65] op_sel:[0,0,0] op_sel_hi:[0,1,1]
	v_pk_fma_f32 v[66:67], v[20:21], v[110:111], v[66:67] op_sel:[0,0,0] op_sel_hi:[0,1,1]
	v_pk_fma_f32 v[64:65], v[12:13], v[96:97], v[64:65] op_sel:[1,0,0] op_sel_hi:[1,1,1]
	v_pk_fma_f32 v[66:67], v[20:21], v[112:113], v[66:67] op_sel:[1,0,0] op_sel_hi:[1,1,1]
	v_pk_fma_f32 v[64:65], v[14:15], v[98:99], v[64:65] op_sel:[0,0,0] op_sel_hi:[0,1,1]
	v_pk_fma_f32 v[66:67], v[22:23], v[114:115], v[66:67] op_sel:[0,0,0] op_sel_hi:[0,1,1]
	v_pk_fma_f32 v[64:65], v[14:15], v[100:101], v[64:65] op_sel:[1,0,0] op_sel_hi:[1,1,1]
	v_pk_fma_f32 v[66:67], v[22:23], v[116:117], v[66:67] op_sel:[1,0,0] op_sel_hi:[1,1,1]
	v_lshlrev_b32_e32 v148, 16, v24
	v_pk_add_f32 v[64:65], v[64:65], v[66:67]
	v_and_b32_e32 v149, 0xffff0000, v24
	s_waitcnt lgkmcnt(0)
	v_pk_mul_f32 v[0:1], v[0:1], v[240:241]
	v_pk_mul_f32 v[2:3], v[2:3], v[242:243]
	v_pk_mul_f32 v[4:5], v[4:5], v[240:241]
	v_pk_mul_f32 v[6:7], v[6:7], v[242:243]
	s_waitcnt vmcnt(8)
	s_nop 0
	v_mfma_f32_16x16x32_bf16 v[0:3], v[154:157], v[194:197], v[0:3]
	v_mfma_f32_16x16x32_bf16 v[4:7], v[154:157], v[202:205], v[4:7]
	v_mfma_f32_16x16x32_bf16 v[0:3], v[236:239], v[198:201], v[0:3]
	v_mfma_f32_16x16x32_bf16 v[4:7], v[236:239], v[206:209], v[4:7]
	v_mul_f32_e64 v68, |v64|, v220
	v_mul_f32_e64 v69, |v65|, v220
	v_exp_f32_e32 v68, v68
	v_exp_f32_e32 v69, v69
	v_min_f32_e32 v70, 0, v64
	v_min_f32_e32 v71, 0, v65
	v_pk_add_f32 v[68:69], v[68:69], v[222:223]
	s_nop 0
	v_log_f32_e32 v138, v68
	v_log_f32_e32 v139, v69
	s_nop 0
	v_pk_mul_f32 v[140:141], v[138:139], v[224:225]
	s_nop 0
	v_pk_fma_f32 v[142:143], v[138:139], v[224:225], v[140:141] neg_lo:[0,0,1] neg_hi:[0,0,1]
	s_nop 0
	v_pk_fma_f32 v[142:143], v[138:139], v[226:227], v[142:143]
	s_nop 0
	v_pk_fma_f32 v[142:143], v[138:139], v[224:225], v[142:143]
	s_nop 0
	v_pk_add_f32 v[144:145], v[70:71], v[142:143] neg_lo:[0,1] neg_hi:[0,1]
	s_nop 0
	v_pk_mul_f32 v[144:145], v[144:145], v[214:215]
	v_cvt_pk_bf16_f32 v244, v0, v1
	v_cvt_pk_bf16_f32 v245, v2, v3
	v_cvt_pk_bf16_f32 v246, v4, v5
	v_cvt_pk_bf16_f32 v247, v6, v7
	global_store_dwordx2 v234, v[244:245], s[100:101]
	global_store_dwordx2 v235, v[246:247], s[100:101]
	s_add_u32 s100, s100, 0x40000
	s_addc_u32 s101, s101, 0
	v_add_f32_dpp v144, v144, v144 row_shr:1 row_mask:0xf bank_mask:0xf
	v_add_f32_dpp v145, v145, v145 row_shr:1 row_mask:0xf bank_mask:0xf
	s_nop 0
	v_add_f32_dpp v144, v144, v144 row_shr:2 row_mask:0xf bank_mask:0xf
	v_add_f32_dpp v145, v145, v145 row_shr:2 row_mask:0xf bank_mask:0xf
	s_nop 0
	v_add_f32_dpp v144, v144, v144 row_shr:4 row_mask:0xf bank_mask:0xf
	v_add_f32_dpp v145, v145, v145 row_shr:4 row_mask:0xf bank_mask:0xf
	s_nop 0
	v_add_f32_dpp v144, v144, v144 row_shr:8 row_mask:0xf bank_mask:0xf
	v_add_f32_dpp v145, v145, v145 row_shr:8 row_mask:0xf bank_mask:0xf
	s_nop 0
	v_add_f32_dpp v144, v144, v144 row_bcast:15 row_mask:0xa bank_mask:0xf
	v_add_f32_dpp v145, v145, v145 row_bcast:15 row_mask:0xa bank_mask:0xf
	s_nop 0
	v_add_f32_dpp v144, v144, v144 row_bcast:31 row_mask:0xc bank_mask:0xf
	v_add_f32_dpp v145, v145, v145 row_bcast:31 row_mask:0xc bank_mask:0xf
	s_nop 0
	v_readlane_b32 s98, v144, 63
	v_readlane_b32 s99, v145, 63
	s_nop 1
	v_pk_add_f32 v[146:147], s[98:99], v[144:145] neg_lo:[0,1] neg_hi:[0,1]
	v_mul_f32_e64 v152, s98, v228
	v_mul_f32_e64 v153, s99, v228
	v_pk_mul_f32 v[146:147], v[146:147], v[228:229]
	v_exp_f32_e32 v152, v152
	v_exp_f32_e32 v153, v153
	v_exp_f32_e32 v146, v146
	v_exp_f32_e32 v147, v147
	s_nop 0
	v_pk_mul_f32 v[146:147], v[146:147], v[148:149]
	s_nop 0
	v_cvt_pk_bf16_f32 v150, v146, v147
	s_nop 0
	ds_write_b16 v172, v150 offset:2048
	ds_write_b16_d16_hi v172, v150 offset:2176
	s_and_saveexec_b64 s[20:21], vcc
	ds_write_b64 v163, v[152:153] offset:4160
	s_mov_b64 exec, s[20:21]
	s_waitcnt lgkmcnt(0)
	s_barrier
	ds_read_b128 v[154:157], v75 offset:2048
	ds_read_b128 v[240:243], v164 offset:4160
	ds_read_b128 v[236:239], v75 offset:2112
	s_waitcnt lgkmcnt(0)
	v_pk_mul_f32 v[0:1], v[0:1], v[240:241]
	v_pk_mul_f32 v[2:3], v[2:3], v[242:243]
	v_pk_mul_f32 v[4:5], v[4:5], v[240:241]
	v_pk_mul_f32 v[6:7], v[6:7], v[242:243]
	s_waitcnt vmcnt(4)
	s_nop 0
	v_mfma_f32_16x16x32_bf16 v[0:3], v[154:157], v[32:35], v[0:3]
	v_mfma_f32_16x16x32_bf16 v[4:7], v[154:157], v[40:43], v[4:7]
	v_mfma_f32_16x16x32_bf16 v[0:3], v[236:239], v[36:39], v[0:3]
	v_mfma_f32_16x16x32_bf16 v[4:7], v[236:239], v[44:47], v[4:7]
	s_nop 7
	s_nop 1
	v_cvt_pk_bf16_f32 v244, v0, v1
	v_cvt_pk_bf16_f32 v245, v2, v3
	v_cvt_pk_bf16_f32 v246, v4, v5
	v_cvt_pk_bf16_f32 v247, v6, v7
	global_store_dwordx2 v234, v[244:245], s[100:101]
	global_store_dwordx2 v235, v[246:247], s[100:101]
	s_add_u32 s100, s100, 0x40000
	s_addc_u32 s101, s101, 0
	s_add_i32 s56, s56, s96
	s_cmpk_gt_i32 s56, 0xff
	s_cbranch_scc0 .LBB0_418
